# GEMM tiles: static s_setprio 1 for the second wave group instead of per-segment toggling
# baseline (speedup 1.0000x reference)
.LBB0_109:
	s_setprio 0
	v_or_b32_e32 v130, s24, v146
	v_add_u32_e32 v136, s25, v130
	v_or_b32_e32 v140, 16, v136
	v_ashrrev_i32_e32 v137, 31, v136
	v_ashrrev_i32_e32 v141, 31, v140
	v_lshl_add_u64 v[138:139], v[136:137], 2, s[2:3]
	v_lshl_add_u64 v[132:133], v[140:141], 2, s[2:3]
	global_load_dword v130, v[138:139], off
	global_load_dword v137, v[132:133], off
	global_load_dword v150, v[138:139], off offset:128
	global_load_dword v151, v[138:139], off offset:192
	global_load_dword v152, v[138:139], off offset:512
	global_load_dword v153, v[138:139], off offset:576
	global_load_dword v154, v[138:139], off offset:640
	global_load_dword v155, v[138:139], off offset:704
	v_or_b32_e32 v134, s22, v145
	v_or_b32_e32 v134, s23, v134
	v_mov_b64_e32 v[132:133], s[60:61]
	v_ashrrev_i32_e32 v135, 31, v134
	v_mad_i64_i32 v[142:143], s[22:23], v136, s36, v[132:133]
	v_lshlrev_b64 v[134:135], 1, v[134:135]
	v_mad_i64_i32 v[140:141], s[22:23], v140, s36, v[132:133]
	v_lshl_add_u64 v[142:143], v[142:143], 0, v[134:135]
	v_lshl_add_u64 v[140:141], v[140:141], 0, v[134:135]
	s_add_i32 s37, s37, s58
	s_cmpk_gt_i32 s37, 0x4a3
	s_cbranch_scc1 .Lp1pf_last
	s_mov_b32 s96, 1
	s_and_b32 s27, s37, 7
	s_lshr_b32 s26, s37, 3
	s_mul_i32 s28, s27, 0x95
	s_mul_i32 s29, s27, 0x94
	s_add_i32 s29, s29, 4
	s_cmp_gt_u32 s27, 3
	s_cselect_b32 s28, s29, s28
	s_add_i32 s26, s28, s26
	s_mul_hi_u32 s27, s26, 0x38e38e39
	s_lshr_b32 s27, s27, 5
	s_mul_i32 s28, s27, 0x90
	s_sub_i32 s26, s26, s28
	s_cmp_lt_u32 s27, 8
	s_cselect_b32 s28, 3, 1
	s_cselect_b32 s29, 7, 1
	s_lshr_b32 s30, s26, s28
	s_and_b32 s26, s26, s29
	s_lshl_b32 s27, s27, 3
	s_add_i32 s26, s26, s27
	s_lshl_b32 s26, s26, 19
	s_lshl_b32 s28, s30, 19
	s_add_u32 s26, s34, s26
	s_addc_u32 s27, s35, 0
	s_add_u32 s28, s76, s28
	s_addc_u32 s29, s77, 0
	s_add_u32 s42, s28, 0x40000
	s_addc_u32 s43, s29, 0
	s_add_u32 s50, s26, 0x40000
	s_addc_u32 s51, s27, 0
	s_add_i32 m0, s40, 0x10000
	s_nop 0
	global_load_lds_dwordx4 v243, s[28:29]
	s_add_i32 m0, s40, 0x12000
	s_nop 0
	global_load_lds_dwordx4 v244, s[28:29]
	s_add_i32 m0, s40, 0
	s_nop 0
	global_load_lds_dwordx4 v245, s[26:27]
	s_add_i32 m0, s40, 0x2000
	s_nop 0
	global_load_lds_dwordx4 v246, s[26:27]
	s_add_i32 m0, s40, 0x14000
	s_nop 0
	global_load_lds_dwordx4 v243, s[42:43]
	s_add_i32 m0, s40, 0x16000
	s_nop 0
	global_load_lds_dwordx4 v244, s[42:43]
	s_add_i32 m0, s40, 0x4000
	s_nop 0
	global_load_lds_dwordx4 v245, s[50:51]
	s_add_i32 m0, s40, 0x6000
	s_nop 0
	global_load_lds_dwordx4 v246, s[50:51]
	s_branch .Lp1pf_done

.Lp1pf_join:
	v_mov_b32_e32 v135, v131
	v_lshl_add_u64 v[10:11], s[28:29], 0, v[130:131]
	v_lshl_add_u64 v[8:9], s[28:29], 0, v[2:3]
	v_lshl_add_u64 v[6:7], s[26:27], 0, v[132:133]
	s_cmp_lg_u32 s44, 1
	v_lshl_add_u64 v[4:5], s[26:27], 0, v[134:135]
	s_cbranch_scc1 .LBB0_116
	s_setprio 1
	s_barrier

.LBB0_117:
	s_add_i32 s47, 0, 0x10000
	v_add_u32_e32 v130, s47, v148
	ds_read_b128 v[150:153], v130
	ds_read_b128 v[154:157], v130 offset:1024
	ds_read_b128 v[158:161], v130 offset:2048
	ds_read_b128 v[162:165], v130 offset:3072
	v_lshl_add_u64 v[214:215], s[28:29], 0, v[136:137]
	s_add_i32 s31, s40, 0xc000
	v_lshl_add_u64 v[198:199], v[214:215], 0, s[6:7]
	s_mov_b32 m0, s31
	v_lshl_add_u64 v[216:217], s[28:29], 0, v[138:139]
	s_add_i32 s30, s40, 0xe000
	ds_read_b128 v[166:169], v147
	ds_read_b128 v[170:173], v147 offset:1024
	ds_read_b128 v[174:177], v147 offset:2048
	ds_read_b128 v[178:181], v147 offset:3072
	ds_read_b128 v[182:185], v147 offset:4096
	ds_read_b128 v[186:189], v147 offset:5120
	ds_read_b128 v[190:193], v147 offset:6144
	ds_read_b128 v[194:197], v147 offset:7168
	global_load_lds_dwordx4 v[198:199], off
	v_lshl_add_u64 v[198:199], v[216:217], 0, s[6:7]
	s_mov_b32 m0, s30
	s_nop 0
	global_load_lds_dwordx4 v[198:199], off
	s_waitcnt lgkmcnt(8)
	s_barrier
	s_waitcnt lgkmcnt(0)
	s_waitcnt lgkmcnt(0)
	v_mfma_f32_16x16x32_bf16 v[126:129], v[150:153], v[166:169], v[126:129]
	v_mfma_f32_16x16x32_bf16 v[122:125], v[158:161], v[166:169], v[122:125]
	v_mfma_f32_16x16x32_bf16 v[118:121], v[150:153], v[174:177], v[118:121]
	v_mfma_f32_16x16x32_bf16 v[114:117], v[158:161], v[174:177], v[114:117]
	v_mfma_f32_16x16x32_bf16 v[110:113], v[150:153], v[182:185], v[110:113]
	v_mfma_f32_16x16x32_bf16 v[106:109], v[158:161], v[182:185], v[106:109]
	v_mfma_f32_16x16x32_bf16 v[102:105], v[150:153], v[190:193], v[102:105]
	v_mfma_f32_16x16x32_bf16 v[98:101], v[158:161], v[190:193], v[98:101]
	v_mfma_f32_16x16x32_bf16 v[126:129], v[154:157], v[170:173], v[126:129]
	v_mfma_f32_16x16x32_bf16 v[122:125], v[162:165], v[170:173], v[122:125]
	v_mfma_f32_16x16x32_bf16 v[118:121], v[154:157], v[178:181], v[118:121]
	v_mfma_f32_16x16x32_bf16 v[114:117], v[162:165], v[178:181], v[114:117]
	v_mfma_f32_16x16x32_bf16 v[110:113], v[154:157], v[186:189], v[110:113]
	v_mfma_f32_16x16x32_bf16 v[106:109], v[162:165], v[186:189], v[106:109]
	v_mfma_f32_16x16x32_bf16 v[102:105], v[154:157], v[194:197], v[102:105]
	v_mfma_f32_16x16x32_bf16 v[98:101], v[162:165], v[194:197], v[98:101]
	s_barrier
	s_add_i32 s48, 0, 0x14000
	v_lshl_add_u64 v[218:219], s[28:29], 0, v[140:141]
	s_add_i32 s47, s47, s39
	v_add_u32_e32 v130, s48, v148
	v_lshl_add_u64 v[220:221], v[218:219], 0, s[8:9]
	s_mov_b32 m0, s47
	ds_read_b128 v[198:201], v130
	ds_read_b128 v[202:205], v130 offset:1024
	ds_read_b128 v[206:209], v130 offset:2048
	ds_read_b128 v[210:213], v130 offset:3072
	global_load_lds_dwordx4 v[220:221], off
	v_lshl_add_u64 v[220:221], s[28:29], 0, v[142:143]
	v_lshl_add_u64 v[222:223], v[220:221], 0, s[8:9]
	s_add_i32 m0, s47, 0x2000
	s_nop 0
	global_load_lds_dwordx4 v[222:223], off
	s_barrier
	s_waitcnt lgkmcnt(0)
	s_waitcnt lgkmcnt(0)
	v_mfma_f32_16x16x32_bf16 v[94:97], v[198:201], v[166:169], v[94:97]
	v_mfma_f32_16x16x32_bf16 v[90:93], v[206:209], v[166:169], v[90:93]
	v_mfma_f32_16x16x32_bf16 v[86:89], v[198:201], v[174:177], v[86:89]
	v_mfma_f32_16x16x32_bf16 v[82:85], v[206:209], v[174:177], v[82:85]
	v_mfma_f32_16x16x32_bf16 v[78:81], v[198:201], v[182:185], v[78:81]
	v_mfma_f32_16x16x32_bf16 v[74:77], v[206:209], v[182:185], v[74:77]
	v_mfma_f32_16x16x32_bf16 v[70:73], v[198:201], v[190:193], v[70:73]
	v_mfma_f32_16x16x32_bf16 v[66:69], v[206:209], v[190:193], v[66:69]
	v_mfma_f32_16x16x32_bf16 v[94:97], v[202:205], v[170:173], v[94:97]
	v_mfma_f32_16x16x32_bf16 v[90:93], v[210:213], v[170:173], v[90:93]
	v_mfma_f32_16x16x32_bf16 v[86:89], v[202:205], v[178:181], v[86:89]
	v_mfma_f32_16x16x32_bf16 v[82:85], v[210:213], v[178:181], v[82:85]
	v_mfma_f32_16x16x32_bf16 v[78:81], v[202:205], v[186:189], v[78:81]
	v_mfma_f32_16x16x32_bf16 v[74:77], v[210:213], v[186:189], v[74:77]
	v_mfma_f32_16x16x32_bf16 v[70:73], v[202:205], v[194:197], v[70:73]
	v_mfma_f32_16x16x32_bf16 v[66:69], v[210:213], v[194:197], v[66:69]
	s_mov_b32 m0, s40
	v_lshl_add_u64 v[222:223], v[214:215], 0, s[10:11]
	s_barrier
	ds_read_b128 v[166:169], v147 offset:16384
	ds_read_b128 v[170:173], v147 offset:17408
	ds_read_b128 v[174:177], v147 offset:18432
	ds_read_b128 v[178:181], v147 offset:19456
	ds_read_b128 v[182:185], v147 offset:20480
	ds_read_b128 v[186:189], v147 offset:21504
	ds_read_b128 v[190:193], v147 offset:22528
	ds_read_b128 v[194:197], v147 offset:23552
	global_load_lds_dwordx4 v[222:223], off
	v_lshl_add_u64 v[222:223], v[216:217], 0, s[10:11]
	s_mov_b32 m0, s41
	s_nop 0
	global_load_lds_dwordx4 v[222:223], off
	s_barrier
	s_waitcnt lgkmcnt(0)
	s_waitcnt lgkmcnt(0)
	v_mfma_f32_16x16x32_bf16 v[62:65], v[150:153], v[166:169], v[62:65]
	v_mfma_f32_16x16x32_bf16 v[58:61], v[158:161], v[166:169], v[58:61]
	v_mfma_f32_16x16x32_bf16 v[54:57], v[150:153], v[174:177], v[54:57]
	v_mfma_f32_16x16x32_bf16 v[50:53], v[158:161], v[174:177], v[50:53]
	v_mfma_f32_16x16x32_bf16 v[46:49], v[150:153], v[182:185], v[46:49]
	v_mfma_f32_16x16x32_bf16 v[42:45], v[158:161], v[182:185], v[42:45]
	v_mfma_f32_16x16x32_bf16 v[38:41], v[150:153], v[190:193], v[38:41]
	v_mfma_f32_16x16x32_bf16 v[34:37], v[158:161], v[190:193], v[34:37]
	v_mfma_f32_16x16x32_bf16 v[62:65], v[154:157], v[170:173], v[62:65]
	v_mfma_f32_16x16x32_bf16 v[58:61], v[162:165], v[170:173], v[58:61]
	v_mfma_f32_16x16x32_bf16 v[54:57], v[154:157], v[178:181], v[54:57]
	v_mfma_f32_16x16x32_bf16 v[50:53], v[162:165], v[178:181], v[50:53]
	v_mfma_f32_16x16x32_bf16 v[46:49], v[154:157], v[186:189], v[46:49]
	v_mfma_f32_16x16x32_bf16 v[42:45], v[162:165], v[186:189], v[42:45]
	v_mfma_f32_16x16x32_bf16 v[38:41], v[154:157], v[194:197], v[38:41]
	v_mfma_f32_16x16x32_bf16 v[34:37], v[162:165], v[194:197], v[34:37]
	s_barrier
	s_add_i32 s47, s48, s39
	v_lshl_add_u64 v[150:151], v[218:219], 0, s[12:13]
	s_mov_b32 m0, s47
	s_nop 0
	global_load_lds_dwordx4 v[150:151], off
	v_lshl_add_u64 v[150:151], v[220:221], 0, s[12:13]
	s_add_i32 m0, s47, 0x2000
	s_nop 0
	global_load_lds_dwordx4 v[150:151], off
	s_waitcnt vmcnt(6)
	s_barrier
	v_mfma_f32_16x16x32_bf16 v[30:33], v[198:201], v[166:169], v[30:33]
	v_mfma_f32_16x16x32_bf16 v[26:29], v[206:209], v[166:169], v[26:29]
	v_mfma_f32_16x16x32_bf16 v[22:25], v[198:201], v[174:177], v[22:25]
	v_mfma_f32_16x16x32_bf16 v[18:21], v[206:209], v[174:177], v[18:21]
	v_mfma_f32_16x16x32_bf16 v[14:17], v[198:201], v[182:185], v[14:17]
	v_mfma_f32_16x16x32_bf16 v[10:13], v[206:209], v[182:185], v[10:13]
	v_mfma_f32_16x16x32_bf16 v[6:9], v[198:201], v[190:193], v[6:9]
	v_mfma_f32_16x16x32_bf16 v[2:5], v[206:209], v[190:193], v[2:5]
	v_mfma_f32_16x16x32_bf16 v[30:33], v[202:205], v[170:173], v[30:33]
	v_mfma_f32_16x16x32_bf16 v[26:29], v[210:213], v[170:173], v[26:29]
	v_mfma_f32_16x16x32_bf16 v[22:25], v[202:205], v[178:181], v[22:25]
	v_mfma_f32_16x16x32_bf16 v[18:21], v[210:213], v[178:181], v[18:21]
	v_mfma_f32_16x16x32_bf16 v[14:17], v[202:205], v[186:189], v[14:17]
	v_mfma_f32_16x16x32_bf16 v[10:13], v[210:213], v[186:189], v[10:13]
	v_mfma_f32_16x16x32_bf16 v[6:9], v[202:205], v[194:197], v[6:9]
	v_mfma_f32_16x16x32_bf16 v[2:5], v[210:213], v[194:197], v[2:5]
	s_add_i32 s47, 0, 0x18000
	v_add_u32_e32 v130, s47, v148
	s_barrier
	ds_read_b128 v[150:153], v130
	ds_read_b128 v[154:157], v130 offset:1024
	ds_read_b128 v[158:161], v130 offset:2048
	ds_read_b128 v[162:165], v130 offset:3072
	s_mov_b32 m0, s42
	v_lshl_add_u64 v[198:199], v[214:215], 0, s[14:15]
	ds_read_b128 v[166:169], v147 offset:32768
	ds_read_b128 v[170:173], v147 offset:33792
	ds_read_b128 v[174:177], v147 offset:34816
	ds_read_b128 v[178:181], v147 offset:35840
	ds_read_b128 v[182:185], v147 offset:36864
	ds_read_b128 v[186:189], v147 offset:37888
	ds_read_b128 v[190:193], v147 offset:38912
	ds_read_b128 v[194:197], v147 offset:39936
	global_load_lds_dwordx4 v[198:199], off
	v_lshl_add_u64 v[198:199], v[216:217], 0, s[14:15]
	s_mov_b32 m0, s43
	s_nop 0
	global_load_lds_dwordx4 v[198:199], off
	s_waitcnt lgkmcnt(8)
	s_barrier
	s_waitcnt lgkmcnt(0)
	s_waitcnt lgkmcnt(0)
	v_mfma_f32_16x16x32_bf16 v[126:129], v[150:153], v[166:169], v[126:129]
	v_mfma_f32_16x16x32_bf16 v[122:125], v[158:161], v[166:169], v[122:125]
	v_mfma_f32_16x16x32_bf16 v[118:121], v[150:153], v[174:177], v[118:121]
	v_mfma_f32_16x16x32_bf16 v[114:117], v[158:161], v[174:177], v[114:117]
	v_mfma_f32_16x16x32_bf16 v[110:113], v[150:153], v[182:185], v[110:113]
	v_mfma_f32_16x16x32_bf16 v[106:109], v[158:161], v[182:185], v[106:109]
	v_mfma_f32_16x16x32_bf16 v[102:105], v[150:153], v[190:193], v[102:105]
	v_mfma_f32_16x16x32_bf16 v[98:101], v[158:161], v[190:193], v[98:101]
	v_mfma_f32_16x16x32_bf16 v[126:129], v[154:157], v[170:173], v[126:129]
	v_mfma_f32_16x16x32_bf16 v[122:125], v[162:165], v[170:173], v[122:125]
	v_mfma_f32_16x16x32_bf16 v[118:121], v[154:157], v[178:181], v[118:121]
	v_mfma_f32_16x16x32_bf16 v[114:117], v[162:165], v[178:181], v[114:117]
	v_mfma_f32_16x16x32_bf16 v[110:113], v[154:157], v[186:189], v[110:113]
	v_mfma_f32_16x16x32_bf16 v[106:109], v[162:165], v[186:189], v[106:109]
	v_mfma_f32_16x16x32_bf16 v[102:105], v[154:157], v[194:197], v[102:105]
	v_mfma_f32_16x16x32_bf16 v[98:101], v[162:165], v[194:197], v[98:101]
	s_barrier
	s_add_i32 s48, 0, 0x1c000
	s_add_i32 s47, s47, s39
	v_add_u32_e32 v130, s48, v148
	v_lshl_add_u64 v[222:223], v[218:219], 0, s[16:17]
	s_mov_b32 m0, s47
	ds_read_b128 v[198:201], v130
	ds_read_b128 v[202:205], v130 offset:1024
	ds_read_b128 v[206:209], v130 offset:2048
	ds_read_b128 v[210:213], v130 offset:3072
	global_load_lds_dwordx4 v[222:223], off
	v_lshl_add_u64 v[222:223], v[220:221], 0, s[16:17]
	s_add_i32 m0, s47, 0x2000
	s_nop 0
	global_load_lds_dwordx4 v[222:223], off
	s_barrier
	s_waitcnt lgkmcnt(0)
	s_waitcnt lgkmcnt(0)
	v_mfma_f32_16x16x32_bf16 v[94:97], v[198:201], v[166:169], v[94:97]
	v_mfma_f32_16x16x32_bf16 v[90:93], v[206:209], v[166:169], v[90:93]
	v_mfma_f32_16x16x32_bf16 v[86:89], v[198:201], v[174:177], v[86:89]
	v_mfma_f32_16x16x32_bf16 v[82:85], v[206:209], v[174:177], v[82:85]
	v_mfma_f32_16x16x32_bf16 v[78:81], v[198:201], v[182:185], v[78:81]
	v_mfma_f32_16x16x32_bf16 v[74:77], v[206:209], v[182:185], v[74:77]
	v_mfma_f32_16x16x32_bf16 v[70:73], v[198:201], v[190:193], v[70:73]
	v_mfma_f32_16x16x32_bf16 v[66:69], v[206:209], v[190:193], v[66:69]
	v_mfma_f32_16x16x32_bf16 v[94:97], v[202:205], v[170:173], v[94:97]
	v_mfma_f32_16x16x32_bf16 v[90:93], v[210:213], v[170:173], v[90:93]
	v_mfma_f32_16x16x32_bf16 v[86:89], v[202:205], v[178:181], v[86:89]
	v_mfma_f32_16x16x32_bf16 v[82:85], v[210:213], v[178:181], v[82:85]
	v_mfma_f32_16x16x32_bf16 v[78:81], v[202:205], v[186:189], v[78:81]
	v_mfma_f32_16x16x32_bf16 v[74:77], v[210:213], v[186:189], v[74:77]
	v_mfma_f32_16x16x32_bf16 v[70:73], v[202:205], v[194:197], v[70:73]
	v_mfma_f32_16x16x32_bf16 v[66:69], v[210:213], v[194:197], v[66:69]
	s_mov_b32 m0, s44
	v_lshl_add_u64 v[214:215], v[214:215], 0, s[18:19]
	s_barrier
	ds_read_b128 v[166:169], v147 offset:49152
	ds_read_b128 v[170:173], v147 offset:50176
	ds_read_b128 v[174:177], v147 offset:51200
	ds_read_b128 v[178:181], v147 offset:52224
	ds_read_b128 v[182:185], v147 offset:53248
	ds_read_b128 v[186:189], v147 offset:54272
	ds_read_b128 v[190:193], v147 offset:55296
	ds_read_b128 v[194:197], v147 offset:56320
	global_load_lds_dwordx4 v[214:215], off
	v_lshl_add_u64 v[214:215], v[216:217], 0, s[18:19]
	s_mov_b32 m0, s45
	s_nop 0
	global_load_lds_dwordx4 v[214:215], off
	s_barrier
	s_waitcnt lgkmcnt(0)
	s_waitcnt lgkmcnt(0)
	v_mfma_f32_16x16x32_bf16 v[62:65], v[150:153], v[166:169], v[62:65]
	v_mfma_f32_16x16x32_bf16 v[58:61], v[158:161], v[166:169], v[58:61]
	v_mfma_f32_16x16x32_bf16 v[54:57], v[150:153], v[174:177], v[54:57]
	v_mfma_f32_16x16x32_bf16 v[50:53], v[158:161], v[174:177], v[50:53]
	v_mfma_f32_16x16x32_bf16 v[46:49], v[150:153], v[182:185], v[46:49]
	v_mfma_f32_16x16x32_bf16 v[42:45], v[158:161], v[182:185], v[42:45]
	v_mfma_f32_16x16x32_bf16 v[38:41], v[150:153], v[190:193], v[38:41]
	v_mfma_f32_16x16x32_bf16 v[34:37], v[158:161], v[190:193], v[34:37]
	v_mfma_f32_16x16x32_bf16 v[62:65], v[154:157], v[170:173], v[62:65]
	v_mfma_f32_16x16x32_bf16 v[58:61], v[162:165], v[170:173], v[58:61]
	v_mfma_f32_16x16x32_bf16 v[54:57], v[154:157], v[178:181], v[54:57]
	v_mfma_f32_16x16x32_bf16 v[50:53], v[162:165], v[178:181], v[50:53]
	v_mfma_f32_16x16x32_bf16 v[46:49], v[154:157], v[186:189], v[46:49]
	v_mfma_f32_16x16x32_bf16 v[42:45], v[162:165], v[186:189], v[42:45]
	v_mfma_f32_16x16x32_bf16 v[38:41], v[154:157], v[194:197], v[38:41]
	v_mfma_f32_16x16x32_bf16 v[34:37], v[162:165], v[194:197], v[34:37]
	s_barrier
	s_add_i32 s47, s48, s39
	v_lshl_add_u64 v[150:151], v[218:219], 0, s[20:21]
	s_mov_b32 m0, s47
	s_nop 0
	global_load_lds_dwordx4 v[150:151], off
	v_lshl_add_u64 v[150:151], v[220:221], 0, s[20:21]
	s_add_i32 m0, s47, 0x2000
	s_nop 0
	global_load_lds_dwordx4 v[150:151], off
	s_waitcnt vmcnt(6)
	s_barrier
	v_mfma_f32_16x16x32_bf16 v[30:33], v[198:201], v[166:169], v[30:33]
	v_mfma_f32_16x16x32_bf16 v[26:29], v[206:209], v[166:169], v[26:29]
	v_mfma_f32_16x16x32_bf16 v[22:25], v[198:201], v[174:177], v[22:25]
	v_mfma_f32_16x16x32_bf16 v[18:21], v[206:209], v[174:177], v[18:21]
	v_mfma_f32_16x16x32_bf16 v[14:17], v[198:201], v[182:185], v[14:17]
	v_mfma_f32_16x16x32_bf16 v[10:13], v[206:209], v[182:185], v[10:13]
	v_mfma_f32_16x16x32_bf16 v[6:9], v[198:201], v[190:193], v[6:9]
	v_mfma_f32_16x16x32_bf16 v[2:5], v[206:209], v[190:193], v[2:5]
	v_mfma_f32_16x16x32_bf16 v[30:33], v[202:205], v[170:173], v[30:33]
	v_mfma_f32_16x16x32_bf16 v[26:29], v[210:213], v[170:173], v[26:29]
	v_mfma_f32_16x16x32_bf16 v[22:25], v[202:205], v[178:181], v[22:25]
	v_mfma_f32_16x16x32_bf16 v[18:21], v[210:213], v[178:181], v[18:21]
	v_mfma_f32_16x16x32_bf16 v[14:17], v[202:205], v[186:189], v[14:17]
	v_mfma_f32_16x16x32_bf16 v[10:13], v[210:213], v[186:189], v[10:13]
	v_mfma_f32_16x16x32_bf16 v[6:9], v[202:205], v[194:197], v[6:9]
	v_mfma_f32_16x16x32_bf16 v[2:5], v[210:213], v[194:197], v[2:5]
	s_add_i32 s46, s46, 2
	s_add_u32 s28, s28, 0x100
	s_addc_u32 s29, s29, 0
	s_cmp_gt_u32 s46, 11
	s_barrier
	s_cbranch_scc0 .LBB0_117
	s_add_u32 s26, s26, 0x40780
	v_add_u32_e32 v130, 0, v148
	s_addc_u32 s27, s27, 0
	s_mov_b32 m0, s31
	v_add_u32_e32 v152, 0x10000, v130
	v_lshl_add_u64 v[132:133], s[26:27], 0, v[132:133]
	ds_read_b128 v[136:139], v152
	ds_read_b128 v[140:143], v152 offset:1024
	ds_read_b128 v[148:151], v152 offset:2048
	ds_read_b128 v[152:155], v152 offset:3072
	ds_read_b128 v[156:159], v147
	ds_read_b128 v[160:163], v147 offset:1024
	ds_read_b128 v[164:167], v147 offset:2048
	ds_read_b128 v[168:171], v147 offset:3072
	ds_read_b128 v[172:175], v147 offset:4096
	ds_read_b128 v[176:179], v147 offset:5120
	ds_read_b128 v[180:183], v147 offset:6144
	ds_read_b128 v[184:187], v147 offset:7168
	global_load_lds_dwordx4 v[132:133], off
	v_lshl_add_u64 v[132:133], s[26:27], 0, v[134:135]
	s_mov_b32 m0, s30
	s_nop 0
	global_load_lds_dwordx4 v[132:133], off
	s_barrier
	s_waitcnt lgkmcnt(0)
	s_waitcnt lgkmcnt(0)
	v_mfma_f32_16x16x32_bf16 v[126:129], v[136:139], v[156:159], v[126:129]
	v_mfma_f32_16x16x32_bf16 v[122:125], v[148:151], v[156:159], v[122:125]
	v_mfma_f32_16x16x32_bf16 v[110:113], v[136:139], v[172:175], v[110:113]
	v_mfma_f32_16x16x32_bf16 v[106:109], v[148:151], v[172:175], v[106:109]
	v_mfma_f32_16x16x32_bf16 v[126:129], v[140:143], v[160:163], v[126:129]
	v_mfma_f32_16x16x32_bf16 v[122:125], v[152:155], v[160:163], v[122:125]
	v_mfma_f32_16x16x32_bf16 v[118:121], v[136:139], v[164:167], v[118:121]
	v_mfma_f32_16x16x32_bf16 v[114:117], v[148:151], v[164:167], v[114:117]
	v_mfma_f32_16x16x32_bf16 v[110:113], v[140:143], v[176:179], v[110:113]
	v_mfma_f32_16x16x32_bf16 v[106:109], v[152:155], v[176:179], v[106:109]
	v_mfma_f32_16x16x32_bf16 v[102:105], v[136:139], v[180:183], v[102:105]
	v_mfma_f32_16x16x32_bf16 v[98:101], v[148:151], v[180:183], v[98:101]
	v_mfma_f32_16x16x32_bf16 v[132:135], v[140:143], v[168:171], v[118:121]
	v_mfma_f32_16x16x32_bf16 v[188:191], v[152:155], v[168:171], v[114:117]
	v_mfma_f32_16x16x32_bf16 v[192:195], v[140:143], v[184:187], v[102:105]
	v_mfma_f32_16x16x32_bf16 v[196:199], v[152:155], v[184:187], v[98:101]
	v_add_u32_e32 v118, 0x14000, v130
	s_barrier
	s_nop 0
	ds_read_b128 v[98:101], v118
	ds_read_b128 v[102:105], v118 offset:1024
	ds_read_b128 v[114:117], v118 offset:2048
	ds_read_b128 v[118:121], v118 offset:3072
	s_barrier
	s_waitcnt lgkmcnt(0)
	s_waitcnt lgkmcnt(0)
	v_mfma_f32_16x16x32_bf16 v[94:97], v[98:101], v[156:159], v[94:97]
	v_mfma_f32_16x16x32_bf16 v[90:93], v[114:117], v[156:159], v[90:93]
	v_mfma_f32_16x16x32_bf16 v[86:89], v[98:101], v[164:167], v[86:89]
	v_mfma_f32_16x16x32_bf16 v[82:85], v[114:117], v[164:167], v[82:85]
	v_mfma_f32_16x16x32_bf16 v[94:97], v[102:105], v[160:163], v[94:97]
	v_mfma_f32_16x16x32_bf16 v[90:93], v[118:121], v[160:163], v[90:93]
	v_mfma_f32_16x16x32_bf16 v[86:89], v[102:105], v[168:171], v[86:89]
	v_mfma_f32_16x16x32_bf16 v[82:85], v[118:121], v[168:171], v[82:85]
	v_mfma_f32_16x16x32_bf16 v[78:81], v[98:101], v[172:175], v[78:81]
	v_mfma_f32_16x16x32_bf16 v[74:77], v[114:117], v[172:175], v[74:77]
	v_mfma_f32_16x16x32_bf16 v[70:73], v[98:101], v[180:183], v[70:73]
	v_mfma_f32_16x16x32_bf16 v[66:69], v[114:117], v[180:183], v[66:69]
	v_mfma_f32_16x16x32_bf16 v[156:159], v[102:105], v[176:179], v[78:81]
	v_mfma_f32_16x16x32_bf16 v[160:163], v[118:121], v[176:179], v[74:77]
	v_mfma_f32_16x16x32_bf16 v[164:167], v[102:105], v[184:187], v[70:73]
	v_mfma_f32_16x16x32_bf16 v[168:171], v[118:121], v[184:187], v[66:69]
	s_barrier
	s_nop 1
	ds_read_b128 v[66:69], v147 offset:16384
	ds_read_b128 v[70:73], v147 offset:17408
	ds_read_b128 v[74:77], v147 offset:18432
	ds_read_b128 v[78:81], v147 offset:19456
	ds_read_b128 v[172:175], v147 offset:20480
	ds_read_b128 v[176:179], v147 offset:21504
	ds_read_b128 v[180:183], v147 offset:22528
	ds_read_b128 v[184:187], v147 offset:23552
	s_waitcnt vmcnt(4)
	s_barrier
	s_waitcnt lgkmcnt(0)
	s_waitcnt lgkmcnt(0)
	v_mfma_f32_16x16x32_bf16 v[62:65], v[136:139], v[66:69], v[62:65]
	v_mfma_f32_16x16x32_bf16 v[58:61], v[148:151], v[66:69], v[58:61]
	v_mfma_f32_16x16x32_bf16 v[50:53], v[148:151], v[74:77], v[50:53]
	v_mfma_f32_16x16x32_bf16 v[42:45], v[148:151], v[172:175], v[42:45]
	v_mfma_f32_16x16x32_bf16 v[62:65], v[140:143], v[70:73], v[62:65]
	v_mfma_f32_16x16x32_bf16 v[58:61], v[152:155], v[70:73], v[58:61]
	v_mfma_f32_16x16x32_bf16 v[54:57], v[136:139], v[74:77], v[54:57]
	v_mfma_f32_16x16x32_bf16 v[50:53], v[152:155], v[78:81], v[50:53]
	v_mfma_f32_16x16x32_bf16 v[46:49], v[136:139], v[172:175], v[46:49]
	v_mfma_f32_16x16x32_bf16 v[42:45], v[152:155], v[176:179], v[42:45]
	v_mfma_f32_16x16x32_bf16 v[38:41], v[136:139], v[180:183], v[38:41]
	v_mfma_f32_16x16x32_bf16 v[34:37], v[148:151], v[180:183], v[34:37]
	v_mfma_f32_16x16x32_bf16 v[200:203], v[140:143], v[78:81], v[54:57]
	v_mfma_f32_16x16x32_bf16 v[204:207], v[140:143], v[176:179], v[46:49]
	v_mfma_f32_16x16x32_bf16 v[136:139], v[140:143], v[184:187], v[38:41]
	v_mfma_f32_16x16x32_bf16 v[140:143], v[152:155], v[184:187], v[34:37]
	v_mfma_f32_16x16x32_bf16 v[30:33], v[98:101], v[66:69], v[30:33]
	v_mfma_f32_16x16x32_bf16 v[26:29], v[114:117], v[66:69], v[26:29]
	v_mfma_f32_16x16x32_bf16 v[18:21], v[114:117], v[74:77], v[18:21]
	v_mfma_f32_16x16x32_bf16 v[10:13], v[114:117], v[172:175], v[10:13]
	v_mfma_f32_16x16x32_bf16 v[30:33], v[102:105], v[70:73], v[30:33]
	v_mfma_f32_16x16x32_bf16 v[26:29], v[118:121], v[70:73], v[26:29]
	v_mfma_f32_16x16x32_bf16 v[22:25], v[98:101], v[74:77], v[22:25]
	v_mfma_f32_16x16x32_bf16 v[18:21], v[118:121], v[78:81], v[18:21]
	v_mfma_f32_16x16x32_bf16 v[14:17], v[98:101], v[172:175], v[14:17]
	v_mfma_f32_16x16x32_bf16 v[10:13], v[118:121], v[176:179], v[10:13]
	v_mfma_f32_16x16x32_bf16 v[6:9], v[98:101], v[180:183], v[6:9]
	v_mfma_f32_16x16x32_bf16 v[2:5], v[114:117], v[180:183], v[2:5]
	v_mfma_f32_16x16x32_bf16 v[148:151], v[102:105], v[78:81], v[22:25]
	v_mfma_f32_16x16x32_bf16 v[152:155], v[102:105], v[176:179], v[14:17]
	v_mfma_f32_16x16x32_bf16 v[172:175], v[102:105], v[184:187], v[6:9]
	v_mfma_f32_16x16x32_bf16 v[176:179], v[118:121], v[184:187], v[2:5]
	v_add_u32_e32 v14, 0x18000, v130
	s_barrier
	s_nop 0
	ds_read_b128 v[2:5], v14
	ds_read_b128 v[6:9], v14 offset:1024
	ds_read_b128 v[180:183], v14 offset:2048
	ds_read_b128 v[184:187], v14 offset:3072
	ds_read_b128 v[14:17], v147 offset:32768
	ds_read_b128 v[22:25], v147 offset:33792
	ds_read_b128 v[34:37], v147 offset:34816
	ds_read_b128 v[38:41], v147 offset:35840
	ds_read_b128 v[46:49], v147 offset:36864
	ds_read_b128 v[54:57], v147 offset:37888
	ds_read_b128 v[208:211], v147 offset:38912
	ds_read_b128 v[212:215], v147 offset:39936
	s_waitcnt vmcnt(2)
	s_barrier
	s_waitcnt lgkmcnt(0)
	s_waitcnt lgkmcnt(0)
	v_mfma_f32_16x16x32_bf16 v[66:69], v[2:5], v[14:17], v[126:129]
	v_mfma_f32_16x16x32_bf16 v[118:121], v[6:9], v[22:25], v[66:69]
	v_mfma_f32_16x16x32_bf16 v[66:69], v[180:183], v[14:17], v[122:125]
	v_mfma_f32_16x16x32_bf16 v[114:117], v[184:187], v[22:25], v[66:69]
	v_mfma_f32_16x16x32_bf16 v[66:69], v[2:5], v[34:37], v[132:135]
	v_mfma_f32_16x16x32_bf16 v[102:105], v[6:9], v[38:41], v[66:69]
	v_mfma_f32_16x16x32_bf16 v[66:69], v[180:183], v[34:37], v[188:191]
	v_mfma_f32_16x16x32_bf16 v[98:101], v[184:187], v[38:41], v[66:69]
	v_mfma_f32_16x16x32_bf16 v[66:69], v[2:5], v[46:49], v[110:113]
	v_mfma_f32_16x16x32_bf16 v[78:81], v[6:9], v[54:57], v[66:69]
	v_mfma_f32_16x16x32_bf16 v[66:69], v[180:183], v[46:49], v[106:109]
	v_mfma_f32_16x16x32_bf16 v[74:77], v[184:187], v[54:57], v[66:69]
	v_mfma_f32_16x16x32_bf16 v[66:69], v[2:5], v[208:211], v[192:195]
	v_mfma_f32_16x16x32_bf16 v[70:73], v[6:9], v[212:215], v[66:69]
	v_mfma_f32_16x16x32_bf16 v[66:69], v[180:183], v[208:211], v[196:199]
	v_mfma_f32_16x16x32_bf16 v[66:69], v[184:187], v[212:215], v[66:69]
	v_add_u32_e32 v106, 0x1c000, v130
	s_barrier
	ds_read_b128 v[132:135], v106
	ds_read_b128 v[188:191], v106 offset:1024
	ds_read_b128 v[192:195], v106 offset:2048
	ds_read_b128 v[196:199], v106 offset:3072
	s_waitcnt vmcnt(0)
	s_barrier
	s_waitcnt lgkmcnt(0)
	s_waitcnt lgkmcnt(0)
	v_mfma_f32_16x16x32_bf16 v[94:97], v[132:135], v[14:17], v[94:97]
	v_mfma_f32_16x16x32_bf16 v[14:17], v[192:195], v[14:17], v[90:93]
	v_mfma_f32_16x16x32_bf16 v[122:125], v[196:199], v[22:25], v[14:17]
	v_mfma_f32_16x16x32_bf16 v[14:17], v[132:135], v[34:37], v[86:89]
	v_mfma_f32_16x16x32_bf16 v[110:113], v[188:191], v[38:41], v[14:17]
	v_mfma_f32_16x16x32_bf16 v[14:17], v[192:195], v[34:37], v[82:85]
	v_mfma_f32_16x16x32_bf16 v[106:109], v[196:199], v[38:41], v[14:17]
	v_mfma_f32_16x16x32_bf16 v[14:17], v[132:135], v[46:49], v[156:159]
	v_mfma_f32_16x16x32_bf16 v[126:129], v[188:191], v[22:25], v[94:97]
	v_mfma_f32_16x16x32_bf16 v[94:97], v[188:191], v[54:57], v[14:17]
	v_mfma_f32_16x16x32_bf16 v[14:17], v[192:195], v[46:49], v[160:163]
	v_mfma_f32_16x16x32_bf16 v[90:93], v[196:199], v[54:57], v[14:17]
	v_mfma_f32_16x16x32_bf16 v[14:17], v[132:135], v[208:211], v[164:167]
	v_mfma_f32_16x16x32_bf16 v[86:89], v[188:191], v[212:215], v[14:17]
	v_mfma_f32_16x16x32_bf16 v[14:17], v[192:195], v[208:211], v[168:171]
	v_mfma_f32_16x16x32_bf16 v[82:85], v[196:199], v[212:215], v[14:17]
	s_barrier
	ds_read_b128 v[156:159], v147 offset:49152
	ds_read_b128 v[160:163], v147 offset:50176
	ds_read_b128 v[164:167], v147 offset:51200
	ds_read_b128 v[168:171], v147 offset:52224
	ds_read_b128 v[208:211], v147 offset:53248
	ds_read_b128 v[212:215], v147 offset:54272
	ds_read_b128 v[216:219], v147 offset:55296
	ds_read_b128 v[220:223], v147 offset:56320
	s_barrier
	s_waitcnt lgkmcnt(0)
	s_waitcnt lgkmcnt(0)
	v_mfma_f32_16x16x32_bf16 v[14:17], v[2:5], v[156:159], v[62:65]
	v_mfma_f32_16x16x32_bf16 v[54:57], v[6:9], v[160:163], v[14:17]
	v_mfma_f32_16x16x32_bf16 v[14:17], v[180:183], v[156:159], v[58:61]
	v_mfma_f32_16x16x32_bf16 v[46:49], v[184:187], v[160:163], v[14:17]
	v_mfma_f32_16x16x32_bf16 v[14:17], v[2:5], v[164:167], v[200:203]
	v_mfma_f32_16x16x32_bf16 v[38:41], v[6:9], v[168:171], v[14:17]
	v_mfma_f32_16x16x32_bf16 v[14:17], v[180:183], v[164:167], v[50:53]
	v_mfma_f32_16x16x32_bf16 v[34:37], v[184:187], v[168:171], v[14:17]
	v_mfma_f32_16x16x32_bf16 v[14:17], v[2:5], v[208:211], v[204:207]
	v_mfma_f32_16x16x32_bf16 v[2:5], v[2:5], v[216:219], v[136:139]
	v_mfma_f32_16x16x32_bf16 v[22:25], v[6:9], v[212:215], v[14:17]
	v_mfma_f32_16x16x32_bf16 v[14:17], v[180:183], v[208:211], v[42:45]
	v_mfma_f32_16x16x32_bf16 v[6:9], v[6:9], v[220:223], v[2:5]
	v_mfma_f32_16x16x32_bf16 v[2:5], v[180:183], v[216:219], v[140:143]
	v_mfma_f32_16x16x32_bf16 v[14:17], v[184:187], v[212:215], v[14:17]
	v_mfma_f32_16x16x32_bf16 v[2:5], v[184:187], v[220:223], v[2:5]
	v_mfma_f32_16x16x32_bf16 v[26:29], v[192:195], v[156:159], v[26:29]
	v_mfma_f32_16x16x32_bf16 v[58:61], v[196:199], v[160:163], v[26:29]
	v_mfma_f32_16x16x32_bf16 v[26:29], v[132:135], v[164:167], v[148:151]
	v_mfma_f32_16x16x32_bf16 v[18:21], v[192:195], v[164:167], v[18:21]
	v_mfma_f32_16x16x32_bf16 v[10:13], v[192:195], v[208:211], v[10:13]
	v_mfma_f32_16x16x32_bf16 v[30:33], v[132:135], v[156:159], v[30:33]
	v_mfma_f32_16x16x32_bf16 v[50:53], v[188:191], v[168:171], v[26:29]
	v_mfma_f32_16x16x32_bf16 v[42:45], v[196:199], v[168:171], v[18:21]
	v_mfma_f32_16x16x32_bf16 v[18:21], v[132:135], v[208:211], v[152:155]
	v_mfma_f32_16x16x32_bf16 v[26:29], v[196:199], v[212:215], v[10:13]
	v_mfma_f32_16x16x32_bf16 v[10:13], v[132:135], v[216:219], v[172:175]
	v_mfma_f32_16x16x32_bf16 v[62:65], v[188:191], v[160:163], v[30:33]
	v_mfma_f32_16x16x32_bf16 v[30:33], v[188:191], v[212:215], v[18:21]
	v_mfma_f32_16x16x32_bf16 v[18:21], v[188:191], v[220:223], v[10:13]
	v_mfma_f32_16x16x32_bf16 v[10:13], v[192:195], v[216:219], v[176:179]
	v_mfma_f32_16x16x32_bf16 v[10:13], v[196:199], v[220:223], v[10:13]
	s_cmpk_lt_u32 s38, 0x100
	s_barrier
	s_cbranch_scc0 .LBB0_109
	s_barrier
	s_branch .LBB0_109

.LBB0_122:
	s_setprio 0
	s_lshl_b32 s13, s26, 6
	v_or_b32_e32 v130, s12, v132
	v_add_u32_e32 v132, s13, v130
	v_or_b32_e32 v130, s10, v133
	v_or_b32_e32 v136, s11, v130
	v_or_b32_e32 v138, 16, v132
	v_ashrrev_i32_e32 v133, 31, v132
	v_ashrrev_i32_e32 v139, 31, v138
	s_add_i32 s14, s18, s97
	s_mov_b32 s96, 0
	s_cmpk_gt_i32 s14, 0x107
	s_cbranch_scc1 .Lpppf_skip
	s_mov_b32 s96, 1
	s_and_b32 s15, s14, 7
	s_lshr_b32 s14, s14, 3
	s_mul_i32 s15, s15, 33
	s_add_i32 s14, s14, s15
	s_lshr_b32 s15, s14, 5
	s_and_b32 s14, s14, 31
	s_cmp_lt_u32 s15, 8
	s_cselect_b32 s16, 3, 1
	s_cselect_b32 s17, 7, 1
	s_lshr_b32 s16, s14, s16
	s_and_b32 s14, s14, s17
	s_lshl_b32 s15, s15, 3
	s_add_i32 s14, s14, s15
	s_lshl_b32 s14, s14, 17
	s_lshl_b32 s16, s16, 17
	s_add_u32 s14, s0, s14
	s_addc_u32 s15, s1, 0
	s_add_u32 s16, s19, s16
	s_addc_u32 s17, s20, 0
	s_add_u32 s30, s16, 0x10000
	s_addc_u32 s31, s17, 0
	s_add_u32 s28, s14, 0x10000
	s_addc_u32 s29, s15, 0
	v_readfirstlane_b32 s27, v0
	s_lshr_b32 s27, s27, 6
	s_lshl_b32 s27, s27, 10
	s_add_i32 m0, s27, 0x10000
	s_nop 0
	global_load_lds_dwordx4 v243, s[16:17]
	s_add_i32 m0, s27, 0x12000
	s_nop 0
	global_load_lds_dwordx4 v244, s[16:17]
	s_add_i32 m0, s27, 0
	s_nop 0
	global_load_lds_dwordx4 v245, s[14:15]
	s_add_i32 m0, s27, 0x2000
	s_nop 0
	global_load_lds_dwordx4 v246, s[14:15]
	s_add_i32 m0, s27, 0x14000
	s_nop 0
	global_load_lds_dwordx4 v243, s[30:31]
	s_add_i32 m0, s27, 0x16000
	s_nop 0
	global_load_lds_dwordx4 v244, s[30:31]
	s_add_i32 m0, s27, 0x4000
	s_nop 0
	global_load_lds_dwordx4 v245, s[28:29]
	s_add_i32 m0, s27, 0x6000
	s_nop 0
	global_load_lds_dwordx4 v246, s[28:29]

.Lpppf_join:
	v_lshl_add_u64 v[14:15], s[16:17], 0, v[130:131]
	v_lshl_add_u64 v[12:13], s[16:17], 0, v[6:7]
	v_lshl_add_u64 v[8:9], s[14:15], 0, v[2:3]
	s_cmp_lg_u32 s26, 1
	v_lshl_add_u64 v[10:11], s[14:15], 0, v[4:5]
	s_cbranch_scc1 .LBB0_125
	s_setprio 1
	s_barrier
.LBB0_125:
	s_lshl_b32 s11, s28, 5
	s_add_i32 s38, s22, s35
	s_and_b32 s11, s11, 0x60
	v_lshl_add_u64 v[18:19], v[14:15], 0, s[4:5]
	s_mov_b32 m0, s38
	s_add_i32 s37, s38, 0x2000
	s_lshl_b32 s28, s26, 13
	s_lshl_b32 s30, s11, 7
	s_barrier
	global_load_lds_dwordx4 v[18:19], off
	v_lshl_add_u64 v[18:19], v[12:13], 0, s[4:5]
	s_mov_b32 m0, s37
	s_add_i32 s34, s40, 0x8000
	s_add_i32 s31, s40, 0xa000
	global_load_lds_dwordx4 v[18:19], off
	v_lshl_add_u64 v[18:19], v[8:9], 0, s[4:5]
	s_mov_b32 m0, s34
	s_add_u32 s42, s16, 0x10080
	global_load_lds_dwordx4 v[18:19], off
	v_lshl_add_u64 v[18:19], v[10:11], 0, s[4:5]
	s_mov_b32 m0, s31
	s_addc_u32 s43, s17, 0
	s_add_i32 s29, s23, s35
	global_load_lds_dwordx4 v[18:19], off
	v_lshl_add_u64 v[18:19], s[42:43], 0, v[130:131]
	s_mov_b32 m0, s29
	s_add_i32 s13, s29, 0x2000
	global_load_lds_dwordx4 v[18:19], off
	v_lshl_add_u64 v[18:19], s[42:43], 0, v[6:7]
	s_mov_b32 m0, s13
	v_lshrrev_b32_e32 v17, 1, v16
	global_load_lds_dwordx4 v[18:19], off
	v_and_b32_e32 v133, 24, v17
	v_and_b32_e32 v132, 15, v16
	v_lshlrev_b32_e32 v17, 1, v133
	v_lshlrev_b32_e32 v16, 2, v16
	v_lshl_or_b32 v17, v132, 6, v17
	v_and_b32_e32 v16, 32, v16
	v_bitop3_b32 v32, v17, s30, v16 bitop3:0xde
	v_add_u32_e32 v135, s24, v32
	v_bitop3_b32 v33, v17, s28, v16 bitop3:0xde
	s_waitcnt vmcnt(6)
	s_barrier
	ds_read_b128 v[16:19], v135
	ds_read_b128 v[20:23], v135 offset:1024
	ds_read_b128 v[24:27], v135 offset:2048
	ds_read_b128 v[28:31], v135 offset:3072
	v_add_u32_e32 v240, 0, v33
	v_add_u32_e32 v216, s25, v32
	v_add_u32_e32 v217, s22, v32
	v_add_u32_e32 v236, s23, v32
	s_add_u32 s42, s14, 0x10080
	s_addc_u32 s43, s15, 0
	s_add_i32 s30, s40, 0xc000
	v_lshl_add_u64 v[64:65], s[42:43], 0, v[2:3]
	s_mov_b32 m0, s30
	s_add_i32 s28, s40, 0xe000
	ds_read_b128 v[32:35], v240
	ds_read_b128 v[36:39], v240 offset:1024
	ds_read_b128 v[40:43], v240 offset:2048
	ds_read_b128 v[44:47], v240 offset:3072
	ds_read_b128 v[48:51], v240 offset:4096
	ds_read_b128 v[52:55], v240 offset:5120
	ds_read_b128 v[56:59], v240 offset:6144
	ds_read_b128 v[60:63], v240 offset:7168
	global_load_lds_dwordx4 v[64:65], off
	v_lshl_add_u64 v[64:65], s[42:43], 0, v[4:5]
	s_mov_b32 m0, s28
	s_nop 0
	global_load_lds_dwordx4 v[64:65], off
	s_waitcnt lgkmcnt(8)
	s_barrier
	s_waitcnt lgkmcnt(0)
	s_waitcnt lgkmcnt(0)
	v_mfma_f32_16x16x32_bf16 v[64:67], v[16:19], v[32:35], 0
	v_mfma_f32_16x16x32_bf16 v[68:71], v[24:27], v[32:35], 0
	v_mfma_f32_16x16x32_bf16 v[72:75], v[16:19], v[40:43], 0
	v_mfma_f32_16x16x32_bf16 v[76:79], v[24:27], v[40:43], 0
	v_mfma_f32_16x16x32_bf16 v[80:83], v[16:19], v[48:51], 0
	v_mfma_f32_16x16x32_bf16 v[84:87], v[24:27], v[48:51], 0
	v_mfma_f32_16x16x32_bf16 v[88:91], v[16:19], v[56:59], 0
	v_mfma_f32_16x16x32_bf16 v[92:95], v[24:27], v[56:59], 0
	v_mfma_f32_16x16x32_bf16 v[64:67], v[20:23], v[36:39], v[64:67]
	v_mfma_f32_16x16x32_bf16 v[68:71], v[28:31], v[36:39], v[68:71]
	v_mfma_f32_16x16x32_bf16 v[72:75], v[20:23], v[44:47], v[72:75]
	v_mfma_f32_16x16x32_bf16 v[76:79], v[28:31], v[44:47], v[76:79]
	v_mfma_f32_16x16x32_bf16 v[80:83], v[20:23], v[52:55], v[80:83]
	v_mfma_f32_16x16x32_bf16 v[84:87], v[28:31], v[52:55], v[84:87]
	v_mfma_f32_16x16x32_bf16 v[88:91], v[20:23], v[60:63], v[88:91]
	v_mfma_f32_16x16x32_bf16 v[92:95], v[28:31], v[60:63], v[92:95]
	s_barrier
	s_add_i32 s42, s24, s35
	v_lshl_add_u64 v[112:113], v[14:15], 0, s[6:7]
	s_mov_b32 m0, s42
	ds_read_b128 v[96:99], v216
	ds_read_b128 v[100:103], v216 offset:1024
	ds_read_b128 v[104:107], v216 offset:2048
	ds_read_b128 v[108:111], v216 offset:3072
	global_load_lds_dwordx4 v[112:113], off
	v_lshl_add_u64 v[112:113], v[12:13], 0, s[6:7]
	s_add_i32 m0, s42, 0x2000
	s_nop 0
	global_load_lds_dwordx4 v[112:113], off
	s_barrier
	s_waitcnt lgkmcnt(0)
	s_waitcnt lgkmcnt(0)
	v_mfma_f32_16x16x32_bf16 v[112:115], v[96:99], v[32:35], 0
	v_mfma_f32_16x16x32_bf16 v[32:35], v[104:107], v[32:35], 0
	v_mfma_f32_16x16x32_bf16 v[112:115], v[100:103], v[36:39], v[112:115]
	v_mfma_f32_16x16x32_bf16 v[32:35], v[108:111], v[36:39], v[32:35]
	v_mfma_f32_16x16x32_bf16 v[36:39], v[96:99], v[40:43], 0
	v_mfma_f32_16x16x32_bf16 v[40:43], v[104:107], v[40:43], 0
	v_mfma_f32_16x16x32_bf16 v[36:39], v[100:103], v[44:47], v[36:39]
	v_mfma_f32_16x16x32_bf16 v[40:43], v[108:111], v[44:47], v[40:43]
	v_mfma_f32_16x16x32_bf16 v[44:47], v[96:99], v[48:51], 0
	v_mfma_f32_16x16x32_bf16 v[48:51], v[104:107], v[48:51], 0
	v_mfma_f32_16x16x32_bf16 v[44:47], v[100:103], v[52:55], v[44:47]
	v_mfma_f32_16x16x32_bf16 v[48:51], v[108:111], v[52:55], v[48:51]
	v_mfma_f32_16x16x32_bf16 v[52:55], v[96:99], v[56:59], 0
	v_mfma_f32_16x16x32_bf16 v[56:59], v[104:107], v[56:59], 0
	v_mfma_f32_16x16x32_bf16 v[52:55], v[100:103], v[60:63], v[52:55]
	v_mfma_f32_16x16x32_bf16 v[56:59], v[108:111], v[60:63], v[56:59]
	s_mov_b32 m0, s40
	v_lshl_add_u64 v[128:129], v[8:9], 0, s[6:7]
	s_barrier
	ds_read_b128 v[60:63], v240 offset:16384
	ds_read_b128 v[116:119], v240 offset:17408
	ds_read_b128 v[120:123], v240 offset:18432
	ds_read_b128 v[124:127], v240 offset:19456
	ds_read_b128 v[136:139], v240 offset:20480
	ds_read_b128 v[140:143], v240 offset:21504
	ds_read_b128 v[144:147], v240 offset:22528
	ds_read_b128 v[148:151], v240 offset:23552
	global_load_lds_dwordx4 v[128:129], off
	v_lshl_add_u64 v[128:129], v[10:11], 0, s[6:7]
	s_mov_b32 m0, s41
	s_nop 0
	global_load_lds_dwordx4 v[128:129], off
	s_barrier
	s_waitcnt lgkmcnt(0)
	s_waitcnt lgkmcnt(0)
	v_mfma_f32_16x16x32_bf16 v[152:155], v[16:19], v[60:63], 0
	v_mfma_f32_16x16x32_bf16 v[160:163], v[16:19], v[120:123], 0
	v_mfma_f32_16x16x32_bf16 v[168:171], v[16:19], v[136:139], 0
	v_mfma_f32_16x16x32_bf16 v[16:19], v[16:19], v[144:147], 0
	v_mfma_f32_16x16x32_bf16 v[152:155], v[20:23], v[116:119], v[152:155]
	v_mfma_f32_16x16x32_bf16 v[160:163], v[20:23], v[124:127], v[160:163]
	v_mfma_f32_16x16x32_bf16 v[168:171], v[20:23], v[140:143], v[168:171]
	v_mfma_f32_16x16x32_bf16 v[16:19], v[20:23], v[148:151], v[16:19]
	v_mfma_f32_16x16x32_bf16 v[20:23], v[24:27], v[144:147], 0
	v_mfma_f32_16x16x32_bf16 v[156:159], v[24:27], v[60:63], 0
	v_mfma_f32_16x16x32_bf16 v[164:167], v[24:27], v[120:123], 0
	v_mfma_f32_16x16x32_bf16 v[172:175], v[24:27], v[136:139], 0
	v_mfma_f32_16x16x32_bf16 v[20:23], v[28:31], v[148:151], v[20:23]
	v_mfma_f32_16x16x32_bf16 v[156:159], v[28:31], v[116:119], v[156:159]
	v_mfma_f32_16x16x32_bf16 v[164:167], v[28:31], v[124:127], v[164:167]
	v_mfma_f32_16x16x32_bf16 v[172:175], v[28:31], v[140:143], v[172:175]
	s_barrier
	s_add_u32 s40, s16, 0x10100
	s_addc_u32 s41, s17, 0
	s_add_i32 s35, s25, s35
	v_lshl_add_u64 v[24:25], s[40:41], 0, v[130:131]
	s_mov_b32 m0, s35
	s_nop 0
	global_load_lds_dwordx4 v[24:25], off
	v_lshl_add_u64 v[24:25], s[40:41], 0, v[6:7]
	s_add_i32 m0, s35, 0x2000
	s_nop 0
	global_load_lds_dwordx4 v[24:25], off
	s_waitcnt vmcnt(6)
	s_barrier
	v_mfma_f32_16x16x32_bf16 v[24:27], v[96:99], v[60:63], 0
	v_mfma_f32_16x16x32_bf16 v[28:31], v[104:107], v[60:63], 0
	v_mfma_f32_16x16x32_bf16 v[24:27], v[100:103], v[116:119], v[24:27]
	v_mfma_f32_16x16x32_bf16 v[28:31], v[108:111], v[116:119], v[28:31]
	v_mfma_f32_16x16x32_bf16 v[60:63], v[96:99], v[120:123], 0
	v_mfma_f32_16x16x32_bf16 v[116:119], v[104:107], v[120:123], 0
	v_mfma_f32_16x16x32_bf16 v[120:123], v[96:99], v[136:139], 0
	v_mfma_f32_16x16x32_bf16 v[96:99], v[96:99], v[144:147], 0
	v_mfma_f32_16x16x32_bf16 v[60:63], v[100:103], v[124:127], v[60:63]
	v_mfma_f32_16x16x32_bf16 v[116:119], v[108:111], v[124:127], v[116:119]
	v_mfma_f32_16x16x32_bf16 v[120:123], v[100:103], v[140:143], v[120:123]
	v_mfma_f32_16x16x32_bf16 v[124:127], v[104:107], v[136:139], 0
	v_mfma_f32_16x16x32_bf16 v[96:99], v[100:103], v[148:151], v[96:99]
	v_mfma_f32_16x16x32_bf16 v[100:103], v[104:107], v[144:147], 0
	v_mfma_f32_16x16x32_bf16 v[124:127], v[108:111], v[140:143], v[124:127]
	v_mfma_f32_16x16x32_bf16 v[100:103], v[108:111], v[148:151], v[100:103]
	s_barrier
	ds_read_b128 v[104:107], v217
	ds_read_b128 v[108:111], v217 offset:1024
	ds_read_b128 v[136:139], v217 offset:2048
	ds_read_b128 v[140:143], v217 offset:3072
	s_add_u32 s40, s14, 0x10100
	s_addc_u32 s41, s15, 0
	s_mov_b32 m0, s39
	v_lshl_add_u64 v[128:129], s[40:41], 0, v[2:3]
	ds_read_b128 v[144:147], v240 offset:32768
	ds_read_b128 v[148:151], v240 offset:33792
	ds_read_b128 v[176:179], v240 offset:34816
	ds_read_b128 v[180:183], v240 offset:35840
	ds_read_b128 v[184:187], v240 offset:36864
	ds_read_b128 v[188:191], v240 offset:37888
	ds_read_b128 v[192:195], v240 offset:38912
	ds_read_b128 v[196:199], v240 offset:39936
	global_load_lds_dwordx4 v[128:129], off
	v_lshl_add_u64 v[128:129], s[40:41], 0, v[4:5]
	s_mov_b32 m0, s36
	s_nop 0
	global_load_lds_dwordx4 v[128:129], off
	s_waitcnt lgkmcnt(8)
	s_barrier
	s_waitcnt lgkmcnt(0)
	s_waitcnt lgkmcnt(0)
	v_mfma_f32_16x16x32_bf16 v[64:67], v[104:107], v[144:147], v[64:67]
	v_mfma_f32_16x16x32_bf16 v[68:71], v[136:139], v[144:147], v[68:71]
	v_mfma_f32_16x16x32_bf16 v[72:75], v[104:107], v[176:179], v[72:75]
	v_mfma_f32_16x16x32_bf16 v[76:79], v[136:139], v[176:179], v[76:79]
	v_mfma_f32_16x16x32_bf16 v[80:83], v[104:107], v[184:187], v[80:83]
	v_mfma_f32_16x16x32_bf16 v[84:87], v[136:139], v[184:187], v[84:87]
	v_mfma_f32_16x16x32_bf16 v[88:91], v[104:107], v[192:195], v[88:91]
	v_mfma_f32_16x16x32_bf16 v[92:95], v[136:139], v[192:195], v[92:95]
	v_mfma_f32_16x16x32_bf16 v[64:67], v[108:111], v[148:151], v[64:67]
	v_mfma_f32_16x16x32_bf16 v[68:71], v[140:143], v[148:151], v[68:71]
	v_mfma_f32_16x16x32_bf16 v[72:75], v[108:111], v[180:183], v[72:75]
	v_mfma_f32_16x16x32_bf16 v[76:79], v[140:143], v[180:183], v[76:79]
	v_mfma_f32_16x16x32_bf16 v[80:83], v[108:111], v[188:191], v[80:83]
	v_mfma_f32_16x16x32_bf16 v[84:87], v[140:143], v[188:191], v[84:87]
	v_mfma_f32_16x16x32_bf16 v[88:91], v[108:111], v[196:199], v[88:91]
	v_mfma_f32_16x16x32_bf16 v[92:95], v[140:143], v[196:199], v[92:95]
	s_barrier
	s_mov_b32 m0, s38
	v_lshl_add_u64 v[14:15], v[14:15], 0, s[8:9]
	ds_read_b128 v[200:203], v236
	ds_read_b128 v[204:207], v236 offset:1024
	ds_read_b128 v[208:211], v236 offset:2048
	ds_read_b128 v[212:215], v236 offset:3072
	global_load_lds_dwordx4 v[14:15], off
	v_lshl_add_u64 v[12:13], v[12:13], 0, s[8:9]
	s_mov_b32 m0, s37
	s_nop 0
	global_load_lds_dwordx4 v[12:13], off
	s_barrier
	s_waitcnt lgkmcnt(0)
	s_waitcnt lgkmcnt(0)
	v_mfma_f32_16x16x32_bf16 v[12:15], v[200:203], v[144:147], v[112:115]
	v_mfma_f32_16x16x32_bf16 v[32:35], v[208:211], v[144:147], v[32:35]
	v_mfma_f32_16x16x32_bf16 v[36:39], v[200:203], v[176:179], v[36:39]
	v_mfma_f32_16x16x32_bf16 v[40:43], v[208:211], v[176:179], v[40:43]
	v_mfma_f32_16x16x32_bf16 v[44:47], v[200:203], v[184:187], v[44:47]
	v_mfma_f32_16x16x32_bf16 v[48:51], v[208:211], v[184:187], v[48:51]
	v_mfma_f32_16x16x32_bf16 v[52:55], v[200:203], v[192:195], v[52:55]
	v_mfma_f32_16x16x32_bf16 v[56:59], v[208:211], v[192:195], v[56:59]
	v_mfma_f32_16x16x32_bf16 v[12:15], v[204:207], v[148:151], v[12:15]
	v_mfma_f32_16x16x32_bf16 v[32:35], v[212:215], v[148:151], v[32:35]
	v_mfma_f32_16x16x32_bf16 v[36:39], v[204:207], v[180:183], v[36:39]
	v_mfma_f32_16x16x32_bf16 v[40:43], v[212:215], v[180:183], v[40:43]
	v_mfma_f32_16x16x32_bf16 v[44:47], v[204:207], v[188:191], v[44:47]
	v_mfma_f32_16x16x32_bf16 v[48:51], v[212:215], v[188:191], v[48:51]
	v_mfma_f32_16x16x32_bf16 v[52:55], v[204:207], v[196:199], v[52:55]
	v_mfma_f32_16x16x32_bf16 v[56:59], v[212:215], v[196:199], v[56:59]
	s_mov_b32 m0, s34
	v_lshl_add_u64 v[8:9], v[8:9], 0, s[8:9]
	s_barrier
	ds_read_b128 v[112:115], v240 offset:49152
	ds_read_b128 v[144:147], v240 offset:50176
	ds_read_b128 v[148:151], v240 offset:51200
	ds_read_b128 v[176:179], v240 offset:52224
	ds_read_b128 v[180:183], v240 offset:53248
	ds_read_b128 v[184:187], v240 offset:54272
	ds_read_b128 v[188:191], v240 offset:55296
	ds_read_b128 v[192:195], v240 offset:56320
	global_load_lds_dwordx4 v[8:9], off
	v_lshl_add_u64 v[8:9], v[10:11], 0, s[8:9]
	s_mov_b32 m0, s31
	s_nop 0
	global_load_lds_dwordx4 v[8:9], off
	s_barrier
	s_waitcnt lgkmcnt(0)
	s_waitcnt lgkmcnt(0)
	v_mfma_f32_16x16x32_bf16 v[8:11], v[104:107], v[112:115], v[152:155]
	v_mfma_f32_16x16x32_bf16 v[16:19], v[104:107], v[188:191], v[16:19]
	v_mfma_f32_16x16x32_bf16 v[20:23], v[136:139], v[188:191], v[20:23]
	v_mfma_f32_16x16x32_bf16 v[8:11], v[108:111], v[144:147], v[8:11]
	v_mfma_f32_16x16x32_bf16 v[152:155], v[136:139], v[112:115], v[156:159]
	v_mfma_f32_16x16x32_bf16 v[156:159], v[104:107], v[148:151], v[160:163]
	v_mfma_f32_16x16x32_bf16 v[160:163], v[136:139], v[148:151], v[164:167]
	v_mfma_f32_16x16x32_bf16 v[164:167], v[104:107], v[180:183], v[168:171]
	v_mfma_f32_16x16x32_bf16 v[168:171], v[136:139], v[180:183], v[172:175]
	v_mfma_f32_16x16x32_bf16 v[16:19], v[108:111], v[192:195], v[16:19]
	v_mfma_f32_16x16x32_bf16 v[20:23], v[140:143], v[192:195], v[20:23]
	v_mfma_f32_16x16x32_bf16 v[152:155], v[140:143], v[144:147], v[152:155]
	v_mfma_f32_16x16x32_bf16 v[156:159], v[108:111], v[176:179], v[156:159]
	v_mfma_f32_16x16x32_bf16 v[160:163], v[140:143], v[176:179], v[160:163]
	v_mfma_f32_16x16x32_bf16 v[164:167], v[108:111], v[184:187], v[164:167]
	v_mfma_f32_16x16x32_bf16 v[168:171], v[140:143], v[184:187], v[168:171]
	s_barrier
	s_add_u32 s16, s16, 0x10180
	s_addc_u32 s17, s17, 0
	s_mov_b32 m0, s29
	v_lshl_add_u64 v[104:105], s[16:17], 0, v[130:131]
	global_load_lds_dwordx4 v[104:105], off
	v_lshl_add_u64 v[6:7], s[16:17], 0, v[6:7]
	s_mov_b32 m0, s13
	s_nop 0
	global_load_lds_dwordx4 v[6:7], off
	s_waitcnt vmcnt(6)
	s_barrier
	v_mfma_f32_16x16x32_bf16 v[24:27], v[200:203], v[112:115], v[24:27]
	v_mfma_f32_16x16x32_bf16 v[28:31], v[208:211], v[112:115], v[28:31]
	v_mfma_f32_16x16x32_bf16 v[60:63], v[200:203], v[148:151], v[60:63]
	v_mfma_f32_16x16x32_bf16 v[104:107], v[208:211], v[148:151], v[116:119]
	v_mfma_f32_16x16x32_bf16 v[108:111], v[200:203], v[180:183], v[120:123]
	v_mfma_f32_16x16x32_bf16 v[112:115], v[208:211], v[180:183], v[124:127]
	v_mfma_f32_16x16x32_bf16 v[96:99], v[200:203], v[188:191], v[96:99]
	v_mfma_f32_16x16x32_bf16 v[100:103], v[208:211], v[188:191], v[100:103]
	v_mfma_f32_16x16x32_bf16 v[24:27], v[204:207], v[144:147], v[24:27]
	v_mfma_f32_16x16x32_bf16 v[28:31], v[212:215], v[144:147], v[28:31]
	v_mfma_f32_16x16x32_bf16 v[60:63], v[204:207], v[176:179], v[60:63]
	v_mfma_f32_16x16x32_bf16 v[104:107], v[212:215], v[176:179], v[104:107]
	v_mfma_f32_16x16x32_bf16 v[108:111], v[204:207], v[184:187], v[108:111]
	v_mfma_f32_16x16x32_bf16 v[112:115], v[212:215], v[184:187], v[112:115]
	v_mfma_f32_16x16x32_bf16 v[96:99], v[204:207], v[192:195], v[96:99]
	v_mfma_f32_16x16x32_bf16 v[100:103], v[212:215], v[192:195], v[100:103]
	s_add_u32 s14, s14, 0x10180
	s_addc_u32 s15, s15, 0
	s_mov_b32 m0, s30
	v_lshl_add_u64 v[2:3], s[14:15], 0, v[2:3]
	s_barrier
	ds_read_b128 v[116:119], v135
	ds_read_b128 v[120:123], v135 offset:1024
	ds_read_b128 v[124:127], v135 offset:2048
	ds_read_b128 v[136:139], v135 offset:3072
	ds_read_b128 v[140:143], v240
	ds_read_b128 v[144:147], v240 offset:1024
	ds_read_b128 v[148:151], v240 offset:2048
	ds_read_b128 v[172:175], v240 offset:3072
	ds_read_b128 v[176:179], v240 offset:4096
	ds_read_b128 v[180:183], v240 offset:5120
	ds_read_b128 v[184:187], v240 offset:6144
	ds_read_b128 v[188:191], v240 offset:7168
	global_load_lds_dwordx4 v[2:3], off
	v_lshl_add_u64 v[2:3], s[14:15], 0, v[4:5]
	s_mov_b32 m0, s28
	s_nop 0
	global_load_lds_dwordx4 v[2:3], off
	s_barrier
	s_waitcnt lgkmcnt(0)
	s_waitcnt lgkmcnt(0)
	v_mfma_f32_16x16x32_bf16 v[2:5], v[116:119], v[140:143], v[64:67]
	v_mfma_f32_16x16x32_bf16 v[64:67], v[124:127], v[140:143], v[68:71]
	v_mfma_f32_16x16x32_bf16 v[68:71], v[116:119], v[148:151], v[72:75]
	v_mfma_f32_16x16x32_bf16 v[72:75], v[124:127], v[148:151], v[76:79]
	v_mfma_f32_16x16x32_bf16 v[76:79], v[116:119], v[176:179], v[80:83]
	v_mfma_f32_16x16x32_bf16 v[80:83], v[124:127], v[176:179], v[84:87]
	v_mfma_f32_16x16x32_bf16 v[84:87], v[116:119], v[184:187], v[88:91]
	v_mfma_f32_16x16x32_bf16 v[192:195], v[120:123], v[188:191], v[84:87]
	v_mfma_f32_16x16x32_bf16 v[84:87], v[124:127], v[184:187], v[92:95]
	v_mfma_f32_16x16x32_bf16 v[2:5], v[120:123], v[144:147], v[2:5]
	v_mfma_f32_16x16x32_bf16 v[64:67], v[136:139], v[144:147], v[64:67]
	v_mfma_f32_16x16x32_bf16 v[68:71], v[120:123], v[172:175], v[68:71]
	v_mfma_f32_16x16x32_bf16 v[72:75], v[136:139], v[172:175], v[72:75]
	v_mfma_f32_16x16x32_bf16 v[76:79], v[120:123], v[180:183], v[76:79]
	v_mfma_f32_16x16x32_bf16 v[80:83], v[136:139], v[180:183], v[80:83]
	v_mfma_f32_16x16x32_bf16 v[90:93], v[136:139], v[188:191], v[84:87]
	s_barrier
	s_nop 0
	ds_read_b128 v[84:87], v216
	ds_read_b128 v[196:199], v216 offset:1024
	ds_read_b128 v[200:203], v216 offset:2048
	ds_read_b128 v[204:207], v216 offset:3072
	s_barrier
	s_waitcnt lgkmcnt(0)
	s_waitcnt lgkmcnt(0)
	v_mfma_f32_16x16x32_bf16 v[12:15], v[84:87], v[140:143], v[12:15]
	v_mfma_f32_16x16x32_bf16 v[32:35], v[200:203], v[140:143], v[32:35]
	v_mfma_f32_16x16x32_bf16 v[36:39], v[84:87], v[148:151], v[36:39]
	v_mfma_f32_16x16x32_bf16 v[40:43], v[200:203], v[148:151], v[40:43]
	v_mfma_f32_16x16x32_bf16 v[44:47], v[84:87], v[176:179], v[44:47]
	v_mfma_f32_16x16x32_bf16 v[48:51], v[200:203], v[176:179], v[48:51]
	v_mfma_f32_16x16x32_bf16 v[52:55], v[84:87], v[184:187], v[52:55]
	v_mfma_f32_16x16x32_bf16 v[12:15], v[196:199], v[144:147], v[12:15]
	v_mfma_f32_16x16x32_bf16 v[32:35], v[204:207], v[144:147], v[32:35]
	v_mfma_f32_16x16x32_bf16 v[36:39], v[196:199], v[172:175], v[36:39]
	v_mfma_f32_16x16x32_bf16 v[40:43], v[204:207], v[172:175], v[40:43]
	v_mfma_f32_16x16x32_bf16 v[44:47], v[196:199], v[180:183], v[44:47]
	v_mfma_f32_16x16x32_bf16 v[48:51], v[204:207], v[180:183], v[48:51]
	v_mfma_f32_16x16x32_bf16 v[52:55], v[196:199], v[188:191], v[52:55]
	v_mfma_f32_16x16x32_bf16 v[56:59], v[200:203], v[184:187], v[56:59]
	v_mfma_f32_16x16x32_bf16 v[140:143], v[204:207], v[188:191], v[56:59]
	s_barrier
	s_nop 4
	ds_read_b128 v[56:59], v240 offset:16384
	ds_read_b128 v[144:147], v240 offset:17408
	ds_read_b128 v[148:151], v240 offset:18432
	ds_read_b128 v[172:175], v240 offset:19456
	ds_read_b128 v[176:179], v240 offset:20480
	ds_read_b128 v[180:183], v240 offset:21504
	ds_read_b128 v[184:187], v240 offset:22528
	ds_read_b128 v[188:191], v240 offset:23552
	s_waitcnt vmcnt(4)
	s_barrier
	s_waitcnt lgkmcnt(0)
	s_waitcnt lgkmcnt(0)
	v_mfma_f32_16x16x32_bf16 v[6:9], v[116:119], v[56:59], v[8:11]
	v_mfma_f32_16x16x32_bf16 v[16:19], v[116:119], v[184:187], v[16:19]
	v_mfma_f32_16x16x32_bf16 v[6:9], v[120:123], v[144:147], v[6:9]
	v_mfma_f32_16x16x32_bf16 v[152:155], v[124:127], v[56:59], v[152:155]
	v_mfma_f32_16x16x32_bf16 v[156:159], v[116:119], v[148:151], v[156:159]
	v_mfma_f32_16x16x32_bf16 v[160:163], v[124:127], v[148:151], v[160:163]
	v_mfma_f32_16x16x32_bf16 v[164:167], v[116:119], v[176:179], v[164:167]
	v_mfma_f32_16x16x32_bf16 v[168:171], v[124:127], v[176:179], v[168:171]
	v_mfma_f32_16x16x32_bf16 v[16:19], v[120:123], v[188:191], v[16:19]
	v_mfma_f32_16x16x32_bf16 v[20:23], v[124:127], v[184:187], v[20:23]
	v_mfma_f32_16x16x32_bf16 v[152:155], v[136:139], v[144:147], v[152:155]
	v_mfma_f32_16x16x32_bf16 v[156:159], v[120:123], v[172:175], v[156:159]
	v_mfma_f32_16x16x32_bf16 v[160:163], v[136:139], v[172:175], v[160:163]
	v_mfma_f32_16x16x32_bf16 v[164:167], v[120:123], v[180:183], v[164:167]
	v_mfma_f32_16x16x32_bf16 v[168:171], v[136:139], v[180:183], v[168:171]
	v_mfma_f32_16x16x32_bf16 v[136:139], v[136:139], v[188:191], v[20:23]
	v_mfma_f32_16x16x32_bf16 v[20:23], v[84:87], v[56:59], v[24:27]
	v_mfma_f32_16x16x32_bf16 v[208:211], v[196:199], v[144:147], v[20:23]
	v_mfma_f32_16x16x32_bf16 v[20:23], v[200:203], v[56:59], v[28:31]
	v_mfma_f32_16x16x32_bf16 v[26:29], v[204:207], v[144:147], v[20:23]
	v_mfma_f32_16x16x32_bf16 v[20:23], v[84:87], v[148:151], v[60:63]
	v_mfma_f32_16x16x32_bf16 v[144:147], v[196:199], v[172:175], v[20:23]
	v_mfma_f32_16x16x32_bf16 v[20:23], v[200:203], v[148:151], v[104:107]
	v_mfma_f32_16x16x32_bf16 v[148:151], v[204:207], v[172:175], v[20:23]
	v_mfma_f32_16x16x32_bf16 v[20:23], v[84:87], v[176:179], v[108:111]
	v_mfma_f32_16x16x32_bf16 v[172:175], v[196:199], v[180:183], v[20:23]
	v_mfma_f32_16x16x32_bf16 v[20:23], v[200:203], v[176:179], v[112:115]
	v_mfma_f32_16x16x32_bf16 v[176:179], v[204:207], v[180:183], v[20:23]
	v_mfma_f32_16x16x32_bf16 v[20:23], v[84:87], v[184:187], v[96:99]
	v_mfma_f32_16x16x32_bf16 v[180:183], v[196:199], v[188:191], v[20:23]
	v_mfma_f32_16x16x32_bf16 v[20:23], v[200:203], v[184:187], v[100:103]
	v_mfma_f32_16x16x32_bf16 v[184:187], v[204:207], v[188:191], v[20:23]
	s_barrier
	ds_read_b128 v[188:191], v217
	ds_read_b128 v[196:199], v217 offset:1024
	ds_read_b128 v[200:203], v217 offset:2048
	ds_read_b128 v[204:207], v217 offset:3072
	s_nop 0
	ds_read_b128 v[20:23], v240 offset:32768
	ds_read_b128 v[94:97], v240 offset:33792
	ds_read_b128 v[106:109], v240 offset:34816
	ds_read_b128 v[212:215], v240 offset:35840
	ds_read_b128 v[216:219], v240 offset:36864
	ds_read_b128 v[220:223], v240 offset:37888
	ds_read_b128 v[224:227], v240 offset:38912
	ds_read_b128 v[228:231], v240 offset:39936
	s_waitcnt vmcnt(2)
	s_barrier
	s_waitcnt lgkmcnt(0)
	s_waitcnt lgkmcnt(0)
	v_mfma_f32_16x16x32_bf16 v[2:5], v[188:191], v[20:23], v[2:5]
	v_mfma_f32_16x16x32_bf16 v[122:125], v[196:199], v[94:97], v[2:5]
	v_mfma_f32_16x16x32_bf16 v[2:5], v[200:203], v[20:23], v[64:67]
	v_mfma_f32_16x16x32_bf16 v[114:117], v[204:207], v[94:97], v[2:5]
	v_mfma_f32_16x16x32_bf16 v[2:5], v[188:191], v[106:109], v[68:71]
	v_mfma_f32_16x16x32_bf16 v[102:105], v[196:199], v[212:215], v[2:5]
	v_mfma_f32_16x16x32_bf16 v[2:5], v[200:203], v[106:109], v[72:75]
	v_mfma_f32_16x16x32_bf16 v[98:101], v[204:207], v[212:215], v[2:5]
	v_mfma_f32_16x16x32_bf16 v[2:5], v[188:191], v[216:219], v[76:79]
	v_mfma_f32_16x16x32_bf16 v[86:89], v[196:199], v[220:223], v[2:5]
	v_mfma_f32_16x16x32_bf16 v[2:5], v[200:203], v[216:219], v[80:83]
	v_mfma_f32_16x16x32_bf16 v[82:85], v[204:207], v[220:223], v[2:5]
	v_mfma_f32_16x16x32_bf16 v[2:5], v[188:191], v[224:227], v[192:195]
	v_mfma_f32_16x16x32_bf16 v[70:73], v[196:199], v[228:231], v[2:5]
	v_mfma_f32_16x16x32_bf16 v[2:5], v[200:203], v[224:227], v[90:93]
	v_mfma_f32_16x16x32_bf16 v[58:61], v[204:207], v[228:231], v[2:5]
	s_barrier
	s_nop 4
	ds_read_b128 v[2:5], v236
	ds_read_b128 v[192:195], v236 offset:1024
	ds_read_b128 v[232:235], v236 offset:2048
	ds_read_b128 v[236:239], v236 offset:3072
	s_waitcnt vmcnt(0)
	s_barrier
	s_waitcnt lgkmcnt(0)
	s_waitcnt lgkmcnt(0)
	v_mfma_f32_16x16x32_bf16 v[10:13], v[2:5], v[20:23], v[12:15]
	v_mfma_f32_16x16x32_bf16 v[126:129], v[192:195], v[94:97], v[10:13]
	v_mfma_f32_16x16x32_bf16 v[10:13], v[232:235], v[20:23], v[32:35]
	v_mfma_f32_16x16x32_bf16 v[118:121], v[236:239], v[94:97], v[10:13]
	v_mfma_f32_16x16x32_bf16 v[10:13], v[2:5], v[106:109], v[36:39]
	v_mfma_f32_16x16x32_bf16 v[110:113], v[192:195], v[212:215], v[10:13]
	v_mfma_f32_16x16x32_bf16 v[10:13], v[232:235], v[106:109], v[40:43]
	v_mfma_f32_16x16x32_bf16 v[106:109], v[236:239], v[212:215], v[10:13]
	v_mfma_f32_16x16x32_bf16 v[10:13], v[2:5], v[216:219], v[44:47]
	v_mfma_f32_16x16x32_bf16 v[94:97], v[192:195], v[220:223], v[10:13]
	v_mfma_f32_16x16x32_bf16 v[10:13], v[232:235], v[216:219], v[48:51]
	v_mfma_f32_16x16x32_bf16 v[90:93], v[236:239], v[220:223], v[10:13]
	v_mfma_f32_16x16x32_bf16 v[10:13], v[2:5], v[224:227], v[52:55]
	v_mfma_f32_16x16x32_bf16 v[78:81], v[192:195], v[228:231], v[10:13]
	v_mfma_f32_16x16x32_bf16 v[10:13], v[232:235], v[224:227], v[140:143]
	v_mfma_f32_16x16x32_bf16 v[74:77], v[236:239], v[228:231], v[10:13]
	s_barrier
	s_nop 4
	ds_read_b128 v[10:13], v240 offset:49152
	ds_read_b128 v[34:37], v240 offset:50176
	ds_read_b128 v[140:143], v240 offset:51200
	ds_read_b128 v[212:215], v240 offset:52224
	ds_read_b128 v[216:219], v240 offset:53248
	ds_read_b128 v[220:223], v240 offset:54272
	ds_read_b128 v[224:227], v240 offset:55296
	ds_read_b128 v[228:231], v240 offset:56320
	s_barrier
	s_waitcnt lgkmcnt(0)
	s_waitcnt lgkmcnt(0)
	v_mfma_f32_16x16x32_bf16 v[6:9], v[188:191], v[10:13], v[6:9]
	v_mfma_f32_16x16x32_bf16 v[66:69], v[196:199], v[34:37], v[6:9]
	v_mfma_f32_16x16x32_bf16 v[6:9], v[200:203], v[10:13], v[152:155]
	v_mfma_f32_16x16x32_bf16 v[54:57], v[204:207], v[34:37], v[6:9]
	v_mfma_f32_16x16x32_bf16 v[6:9], v[188:191], v[140:143], v[156:159]
	v_mfma_f32_16x16x32_bf16 v[46:49], v[196:199], v[212:215], v[6:9]
	v_mfma_f32_16x16x32_bf16 v[6:9], v[200:203], v[140:143], v[160:163]
	v_mfma_f32_16x16x32_bf16 v[38:41], v[204:207], v[212:215], v[6:9]
	v_mfma_f32_16x16x32_bf16 v[6:9], v[188:191], v[216:219], v[164:167]
	v_mfma_f32_16x16x32_bf16 v[30:33], v[196:199], v[220:223], v[6:9]
	v_mfma_f32_16x16x32_bf16 v[6:9], v[200:203], v[216:219], v[168:171]
	v_mfma_f32_16x16x32_bf16 v[22:25], v[204:207], v[220:223], v[6:9]
	v_mfma_f32_16x16x32_bf16 v[6:9], v[188:191], v[224:227], v[16:19]
	v_mfma_f32_16x16x32_bf16 v[14:17], v[196:199], v[228:231], v[6:9]
	v_mfma_f32_16x16x32_bf16 v[6:9], v[200:203], v[224:227], v[136:139]
	v_mfma_f32_16x16x32_bf16 v[6:9], v[204:207], v[228:231], v[6:9]
	v_mfma_f32_16x16x32_bf16 v[18:21], v[2:5], v[10:13], v[208:211]
	v_mfma_f32_16x16x32_bf16 v[10:13], v[232:235], v[10:13], v[26:29]
	v_mfma_f32_16x16x32_bf16 v[50:53], v[236:239], v[34:37], v[10:13]
	v_mfma_f32_16x16x32_bf16 v[10:13], v[2:5], v[140:143], v[144:147]
	v_mfma_f32_16x16x32_bf16 v[42:45], v[192:195], v[212:215], v[10:13]
	v_mfma_f32_16x16x32_bf16 v[10:13], v[232:235], v[140:143], v[148:151]
	v_mfma_f32_16x16x32_bf16 v[62:65], v[192:195], v[34:37], v[18:21]
	v_mfma_f32_16x16x32_bf16 v[34:37], v[236:239], v[212:215], v[10:13]
	v_mfma_f32_16x16x32_bf16 v[10:13], v[2:5], v[216:219], v[172:175]
	v_mfma_f32_16x16x32_bf16 v[26:29], v[192:195], v[220:223], v[10:13]
	v_mfma_f32_16x16x32_bf16 v[10:13], v[232:235], v[216:219], v[176:179]
	v_mfma_f32_16x16x32_bf16 v[2:5], v[2:5], v[224:227], v[180:183]
	v_mfma_f32_16x16x32_bf16 v[18:21], v[236:239], v[220:223], v[10:13]
	v_mfma_f32_16x16x32_bf16 v[10:13], v[192:195], v[228:231], v[2:5]
	v_mfma_f32_16x16x32_bf16 v[2:5], v[232:235], v[224:227], v[184:187]
	v_mfma_f32_16x16x32_bf16 v[2:5], v[236:239], v[228:231], v[2:5]
	s_cmpk_gt_u32 s27, 0xff
	s_barrier
	s_cbranch_scc1 .LBB0_122
	s_barrier
	s_branch .LBB0_122

.LBB0_455:
	s_setprio 0
	v_or_b32_e32 v106, s43, v146
	v_add_u32_e32 v170, s29, v106
	v_or_b32_e32 v106, s45, v147
	v_or_b32_e32 v106, s28, v106
	v_mov_b64_e32 v[172:173], s[60:61]
	v_ashrrev_i32_e32 v107, 31, v106
	v_mad_i64_i32 v[108:109], s[28:29], v170, s40, v[172:173]
	v_lshl_add_u64 v[176:177], v[106:107], 2, s[62:63]
	v_lshl_add_u64 v[110:111], v[108:109], 0, s[26:27]
	v_lshlrev_b64 v[174:175], 1, v[106:107]
	global_load_dwordx4 v[130:133], v[176:177], off offset:16
	global_load_dwordx4 v[146:149], v[176:177], off
	v_lshl_add_u64 v[112:113], v[110:111], 0, v[174:175]
	v_lshl_add_u64 v[182:183], v[108:109], 0, v[174:175]
	global_load_dwordx4 v[186:189], v[112:113], off
	global_load_dwordx4 v[190:193], v[182:183], off offset:2048
	v_or_b32_e32 v106, 0x80, v106
	v_or_b32_e32 v108, 16, v170
	v_ashrrev_i32_e32 v107, 31, v106
	v_mad_i64_i32 v[112:113], s[28:29], v108, s40, v[172:173]
	v_lshlrev_b64 v[178:179], 1, v[106:107]
	global_load_dwordx4 v[106:109], v[176:177], off offset:528
	global_load_dwordx4 v[118:121], v[176:177], off offset:512
	global_load_dwordx4 v[158:161], v[182:183], off offset:2304
	v_lshl_add_u64 v[114:115], v[112:113], 0, s[26:27]
	v_lshl_add_u64 v[180:181], v[112:113], 0, v[174:175]
	v_lshl_add_u64 v[110:111], v[110:111], 0, v[178:179]
	v_lshl_add_u64 v[112:113], v[114:115], 0, v[174:175]
	v_lshl_add_u64 v[194:195], v[114:115], 0, v[178:179]
	global_load_dwordx4 v[138:141], v[180:181], off offset:2048
	global_load_dwordx4 v[114:117], v[180:181], off offset:2304
	global_load_dwordx4 v[154:157], v[110:111], off
	global_load_dwordx4 v[134:137], v[112:113], off
	s_nop 0
	global_load_dwordx4 v[110:113], v[194:195], off
	s_add_i32 s42, s42, s58
	s_cmpk_gt_i32 s42, 0xff
	s_waitcnt vmcnt(0)
	v_add_f32_e32 v162, v162, v130
	v_add_f32_e32 v166, v166, v146
	v_add_f32_e32 v168, v168, v148
	v_add_f32_e32 v169, v169, v149
	v_add_f32_e32 v163, v163, v131
	v_lshlrev_b32_e32 v197, 16, v190
	v_mul_f32_e32 v166, 0xbfb8aa3b, v166
	v_add_f32_e32 v167, v167, v147
	v_lshlrev_b32_e32 v196, 16, v186
	v_and_b32_e32 v198, 0xffff0000, v186
	v_and_b32_e32 v199, 0xffff0000, v190
	v_lshlrev_b32_e32 v201, 16, v191
	v_mul_f32_e32 v168, 0xbfb8aa3b, v168
	v_and_b32_e32 v203, 0xffff0000, v191
	v_mul_f32_e32 v186, 0xbfb8aa3b, v169
	v_mul_f32_e32 v162, 0xbfb8aa3b, v162
	v_mul_f32_e32 v190, 0xbfb8aa3b, v163
	v_exp_f32_e32 v163, v166
	v_mul_f32_e32 v166, 0xbfb8aa3b, v197
	v_mul_f32_e32 v167, 0xbfb8aa3b, v167
	v_lshlrev_b32_e32 v200, 16, v187
	v_and_b32_e32 v202, 0xffff0000, v187
	v_mul_f32_e32 v194, 0xbfb8aa3b, v199
	v_exp_f32_e32 v169, v168
	v_mul_f32_e32 v168, 0xbfb8aa3b, v201
	v_exp_f32_e32 v187, v186
	v_mul_f32_e32 v186, 0xbfb8aa3b, v203
	v_exp_f32_e32 v191, v162
	v_exp_f32_e32 v162, v166
	v_exp_f32_e32 v167, v167
	v_exp_f32_e32 v166, v194
	v_exp_f32_e32 v168, v168
	v_exp_f32_e32 v186, v186
	v_pk_add_f32 v[162:163], v[162:163], 1.0 op_sel_hi:[1,0]
	v_lshlrev_b32_e32 v205, 16, v192
	v_pk_add_f32 v[166:167], v[166:167], 1.0 op_sel_hi:[1,0]
	v_pk_add_f32 v[168:169], v[168:169], 1.0 op_sel_hi:[1,0]
	v_pk_add_f32 v[186:187], v[186:187], 1.0 op_sel_hi:[1,0]
	v_mul_f32_e32 v162, v162, v163
	v_mul_f32_e32 v206, 0xbfb8aa3b, v205
	v_mul_f32_e32 v163, v166, v167
	v_mul_f32_e32 v166, v168, v169
	v_mul_f32_e32 v167, v186, v187
	v_rcp_f32_e32 v162, v162
	v_and_b32_e32 v192, 0xffff0000, v192
	v_exp_f32_e32 v195, v190
	v_exp_f32_e32 v190, v206
	v_rcp_f32_e32 v163, v163
	v_rcp_f32_e32 v166, v166
	v_rcp_f32_e32 v167, v167
	v_mul_f32_e32 v207, 0xbfb8aa3b, v192
	v_exp_f32_e32 v194, v207
	v_mul_f32_e32 v162, v162, v197
	v_pk_add_f32 v[190:191], v[190:191], 1.0 op_sel_hi:[1,0]
	v_mul_f32_e32 v163, v163, v199
	v_mul_f32_e32 v166, v166, v201
	v_mul_f32_e32 v167, v167, v203
	v_mul_f32_e32 v162, v162, v196
	v_mul_f32_e32 v163, v163, v198
	v_mul_f32_e32 v168, v166, v200
	v_mul_f32_e32 v167, v167, v202
	v_cvt_pk_bf16_f32 v166, v162, v163
	v_mul_f32_e32 v162, v190, v191
	v_cvt_pk_bf16_f32 v167, v168, v167
	v_rcp_f32_e32 v168, v162
	v_pk_add_f32 v[162:163], v[194:195], 1.0 op_sel_hi:[1,0]
	v_lshlrev_b32_e32 v204, 16, v188
	v_mul_f32_e32 v162, v162, v163
	v_rcp_f32_e32 v162, v162
	v_mul_f32_e32 v163, v168, v205
	v_and_b32_e32 v168, 0xffff0000, v188
	v_mul_f32_e32 v163, v163, v204
	v_mul_f32_e32 v162, v162, v192
	v_mul_f32_e32 v162, v162, v168
	v_cvt_pk_bf16_f32 v168, v163, v162
	v_add_f32_e32 v162, v164, v132
	v_lshlrev_b32_e32 v186, 16, v193
	v_mul_f32_e32 v162, 0xbfb8aa3b, v162
	v_exp_f32_e32 v163, v162
	v_mul_f32_e32 v162, 0xbfb8aa3b, v186
	v_add_f32_e32 v164, v165, v133
	v_exp_f32_e32 v162, v162
	v_and_b32_e32 v187, 0xffff0000, v193
	v_mul_f32_e32 v164, 0xbfb8aa3b, v164
	v_exp_f32_e32 v165, v164
	v_mul_f32_e32 v164, 0xbfb8aa3b, v187
	v_exp_f32_e32 v164, v164
	v_pk_add_f32 v[162:163], v[162:163], 1.0 op_sel_hi:[1,0]
	v_lshlrev_b32_e32 v169, 16, v189
	v_mul_f32_e32 v162, v162, v163
	v_rcp_f32_e32 v188, v162
	v_pk_add_f32 v[162:163], v[164:165], 1.0 op_sel_hi:[1,0]
	v_add_f32_e32 v150, v150, v118
	v_mul_f32_e32 v162, v162, v163
	v_rcp_f32_e32 v162, v162
	v_mul_f32_e32 v163, v188, v186
	v_mul_f32_e32 v163, v163, v169
	v_and_b32_e32 v164, 0xffff0000, v189
	v_mul_f32_e32 v162, v162, v187
	v_lshlrev_b32_e32 v165, 16, v158
	v_mul_f32_e32 v150, 0xbfb8aa3b, v150
	v_mul_f32_e32 v162, v162, v164
	v_cvt_pk_bf16_f32 v169, v163, v162
	v_exp_f32_e32 v163, v150
	v_mul_f32_e32 v150, 0xbfb8aa3b, v165
	v_exp_f32_e32 v162, v150
	v_add_f32_e32 v150, v151, v119
	v_and_b32_e32 v158, 0xffff0000, v158
	v_mul_f32_e32 v150, 0xbfb8aa3b, v150
	v_exp_f32_e32 v151, v150
	v_mul_f32_e32 v150, 0xbfb8aa3b, v158
	v_exp_f32_e32 v150, v150
	v_pk_add_f32 v[162:163], v[162:163], 1.0 op_sel_hi:[1,0]
	v_lshlrev_b32_e32 v164, 16, v154
	v_mul_f32_e32 v162, v162, v163
	v_pk_add_f32 v[150:151], v[150:151], 1.0 op_sel_hi:[1,0]
	v_rcp_f32_e32 v162, v162
	v_mul_f32_e32 v150, v150, v151
	v_rcp_f32_e32 v150, v150
	v_and_b32_e32 v154, 0xffff0000, v154
	v_add_f32_e32 v152, v152, v120
	v_mul_f32_e32 v152, 0xbfb8aa3b, v152
	v_mul_f32_e32 v150, v150, v158
	v_mul_f32_e32 v150, v150, v154
	v_lshlrev_b32_e32 v154, 16, v159
	v_exp_f32_e32 v163, v152
	v_mul_f32_e32 v152, 0xbfb8aa3b, v154
	v_mul_f32_e32 v151, v162, v165
	v_exp_f32_e32 v162, v152
	v_add_f32_e32 v152, v153, v121
	v_mul_f32_e32 v151, v151, v164
	v_and_b32_e32 v164, 0xffff0000, v159
	v_mul_f32_e32 v152, 0xbfb8aa3b, v152
	v_exp_f32_e32 v153, v152
	v_mul_f32_e32 v152, 0xbfb8aa3b, v164
	v_exp_f32_e32 v152, v152
	v_pk_add_f32 v[158:159], v[162:163], 1.0 op_sel_hi:[1,0]
	v_cvt_pk_bf16_f32 v150, v151, v150
	v_lshlrev_b32_e32 v151, 16, v155
	v_mul_f32_e32 v158, v158, v159
	v_pk_add_f32 v[152:153], v[152:153], 1.0 op_sel_hi:[1,0]
	v_rcp_f32_e32 v158, v158
	v_mul_f32_e32 v152, v152, v153
	v_rcp_f32_e32 v152, v152
	v_add_f32_e32 v142, v142, v106
	v_mul_f32_e32 v153, v158, v154
	v_mul_f32_e32 v151, v153, v151
	v_and_b32_e32 v153, 0xffff0000, v155
	v_mul_f32_e32 v152, v152, v164
	v_lshlrev_b32_e32 v155, 16, v160
	v_mul_f32_e32 v142, 0xbfb8aa3b, v142
	v_mul_f32_e32 v152, v152, v153
	v_exp_f32_e32 v153, v142
	v_mul_f32_e32 v142, 0xbfb8aa3b, v155
	v_cvt_pk_bf16_f32 v151, v151, v152
	v_exp_f32_e32 v152, v142
	v_add_f32_e32 v142, v143, v107
	v_and_b32_e32 v158, 0xffff0000, v160
	v_mul_f32_e32 v142, 0xbfb8aa3b, v142
	v_exp_f32_e32 v143, v142
	v_mul_f32_e32 v142, 0xbfb8aa3b, v158
	v_exp_f32_e32 v142, v142
	v_pk_add_f32 v[152:153], v[152:153], 1.0 op_sel_hi:[1,0]
	v_lshlrev_b32_e32 v154, 16, v156
	v_mul_f32_e32 v152, v152, v153
	v_pk_add_f32 v[142:143], v[142:143], 1.0 op_sel_hi:[1,0]
	v_rcp_f32_e32 v152, v152
	v_mul_f32_e32 v142, v142, v143
	v_rcp_f32_e32 v142, v142
	v_add_f32_e32 v126, v126, v146
	v_mul_f32_e32 v143, v152, v155
	v_and_b32_e32 v152, 0xffff0000, v156
	v_mul_f32_e32 v142, v142, v158
	v_mul_f32_e32 v142, v142, v152
	v_mul_f32_e32 v143, v143, v154
	v_cvt_pk_bf16_f32 v152, v143, v142
	v_add_f32_e32 v142, v144, v108
	v_lshlrev_b32_e32 v154, 16, v161
	v_mul_f32_e32 v142, 0xbfb8aa3b, v142
	v_exp_f32_e32 v143, v142
	v_mul_f32_e32 v142, 0xbfb8aa3b, v154
	v_add_f32_e32 v144, v145, v109
	v_exp_f32_e32 v142, v142
	v_and_b32_e32 v155, 0xffff0000, v161
	v_mul_f32_e32 v144, 0xbfb8aa3b, v144
	v_exp_f32_e32 v145, v144
	v_mul_f32_e32 v144, 0xbfb8aa3b, v155
	v_exp_f32_e32 v144, v144
	v_pk_add_f32 v[142:143], v[142:143], 1.0 op_sel_hi:[1,0]
	v_lshlrev_b32_e32 v153, 16, v157
	v_mul_f32_e32 v142, v142, v143
	v_rcp_f32_e32 v156, v142
	v_pk_add_f32 v[142:143], v[144:145], 1.0 op_sel_hi:[1,0]
	v_and_b32_e32 v144, 0xffff0000, v157
	v_mul_f32_e32 v142, v142, v143
	v_rcp_f32_e32 v142, v142
	v_mul_f32_e32 v143, v156, v154
	v_lshlrev_b32_e32 v145, 16, v138
	v_mul_f32_e32 v126, 0xbfb8aa3b, v126
	v_mul_f32_e32 v142, v142, v155
	v_mul_f32_e32 v142, v142, v144
	v_mul_f32_e32 v143, v143, v153
	v_cvt_pk_bf16_f32 v153, v143, v142
	v_exp_f32_e32 v142, v126
	v_mul_f32_e32 v126, 0xbfb8aa3b, v145
	v_exp_f32_e32 v143, v126
	v_add_f32_e32 v126, v127, v147
	v_and_b32_e32 v138, 0xffff0000, v138
	v_mul_f32_e32 v126, 0xbfb8aa3b, v126
	v_mul_f32_e32 v127, 0xbfb8aa3b, v138
	v_exp_f32_e32 v126, v126
	v_exp_f32_e32 v127, v127
	v_pk_add_f32 v[142:143], v[142:143], 1.0 op_sel_hi:[1,0]
	v_lshlrev_b32_e32 v144, 16, v134
	v_mul_f32_e32 v142, v142, v143
	v_pk_add_f32 v[126:127], v[126:127], 1.0 op_sel_hi:[1,0]
	v_rcp_f32_e32 v142, v142
	v_mul_f32_e32 v126, v126, v127
	v_rcp_f32_e32 v126, v126
	v_and_b32_e32 v134, 0xffff0000, v134
	v_add_f32_e32 v128, v128, v148
	v_mul_f32_e32 v128, 0xbfb8aa3b, v128
	v_mul_f32_e32 v126, v126, v138
	v_mul_f32_e32 v126, v126, v134
	v_lshlrev_b32_e32 v134, 16, v139
	v_mul_f32_e32 v127, v142, v145
	v_exp_f32_e32 v142, v128
	v_mul_f32_e32 v128, 0xbfb8aa3b, v134
	v_mul_f32_e32 v127, v127, v144
	v_exp_f32_e32 v143, v128
	v_add_f32_e32 v128, v129, v149
	v_and_b32_e32 v144, 0xffff0000, v139
	v_mul_f32_e32 v128, 0xbfb8aa3b, v128
	v_mul_f32_e32 v129, 0xbfb8aa3b, v144
	v_exp_f32_e32 v128, v128
	v_exp_f32_e32 v129, v129
	v_pk_add_f32 v[138:139], v[142:143], 1.0 op_sel_hi:[1,0]
	v_cvt_pk_bf16_f32 v126, v127, v126
	v_lshlrev_b32_e32 v127, 16, v135
	v_mul_f32_e32 v138, v138, v139
	v_pk_add_f32 v[128:129], v[128:129], 1.0 op_sel_hi:[1,0]
	v_rcp_f32_e32 v138, v138
	v_mul_f32_e32 v128, v128, v129
	v_rcp_f32_e32 v128, v128
	v_add_f32_e32 v122, v122, v130
	v_mul_f32_e32 v129, v138, v134
	v_mul_f32_e32 v127, v129, v127
	v_and_b32_e32 v129, 0xffff0000, v135
	v_mul_f32_e32 v128, v128, v144
	v_mul_f32_e32 v128, v128, v129
	v_lshlrev_b32_e32 v130, 16, v140
	v_mul_f32_e32 v122, 0xbfb8aa3b, v122
	v_cvt_pk_bf16_f32 v127, v127, v128
	v_exp_f32_e32 v128, v122
	v_mul_f32_e32 v122, 0xbfb8aa3b, v130
	v_exp_f32_e32 v129, v122
	v_add_f32_e32 v122, v123, v131
	v_and_b32_e32 v131, 0xffff0000, v140
	v_mul_f32_e32 v122, 0xbfb8aa3b, v122
	v_mul_f32_e32 v123, 0xbfb8aa3b, v131
	v_exp_f32_e32 v122, v122
	v_exp_f32_e32 v123, v123
	v_pk_add_f32 v[128:129], v[128:129], 1.0 op_sel_hi:[1,0]
	v_lshlrev_b32_e32 v134, 16, v136
	v_mul_f32_e32 v128, v128, v129
	v_pk_add_f32 v[122:123], v[122:123], 1.0 op_sel_hi:[1,0]
	v_rcp_f32_e32 v128, v128
	v_mul_f32_e32 v122, v122, v123
	v_rcp_f32_e32 v122, v122
	v_lshlrev_b32_e32 v129, 16, v137
	v_mul_f32_e32 v123, v128, v130
	v_and_b32_e32 v128, 0xffff0000, v136
	v_mul_f32_e32 v122, v122, v131
	v_mul_f32_e32 v122, v122, v128
	v_mul_f32_e32 v123, v123, v134
	v_cvt_pk_bf16_f32 v128, v123, v122
	v_add_f32_e32 v122, v124, v132
	v_lshlrev_b32_e32 v130, 16, v141
	v_mul_f32_e32 v122, 0xbfb8aa3b, v122
	v_mul_f32_e32 v123, 0xbfb8aa3b, v130
	v_exp_f32_e32 v122, v122
	v_exp_f32_e32 v123, v123
	v_add_f32_e32 v124, v125, v133
	v_and_b32_e32 v131, 0xffff0000, v141
	v_mul_f32_e32 v124, 0xbfb8aa3b, v124
	v_mul_f32_e32 v125, 0xbfb8aa3b, v131
	v_exp_f32_e32 v124, v124
	v_exp_f32_e32 v125, v125
	v_pk_add_f32 v[122:123], v[122:123], 1.0 op_sel_hi:[1,0]
	v_add_f32_e32 v102, v102, v118
	v_mul_f32_e32 v122, v122, v123
	v_rcp_f32_e32 v132, v122
	v_pk_add_f32 v[122:123], v[124:125], 1.0 op_sel_hi:[1,0]
	v_and_b32_e32 v124, 0xffff0000, v137
	v_mul_f32_e32 v122, v122, v123
	v_rcp_f32_e32 v122, v122
	v_mul_f32_e32 v123, v132, v130
	v_mul_f32_e32 v123, v123, v129
	v_mul_f32_e32 v102, 0xbfb8aa3b, v102
	v_mul_f32_e32 v122, v122, v131
	v_mul_f32_e32 v122, v122, v124
	v_cvt_pk_bf16_f32 v129, v123, v122
	v_or_b32_e32 v122, 32, v170
	v_mad_i64_i32 v[122:123], s[28:29], v122, s40, v[172:173]
	v_lshl_add_u64 v[124:125], v[122:123], 0, s[26:27]
	global_store_dwordx4 v[180:181], v[126:129], off offset:2048
	v_add_f32_e32 v104, v104, v120
	v_mul_f32_e32 v104, 0xbfb8aa3b, v104
	v_lshl_add_u64 v[126:127], v[124:125], 0, v[174:175]
	v_lshlrev_b32_e32 v129, 16, v114
	global_load_dwordx4 v[138:141], v[126:127], off
	v_exp_f32_e32 v126, v102
	v_mul_f32_e32 v102, 0xbfb8aa3b, v129
	v_exp_f32_e32 v127, v102
	v_add_f32_e32 v102, v103, v119
	v_and_b32_e32 v114, 0xffff0000, v114
	v_mul_f32_e32 v102, 0xbfb8aa3b, v102
	v_mul_f32_e32 v103, 0xbfb8aa3b, v114
	v_exp_f32_e32 v102, v102
	v_exp_f32_e32 v103, v103
	v_pk_add_f32 v[118:119], v[126:127], 1.0 op_sel_hi:[1,0]
	v_lshlrev_b32_e32 v128, 16, v110
	v_mul_f32_e32 v118, v118, v119
	v_pk_add_f32 v[102:103], v[102:103], 1.0 op_sel_hi:[1,0]
	v_rcp_f32_e32 v118, v118
	v_mul_f32_e32 v102, v102, v103
	v_rcp_f32_e32 v102, v102
	v_and_b32_e32 v110, 0xffff0000, v110
	v_mul_f32_e32 v103, v118, v129
	v_exp_f32_e32 v118, v104
	v_mul_f32_e32 v102, v102, v114
	v_mul_f32_e32 v102, v102, v110
	v_lshlrev_b32_e32 v110, 16, v115
	v_mul_f32_e32 v104, 0xbfb8aa3b, v110
	v_exp_f32_e32 v119, v104
	v_add_f32_e32 v104, v105, v121
	v_and_b32_e32 v120, 0xffff0000, v115
	v_mul_f32_e32 v104, 0xbfb8aa3b, v104
	v_mul_f32_e32 v105, 0xbfb8aa3b, v120
	v_exp_f32_e32 v104, v104
	v_exp_f32_e32 v105, v105
	v_pk_add_f32 v[114:115], v[118:119], 1.0 op_sel_hi:[1,0]
	v_mul_f32_e32 v103, v103, v128
	v_mul_f32_e32 v114, v114, v115
	v_pk_add_f32 v[104:105], v[104:105], 1.0 op_sel_hi:[1,0]
	v_rcp_f32_e32 v114, v114
	v_mul_f32_e32 v104, v104, v105
	v_rcp_f32_e32 v104, v104
	v_cvt_pk_bf16_f32 v102, v103, v102
	v_lshlrev_b32_e32 v103, 16, v111
	v_mul_f32_e32 v105, v114, v110
	v_mul_f32_e32 v103, v105, v103
	v_and_b32_e32 v105, 0xffff0000, v111
	v_mul_f32_e32 v104, v104, v120
	v_add_f32_e32 v98, v98, v106
	v_mul_f32_e32 v104, v104, v105
	v_lshlrev_b32_e32 v106, 16, v116
	v_mul_f32_e32 v98, 0xbfb8aa3b, v98
	v_cvt_pk_bf16_f32 v103, v103, v104
	v_exp_f32_e32 v104, v98
	v_mul_f32_e32 v98, 0xbfb8aa3b, v106
	v_exp_f32_e32 v105, v98
	v_add_f32_e32 v98, v99, v107
	v_and_b32_e32 v107, 0xffff0000, v116
	v_mul_f32_e32 v98, 0xbfb8aa3b, v98
	v_mul_f32_e32 v99, 0xbfb8aa3b, v107
	v_exp_f32_e32 v98, v98
	v_exp_f32_e32 v99, v99
	v_pk_add_f32 v[104:105], v[104:105], 1.0 op_sel_hi:[1,0]
	v_lshlrev_b32_e32 v110, 16, v112
	v_mul_f32_e32 v104, v104, v105
	v_pk_add_f32 v[98:99], v[98:99], 1.0 op_sel_hi:[1,0]
	v_rcp_f32_e32 v104, v104
	v_mul_f32_e32 v98, v98, v99
	v_rcp_f32_e32 v98, v98
	v_lshlrev_b32_e32 v105, 16, v113
	v_mul_f32_e32 v99, v104, v106
	v_and_b32_e32 v104, 0xffff0000, v112
	v_mul_f32_e32 v98, v98, v107
	v_mul_f32_e32 v98, v98, v104
	v_mul_f32_e32 v99, v99, v110
	v_cvt_pk_bf16_f32 v104, v99, v98
	v_add_f32_e32 v98, v100, v108
	v_lshlrev_b32_e32 v106, 16, v117
	v_mul_f32_e32 v98, 0xbfb8aa3b, v98
	v_mul_f32_e32 v99, 0xbfb8aa3b, v106
	v_exp_f32_e32 v98, v98
	v_exp_f32_e32 v99, v99
	v_add_f32_e32 v100, v101, v109
	v_and_b32_e32 v107, 0xffff0000, v117
	v_mul_f32_e32 v100, 0xbfb8aa3b, v100
	v_mul_f32_e32 v101, 0xbfb8aa3b, v107
	v_exp_f32_e32 v100, v100
	v_exp_f32_e32 v101, v101
	v_pk_add_f32 v[98:99], v[98:99], 1.0 op_sel_hi:[1,0]
	global_store_dwordx4 v[182:183], v[166:169], off offset:2048
	v_mul_f32_e32 v98, v98, v99
	v_rcp_f32_e32 v108, v98
	v_pk_add_f32 v[98:99], v[100:101], 1.0 op_sel_hi:[1,0]
	v_and_b32_e32 v100, 0xffff0000, v113
	v_mul_f32_e32 v98, v98, v99
	v_rcp_f32_e32 v98, v98
	v_mul_f32_e32 v99, v108, v106
	global_store_dwordx4 v[182:183], v[150:153], off offset:2304
	v_mul_f32_e32 v99, v99, v105
	v_mul_f32_e32 v98, v98, v107
	v_mul_f32_e32 v98, v98, v100
	v_cvt_pk_bf16_f32 v105, v99, v98
	global_store_dwordx4 v[180:181], v[102:105], off offset:2304
	v_lshl_add_u64 v[144:145], v[122:123], 0, v[174:175]
	global_load_dwordx4 v[126:129], v[176:177], off
	global_load_dwordx4 v[146:149], v[144:145], off offset:2048
	global_load_dwordx4 v[118:121], v[176:177], off offset:16
	global_load_dwordx4 v[134:137], v[144:145], off offset:2304
	global_load_dwordx4 v[102:105], v[176:177], off offset:528
	global_load_dwordx4 v[110:113], v[176:177], off offset:512
	v_or_b32_e32 v100, 48, v170
	v_mad_i64_i32 v[100:101], s[28:29], v100, s40, v[172:173]
	v_lshl_add_u64 v[98:99], v[124:125], 0, v[178:179]
	v_lshl_add_u64 v[106:107], v[100:101], 0, s[26:27]
	v_lshl_add_u64 v[108:109], v[106:107], 0, v[174:175]
	global_load_dwordx4 v[130:133], v[98:99], off
	global_load_dwordx4 v[114:117], v[108:109], off
	s_waitcnt vmcnt(11)
	v_lshlrev_b32_e32 v152, 16, v138
	v_and_b32_e32 v138, 0xffff0000, v138
	v_lshl_add_u64 v[98:99], v[106:107], 0, v[178:179]
	v_lshl_add_u64 v[142:143], v[100:101], 0, v[174:175]
	global_load_dwordx4 v[98:101], v[98:99], off
	s_nop 0
	global_load_dwordx4 v[122:125], v[142:143], off offset:2048
	global_load_dwordx4 v[106:109], v[142:143], off offset:2304
	s_waitcnt vmcnt(10)
	v_add_f32_e32 v94, v94, v126
	s_waitcnt vmcnt(9)
	v_lshlrev_b32_e32 v153, 16, v146
	v_mul_f32_e32 v94, 0xbfb8aa3b, v94
	v_exp_f32_e32 v151, v94
	v_mul_f32_e32 v94, 0xbfb8aa3b, v153
	v_exp_f32_e32 v150, v94
	v_add_f32_e32 v94, v95, v127
	v_and_b32_e32 v146, 0xffff0000, v146
	v_mul_f32_e32 v94, 0xbfb8aa3b, v94
	v_exp_f32_e32 v95, v94
	v_mul_f32_e32 v94, 0xbfb8aa3b, v146
	v_exp_f32_e32 v94, v94
	v_pk_add_f32 v[150:151], v[150:151], 1.0 op_sel_hi:[1,0]
	v_add_f32_e32 v96, v96, v128
	v_mul_f32_e32 v150, v150, v151
	v_pk_add_f32 v[94:95], v[94:95], 1.0 op_sel_hi:[1,0]
	v_rcp_f32_e32 v150, v150
	v_mul_f32_e32 v94, v94, v95
	v_rcp_f32_e32 v94, v94
	v_mul_f32_e32 v96, 0xbfb8aa3b, v96
	v_exp_f32_e32 v151, v96
	v_mul_f32_e32 v95, v150, v153
	v_mul_f32_e32 v94, v94, v146
	v_mul_f32_e32 v94, v94, v138
	v_lshlrev_b32_e32 v138, 16, v147
	v_mul_f32_e32 v96, 0xbfb8aa3b, v138
	v_exp_f32_e32 v150, v96
	v_add_f32_e32 v96, v97, v129
	v_mul_f32_e32 v95, v95, v152
	v_and_b32_e32 v152, 0xffff0000, v147
	v_mul_f32_e32 v96, 0xbfb8aa3b, v96
	v_exp_f32_e32 v97, v96
	v_mul_f32_e32 v96, 0xbfb8aa3b, v152
	v_exp_f32_e32 v96, v96
	v_pk_add_f32 v[146:147], v[150:151], 1.0 op_sel_hi:[1,0]
	v_cvt_pk_bf16_f32 v94, v95, v94
	v_lshlrev_b32_e32 v95, 16, v139
	v_mul_f32_e32 v146, v146, v147
	v_pk_add_f32 v[96:97], v[96:97], 1.0 op_sel_hi:[1,0]
	v_rcp_f32_e32 v146, v146
	v_mul_f32_e32 v96, v96, v97
	v_rcp_f32_e32 v96, v96
	s_waitcnt vmcnt(8)
	v_add_f32_e32 v90, v90, v118
	v_mul_f32_e32 v97, v146, v138
	v_mul_f32_e32 v95, v97, v95
	v_and_b32_e32 v97, 0xffff0000, v139
	v_mul_f32_e32 v96, v96, v152
	v_lshlrev_b32_e32 v139, 16, v148
	v_mul_f32_e32 v90, 0xbfb8aa3b, v90
	v_mul_f32_e32 v96, v96, v97
	v_exp_f32_e32 v97, v90
	v_mul_f32_e32 v90, 0xbfb8aa3b, v139
	v_cvt_pk_bf16_f32 v95, v95, v96
	v_exp_f32_e32 v96, v90
	v_add_f32_e32 v90, v91, v119
	v_and_b32_e32 v146, 0xffff0000, v148
	v_mul_f32_e32 v90, 0xbfb8aa3b, v90
	v_exp_f32_e32 v91, v90
	v_mul_f32_e32 v90, 0xbfb8aa3b, v146
	v_exp_f32_e32 v90, v90
	v_pk_add_f32 v[96:97], v[96:97], 1.0 op_sel_hi:[1,0]
	v_lshlrev_b32_e32 v138, 16, v140
	v_mul_f32_e32 v96, v96, v97
	v_pk_add_f32 v[90:91], v[90:91], 1.0 op_sel_hi:[1,0]
	v_rcp_f32_e32 v96, v96
	v_mul_f32_e32 v90, v90, v91
	v_rcp_f32_e32 v90, v90
	v_lshlrev_b32_e32 v97, 16, v141
	v_mul_f32_e32 v91, v96, v139
	v_and_b32_e32 v96, 0xffff0000, v140
	v_mul_f32_e32 v90, v90, v146
	v_mul_f32_e32 v90, v90, v96
	v_mul_f32_e32 v91, v91, v138
	v_cvt_pk_bf16_f32 v96, v91, v90
	v_add_f32_e32 v90, v92, v120
	v_lshlrev_b32_e32 v138, 16, v149
	v_mul_f32_e32 v90, 0xbfb8aa3b, v90
	v_exp_f32_e32 v91, v90
	v_mul_f32_e32 v90, 0xbfb8aa3b, v138
	v_add_f32_e32 v92, v93, v121
	v_exp_f32_e32 v90, v90
	v_and_b32_e32 v139, 0xffff0000, v149
	v_mul_f32_e32 v92, 0xbfb8aa3b, v92
	v_exp_f32_e32 v93, v92
	v_mul_f32_e32 v92, 0xbfb8aa3b, v139
	v_exp_f32_e32 v92, v92
	v_pk_add_f32 v[90:91], v[90:91], 1.0 op_sel_hi:[1,0]
	s_waitcnt vmcnt(5)
	v_add_f32_e32 v86, v86, v110
	v_mul_f32_e32 v90, v90, v91
	v_rcp_f32_e32 v140, v90
	v_pk_add_f32 v[90:91], v[92:93], 1.0 op_sel_hi:[1,0]
	v_and_b32_e32 v92, 0xffff0000, v141
	v_mul_f32_e32 v90, v90, v91
	v_rcp_f32_e32 v90, v90
	v_mul_f32_e32 v91, v140, v138
	v_mul_f32_e32 v91, v91, v97
	v_lshlrev_b32_e32 v93, 16, v134
	v_mul_f32_e32 v90, v90, v139
	v_mul_f32_e32 v86, 0xbfb8aa3b, v86
	v_mul_f32_e32 v90, v90, v92
	v_cvt_pk_bf16_f32 v97, v91, v90
	v_exp_f32_e32 v91, v86
	v_mul_f32_e32 v86, 0xbfb8aa3b, v93
	v_exp_f32_e32 v90, v86
	v_add_f32_e32 v86, v87, v111
	global_store_dwordx4 v[144:145], v[94:97], off offset:2048
	v_mul_f32_e32 v86, 0xbfb8aa3b, v86
	v_exp_f32_e32 v87, v86
	v_and_b32_e32 v94, 0xffff0000, v134
	v_mul_f32_e32 v86, 0xbfb8aa3b, v94
	v_exp_f32_e32 v86, v86
	v_pk_add_f32 v[90:91], v[90:91], 1.0 op_sel_hi:[1,0]
	s_waitcnt vmcnt(5)
	v_lshlrev_b32_e32 v92, 16, v130
	v_mul_f32_e32 v90, v90, v91
	v_rcp_f32_e32 v90, v90
	v_pk_add_f32 v[86:87], v[86:87], 1.0 op_sel_hi:[1,0]
	v_add_f32_e32 v88, v88, v112
	v_mul_f32_e32 v86, v86, v87
	v_rcp_f32_e32 v86, v86
	v_mul_f32_e32 v87, v90, v93
	v_mul_f32_e32 v87, v87, v92
	v_lshlrev_b32_e32 v92, 16, v135
	v_mul_f32_e32 v88, 0xbfb8aa3b, v88
	v_and_b32_e32 v90, 0xffff0000, v130
	v_mul_f32_e32 v86, v86, v94
	v_exp_f32_e32 v91, v88
	v_mul_f32_e32 v88, 0xbfb8aa3b, v92
	v_mul_f32_e32 v86, v86, v90
	v_exp_f32_e32 v90, v88
	v_add_f32_e32 v88, v89, v113
	v_and_b32_e32 v93, 0xffff0000, v135
	v_mul_f32_e32 v88, 0xbfb8aa3b, v88
	v_exp_f32_e32 v89, v88
	v_mul_f32_e32 v88, 0xbfb8aa3b, v93
	v_exp_f32_e32 v88, v88
	v_pk_add_f32 v[90:91], v[90:91], 1.0 op_sel_hi:[1,0]
	v_cvt_pk_bf16_f32 v86, v87, v86
	v_lshlrev_b32_e32 v87, 16, v131
	v_mul_f32_e32 v90, v90, v91
	v_pk_add_f32 v[88:89], v[88:89], 1.0 op_sel_hi:[1,0]
	v_rcp_f32_e32 v90, v90
	v_mul_f32_e32 v88, v88, v89
	v_rcp_f32_e32 v88, v88
	v_add_f32_e32 v82, v82, v102
	v_mul_f32_e32 v89, v90, v92
	v_mul_f32_e32 v87, v89, v87
	v_and_b32_e32 v89, 0xffff0000, v131
	v_mul_f32_e32 v88, v88, v93
	v_lshlrev_b32_e32 v91, 16, v136
	v_mul_f32_e32 v82, 0xbfb8aa3b, v82
	v_mul_f32_e32 v88, v88, v89
	v_exp_f32_e32 v89, v82
	v_mul_f32_e32 v82, 0xbfb8aa3b, v91
	v_cvt_pk_bf16_f32 v87, v87, v88
	v_exp_f32_e32 v88, v82
	v_add_f32_e32 v82, v83, v103
	v_and_b32_e32 v92, 0xffff0000, v136
	v_mul_f32_e32 v82, 0xbfb8aa3b, v82
	v_exp_f32_e32 v83, v82
	v_mul_f32_e32 v82, 0xbfb8aa3b, v92
	v_exp_f32_e32 v82, v82
	v_pk_add_f32 v[88:89], v[88:89], 1.0 op_sel_hi:[1,0]
	v_lshlrev_b32_e32 v90, 16, v132
	v_mul_f32_e32 v88, v88, v89
	v_pk_add_f32 v[82:83], v[82:83], 1.0 op_sel_hi:[1,0]
	v_rcp_f32_e32 v88, v88
	v_mul_f32_e32 v82, v82, v83
	v_rcp_f32_e32 v82, v82
	v_add_f32_e32 v78, v78, v126
	v_mul_f32_e32 v83, v88, v91
	v_and_b32_e32 v88, 0xffff0000, v132
	v_mul_f32_e32 v82, v82, v92
	v_mul_f32_e32 v82, v82, v88
	v_mul_f32_e32 v83, v83, v90
	v_cvt_pk_bf16_f32 v88, v83, v82
	v_add_f32_e32 v82, v84, v104
	v_lshlrev_b32_e32 v90, 16, v137
	v_mul_f32_e32 v82, 0xbfb8aa3b, v82
	v_exp_f32_e32 v83, v82
	v_mul_f32_e32 v82, 0xbfb8aa3b, v90
	v_add_f32_e32 v84, v85, v105
	v_exp_f32_e32 v82, v82
	v_and_b32_e32 v91, 0xffff0000, v137
	v_mul_f32_e32 v84, 0xbfb8aa3b, v84
	v_exp_f32_e32 v85, v84
	v_mul_f32_e32 v84, 0xbfb8aa3b, v91
	v_exp_f32_e32 v84, v84
	v_pk_add_f32 v[82:83], v[82:83], 1.0 op_sel_hi:[1,0]
	v_lshlrev_b32_e32 v89, 16, v133
	v_mul_f32_e32 v82, v82, v83
	v_rcp_f32_e32 v92, v82
	v_pk_add_f32 v[82:83], v[84:85], 1.0 op_sel_hi:[1,0]
	v_and_b32_e32 v84, 0xffff0000, v133
	v_mul_f32_e32 v82, v82, v83
	v_rcp_f32_e32 v82, v82
	v_mul_f32_e32 v83, v92, v90
	s_waitcnt vmcnt(2)
	v_lshlrev_b32_e32 v85, 16, v122
	v_mul_f32_e32 v78, 0xbfb8aa3b, v78
	v_mul_f32_e32 v82, v82, v91
	v_mul_f32_e32 v82, v82, v84
	v_mul_f32_e32 v83, v83, v89
	v_cvt_pk_bf16_f32 v89, v83, v82
	v_exp_f32_e32 v82, v78
	v_mul_f32_e32 v78, 0xbfb8aa3b, v85
	global_store_dwordx4 v[144:145], v[86:89], off offset:2304
	v_exp_f32_e32 v83, v78
	v_add_f32_e32 v78, v79, v127
	v_and_b32_e32 v86, 0xffff0000, v122
	v_mul_f32_e32 v78, 0xbfb8aa3b, v78
	v_mul_f32_e32 v79, 0xbfb8aa3b, v86
	v_exp_f32_e32 v78, v78
	v_exp_f32_e32 v79, v79
	v_pk_add_f32 v[82:83], v[82:83], 1.0 op_sel_hi:[1,0]
	v_lshlrev_b32_e32 v84, 16, v114
	v_mul_f32_e32 v82, v82, v83
	v_pk_add_f32 v[78:79], v[78:79], 1.0 op_sel_hi:[1,0]
	v_rcp_f32_e32 v82, v82
	v_mul_f32_e32 v78, v78, v79
	v_rcp_f32_e32 v78, v78
	v_add_f32_e32 v80, v80, v128
	v_mul_f32_e32 v79, v82, v85
	v_mul_f32_e32 v79, v79, v84
	v_and_b32_e32 v82, 0xffff0000, v114
	v_mul_f32_e32 v78, v78, v86
	v_lshlrev_b32_e32 v84, 16, v123
	v_mul_f32_e32 v80, 0xbfb8aa3b, v80
	v_mul_f32_e32 v78, v78, v82
	v_exp_f32_e32 v82, v80
	v_mul_f32_e32 v80, 0xbfb8aa3b, v84
	v_exp_f32_e32 v83, v80
	v_add_f32_e32 v80, v81, v129
	v_and_b32_e32 v85, 0xffff0000, v123
	v_mul_f32_e32 v80, 0xbfb8aa3b, v80
	v_mul_f32_e32 v81, 0xbfb8aa3b, v85
	v_exp_f32_e32 v80, v80
	v_exp_f32_e32 v81, v81
	v_pk_add_f32 v[82:83], v[82:83], 1.0 op_sel_hi:[1,0]
	v_cvt_pk_bf16_f32 v78, v79, v78
	v_lshlrev_b32_e32 v79, 16, v115
	v_mul_f32_e32 v82, v82, v83
	v_pk_add_f32 v[80:81], v[80:81], 1.0 op_sel_hi:[1,0]
	v_rcp_f32_e32 v82, v82
	v_mul_f32_e32 v80, v80, v81
	v_rcp_f32_e32 v80, v80
	v_add_f32_e32 v74, v74, v118
	v_mul_f32_e32 v81, v82, v84
	v_mul_f32_e32 v79, v81, v79
	v_and_b32_e32 v81, 0xffff0000, v115
	v_mul_f32_e32 v80, v80, v85
	v_mul_f32_e32 v80, v80, v81
	v_lshlrev_b32_e32 v83, 16, v124
	v_mul_f32_e32 v74, 0xbfb8aa3b, v74
	v_cvt_pk_bf16_f32 v79, v79, v80
	v_exp_f32_e32 v80, v74
	v_mul_f32_e32 v74, 0xbfb8aa3b, v83
	v_exp_f32_e32 v81, v74
	v_add_f32_e32 v74, v75, v119
	v_and_b32_e32 v84, 0xffff0000, v124
	v_mul_f32_e32 v74, 0xbfb8aa3b, v74
	v_mul_f32_e32 v75, 0xbfb8aa3b, v84
	v_exp_f32_e32 v74, v74
	v_exp_f32_e32 v75, v75
	v_pk_add_f32 v[80:81], v[80:81], 1.0 op_sel_hi:[1,0]
	v_lshlrev_b32_e32 v82, 16, v116
	v_mul_f32_e32 v80, v80, v81
	v_pk_add_f32 v[74:75], v[74:75], 1.0 op_sel_hi:[1,0]
	v_rcp_f32_e32 v80, v80
	v_mul_f32_e32 v74, v74, v75
	v_rcp_f32_e32 v74, v74
	v_lshlrev_b32_e32 v81, 16, v117
	v_mul_f32_e32 v75, v80, v83
	v_and_b32_e32 v80, 0xffff0000, v116
	v_mul_f32_e32 v74, v74, v84
	v_mul_f32_e32 v74, v74, v80
	v_mul_f32_e32 v75, v75, v82
	v_cvt_pk_bf16_f32 v80, v75, v74
	v_add_f32_e32 v74, v76, v120
	v_lshlrev_b32_e32 v82, 16, v125
	v_mul_f32_e32 v74, 0xbfb8aa3b, v74
	v_mul_f32_e32 v75, 0xbfb8aa3b, v82
	v_exp_f32_e32 v74, v74
	v_exp_f32_e32 v75, v75
	v_add_f32_e32 v76, v77, v121
	v_and_b32_e32 v83, 0xffff0000, v125
	v_mul_f32_e32 v76, 0xbfb8aa3b, v76
	v_mul_f32_e32 v77, 0xbfb8aa3b, v83
	v_exp_f32_e32 v76, v76
	v_exp_f32_e32 v77, v77
	v_pk_add_f32 v[74:75], v[74:75], 1.0 op_sel_hi:[1,0]
	v_add_f32_e32 v70, v70, v110
	v_mul_f32_e32 v74, v74, v75
	v_rcp_f32_e32 v84, v74
	v_pk_add_f32 v[74:75], v[76:77], 1.0 op_sel_hi:[1,0]
	v_and_b32_e32 v76, 0xffff0000, v117
	v_mul_f32_e32 v74, v74, v75
	v_rcp_f32_e32 v74, v74
	v_mul_f32_e32 v75, v84, v82
	v_mul_f32_e32 v75, v75, v81
	v_mul_f32_e32 v70, 0xbfb8aa3b, v70
	v_mul_f32_e32 v74, v74, v83
	v_mul_f32_e32 v74, v74, v76
	v_cvt_pk_bf16_f32 v81, v75, v74
	v_add_u32_e32 v74, 0x80, v170
	v_mad_i64_i32 v[74:75], s[28:29], v74, s40, v[172:173]
	v_lshl_add_u64 v[76:77], v[74:75], 0, s[26:27]
	global_store_dwordx4 v[142:143], v[78:81], off offset:2048
	s_waitcnt vmcnt(3)
	v_and_b32_e32 v82, 0xffff0000, v106
	v_add_f32_e32 v72, v72, v112
	v_lshl_add_u64 v[78:79], v[76:77], 0, v[174:175]
	v_lshlrev_b32_e32 v81, 16, v106
	global_load_dwordx4 v[114:117], v[78:79], off
	v_exp_f32_e32 v78, v70
	v_mul_f32_e32 v70, 0xbfb8aa3b, v81
	v_exp_f32_e32 v79, v70
	v_add_f32_e32 v70, v71, v111
	v_mul_f32_e32 v70, 0xbfb8aa3b, v70
	v_mul_f32_e32 v71, 0xbfb8aa3b, v82
	v_exp_f32_e32 v70, v70
	v_exp_f32_e32 v71, v71
	v_pk_add_f32 v[78:79], v[78:79], 1.0 op_sel_hi:[1,0]
	v_lshlrev_b32_e32 v80, 16, v98
	v_mul_f32_e32 v78, v78, v79
	v_pk_add_f32 v[70:71], v[70:71], 1.0 op_sel_hi:[1,0]
	v_rcp_f32_e32 v78, v78
	v_mul_f32_e32 v70, v70, v71
	v_rcp_f32_e32 v70, v70
	v_mul_f32_e32 v72, 0xbfb8aa3b, v72
	v_mul_f32_e32 v71, v78, v81
	v_mul_f32_e32 v71, v71, v80
	v_and_b32_e32 v78, 0xffff0000, v98
	v_mul_f32_e32 v70, v70, v82
	v_lshlrev_b32_e32 v80, 16, v107
	v_mul_f32_e32 v70, v70, v78
	v_exp_f32_e32 v78, v72
	v_mul_f32_e32 v72, 0xbfb8aa3b, v80
	v_exp_f32_e32 v79, v72
	v_add_f32_e32 v72, v73, v113
	v_and_b32_e32 v81, 0xffff0000, v107
	v_mul_f32_e32 v72, 0xbfb8aa3b, v72
	v_mul_f32_e32 v73, 0xbfb8aa3b, v81
	v_exp_f32_e32 v72, v72
	v_exp_f32_e32 v73, v73
	v_pk_add_f32 v[78:79], v[78:79], 1.0 op_sel_hi:[1,0]
	v_cvt_pk_bf16_f32 v70, v71, v70
	v_lshlrev_b32_e32 v71, 16, v99
	v_mul_f32_e32 v78, v78, v79
	v_pk_add_f32 v[72:73], v[72:73], 1.0 op_sel_hi:[1,0]
	v_rcp_f32_e32 v78, v78
	v_mul_f32_e32 v72, v72, v73
	v_rcp_f32_e32 v72, v72
	v_add_f32_e32 v66, v66, v102
	v_mul_f32_e32 v73, v78, v80
	v_mul_f32_e32 v71, v73, v71
	v_and_b32_e32 v73, 0xffff0000, v99
	v_mul_f32_e32 v72, v72, v81
	v_mul_f32_e32 v72, v72, v73
	v_lshlrev_b32_e32 v79, 16, v108
	v_mul_f32_e32 v66, 0xbfb8aa3b, v66
	v_cvt_pk_bf16_f32 v71, v71, v72
	v_exp_f32_e32 v72, v66
	v_mul_f32_e32 v66, 0xbfb8aa3b, v79
	v_exp_f32_e32 v73, v66
	v_add_f32_e32 v66, v67, v103
	v_and_b32_e32 v80, 0xffff0000, v108
	v_mul_f32_e32 v66, 0xbfb8aa3b, v66
	v_mul_f32_e32 v67, 0xbfb8aa3b, v80
	v_exp_f32_e32 v66, v66
	v_exp_f32_e32 v67, v67
	v_pk_add_f32 v[72:73], v[72:73], 1.0 op_sel_hi:[1,0]
	v_lshlrev_b32_e32 v78, 16, v100
	v_mul_f32_e32 v72, v72, v73
	v_pk_add_f32 v[66:67], v[66:67], 1.0 op_sel_hi:[1,0]
	v_rcp_f32_e32 v72, v72
	v_mul_f32_e32 v66, v66, v67
	v_rcp_f32_e32 v66, v66
	v_lshlrev_b32_e32 v73, 16, v101
	v_mul_f32_e32 v67, v72, v79
	v_and_b32_e32 v72, 0xffff0000, v100
	v_mul_f32_e32 v66, v66, v80
	v_mul_f32_e32 v66, v66, v72
	v_mul_f32_e32 v67, v67, v78
	v_cvt_pk_bf16_f32 v72, v67, v66
	v_add_f32_e32 v66, v68, v104
	v_lshlrev_b32_e32 v78, 16, v109
	v_mul_f32_e32 v66, 0xbfb8aa3b, v66
	v_mul_f32_e32 v67, 0xbfb8aa3b, v78
	v_exp_f32_e32 v66, v66
	v_exp_f32_e32 v67, v67
	v_add_f32_e32 v68, v69, v105
	v_and_b32_e32 v79, 0xffff0000, v109
	v_mul_f32_e32 v68, 0xbfb8aa3b, v68
	v_mul_f32_e32 v69, 0xbfb8aa3b, v79
	v_exp_f32_e32 v68, v68
	v_exp_f32_e32 v69, v69
	v_pk_add_f32 v[66:67], v[66:67], 1.0 op_sel_hi:[1,0]
	v_lshl_add_u64 v[108:109], v[74:75], 0, v[174:175]
	v_mul_f32_e32 v66, v66, v67
	v_rcp_f32_e32 v80, v66
	v_pk_add_f32 v[66:67], v[68:69], 1.0 op_sel_hi:[1,0]
	v_and_b32_e32 v68, 0xffff0000, v101
	v_mul_f32_e32 v66, v66, v67
	v_rcp_f32_e32 v66, v66
	v_mul_f32_e32 v67, v80, v78
	v_mul_f32_e32 v67, v67, v73
	s_waitcnt vmcnt(0)
	v_lshlrev_b32_e32 v120, 16, v114
	v_mul_f32_e32 v66, v66, v79
	v_mul_f32_e32 v66, v66, v68
	v_cvt_pk_bf16_f32 v73, v67, v66
	global_store_dwordx4 v[142:143], v[70:73], off offset:2304
	global_load_dwordx4 v[94:97], v[176:177], off
	global_load_dwordx4 v[110:113], v[108:109], off offset:2048
	global_load_dwordx4 v[86:89], v[176:177], off offset:16
	global_load_dwordx4 v[102:105], v[108:109], off offset:2304
	s_nop 0
	global_load_dwordx4 v[70:73], v[176:177], off offset:528
	global_load_dwordx4 v[78:81], v[176:177], off offset:512
	v_add_u32_e32 v68, 0x90, v170
	v_mad_i64_i32 v[68:69], s[28:29], v68, s40, v[172:173]
	v_lshl_add_u64 v[66:67], v[76:77], 0, v[178:179]
	v_lshl_add_u64 v[74:75], v[68:69], 0, s[26:27]
	v_lshl_add_u64 v[76:77], v[74:75], 0, v[174:175]
	global_load_dwordx4 v[98:101], v[66:67], off
	global_load_dwordx4 v[82:85], v[76:77], off
	v_and_b32_e32 v114, 0xffff0000, v114
	v_lshl_add_u64 v[66:67], v[74:75], 0, v[178:179]
	v_lshl_add_u64 v[106:107], v[68:69], 0, v[174:175]
	global_load_dwordx4 v[66:69], v[66:67], off
	s_nop 0
	global_load_dwordx4 v[90:93], v[106:107], off offset:2048
	global_load_dwordx4 v[74:77], v[106:107], off offset:2304
	s_waitcnt vmcnt(10)
	v_add_f32_e32 v62, v62, v94
	s_waitcnt vmcnt(9)
	v_lshlrev_b32_e32 v121, 16, v110
	v_mul_f32_e32 v62, 0xbfb8aa3b, v62
	v_exp_f32_e32 v119, v62
	v_mul_f32_e32 v62, 0xbfb8aa3b, v121
	v_exp_f32_e32 v118, v62
	v_add_f32_e32 v62, v63, v95
	v_and_b32_e32 v110, 0xffff0000, v110
	v_mul_f32_e32 v62, 0xbfb8aa3b, v62
	v_exp_f32_e32 v63, v62
	v_mul_f32_e32 v62, 0xbfb8aa3b, v110
	v_exp_f32_e32 v62, v62
	v_pk_add_f32 v[118:119], v[118:119], 1.0 op_sel_hi:[1,0]
	v_add_f32_e32 v64, v64, v96
	v_mul_f32_e32 v118, v118, v119
	v_pk_add_f32 v[62:63], v[62:63], 1.0 op_sel_hi:[1,0]
	v_rcp_f32_e32 v118, v118
	v_mul_f32_e32 v62, v62, v63
	v_rcp_f32_e32 v62, v62
	v_mul_f32_e32 v64, 0xbfb8aa3b, v64
	v_exp_f32_e32 v119, v64
	v_mul_f32_e32 v63, v118, v121
	v_mul_f32_e32 v62, v62, v110
	v_mul_f32_e32 v62, v62, v114
	v_lshlrev_b32_e32 v114, 16, v111
	v_mul_f32_e32 v64, 0xbfb8aa3b, v114
	v_exp_f32_e32 v118, v64
	v_add_f32_e32 v64, v65, v97
	v_mul_f32_e32 v63, v63, v120
	v_and_b32_e32 v120, 0xffff0000, v111
	v_mul_f32_e32 v64, 0xbfb8aa3b, v64
	v_exp_f32_e32 v65, v64
	v_mul_f32_e32 v64, 0xbfb8aa3b, v120
	v_exp_f32_e32 v64, v64
	v_pk_add_f32 v[110:111], v[118:119], 1.0 op_sel_hi:[1,0]
	v_cvt_pk_bf16_f32 v62, v63, v62
	v_lshlrev_b32_e32 v63, 16, v115
	v_mul_f32_e32 v110, v110, v111
	v_pk_add_f32 v[64:65], v[64:65], 1.0 op_sel_hi:[1,0]
	v_rcp_f32_e32 v110, v110
	v_mul_f32_e32 v64, v64, v65
	v_rcp_f32_e32 v64, v64
	s_waitcnt vmcnt(8)
	v_add_f32_e32 v58, v58, v86
	v_mul_f32_e32 v65, v110, v114
	v_mul_f32_e32 v63, v65, v63
	v_and_b32_e32 v65, 0xffff0000, v115
	v_mul_f32_e32 v64, v64, v120
	v_lshlrev_b32_e32 v111, 16, v112
	v_mul_f32_e32 v58, 0xbfb8aa3b, v58
	v_mul_f32_e32 v64, v64, v65
	v_exp_f32_e32 v65, v58
	v_mul_f32_e32 v58, 0xbfb8aa3b, v111
	v_cvt_pk_bf16_f32 v63, v63, v64
	v_exp_f32_e32 v64, v58
	v_add_f32_e32 v58, v59, v87
	v_and_b32_e32 v112, 0xffff0000, v112
	v_mul_f32_e32 v58, 0xbfb8aa3b, v58
	v_exp_f32_e32 v59, v58
	v_mul_f32_e32 v58, 0xbfb8aa3b, v112
	v_exp_f32_e32 v58, v58
	v_pk_add_f32 v[64:65], v[64:65], 1.0 op_sel_hi:[1,0]
	v_lshlrev_b32_e32 v110, 16, v116
	v_mul_f32_e32 v64, v64, v65
	v_pk_add_f32 v[58:59], v[58:59], 1.0 op_sel_hi:[1,0]
	v_rcp_f32_e32 v64, v64
	v_mul_f32_e32 v58, v58, v59
	v_rcp_f32_e32 v58, v58
	v_lshlrev_b32_e32 v65, 16, v117
	v_mul_f32_e32 v59, v64, v111
	v_and_b32_e32 v64, 0xffff0000, v116
	v_mul_f32_e32 v58, v58, v112
	v_mul_f32_e32 v58, v58, v64
	v_mul_f32_e32 v59, v59, v110
	v_cvt_pk_bf16_f32 v64, v59, v58
	v_add_f32_e32 v58, v60, v88
	v_lshlrev_b32_e32 v110, 16, v113
	v_mul_f32_e32 v58, 0xbfb8aa3b, v58
	v_exp_f32_e32 v59, v58
	v_mul_f32_e32 v58, 0xbfb8aa3b, v110
	v_add_f32_e32 v60, v61, v89
	v_exp_f32_e32 v58, v58
	v_and_b32_e32 v111, 0xffff0000, v113
	v_mul_f32_e32 v60, 0xbfb8aa3b, v60
	v_exp_f32_e32 v61, v60
	v_mul_f32_e32 v60, 0xbfb8aa3b, v111
	v_exp_f32_e32 v60, v60
	v_pk_add_f32 v[58:59], v[58:59], 1.0 op_sel_hi:[1,0]
	s_waitcnt vmcnt(5)
	v_add_f32_e32 v54, v54, v78
	v_mul_f32_e32 v58, v58, v59
	v_rcp_f32_e32 v112, v58
	v_pk_add_f32 v[58:59], v[60:61], 1.0 op_sel_hi:[1,0]
	v_and_b32_e32 v60, 0xffff0000, v117
	v_mul_f32_e32 v58, v58, v59
	v_rcp_f32_e32 v58, v58
	v_mul_f32_e32 v59, v112, v110
	v_mul_f32_e32 v59, v59, v65
	v_lshlrev_b32_e32 v61, 16, v102
	v_mul_f32_e32 v58, v58, v111
	v_mul_f32_e32 v54, 0xbfb8aa3b, v54
	v_mul_f32_e32 v58, v58, v60
	v_cvt_pk_bf16_f32 v65, v59, v58
	v_exp_f32_e32 v59, v54
	v_mul_f32_e32 v54, 0xbfb8aa3b, v61
	v_exp_f32_e32 v58, v54
	v_add_f32_e32 v54, v55, v79
	global_store_dwordx4 v[108:109], v[62:65], off offset:2048
	v_mul_f32_e32 v54, 0xbfb8aa3b, v54
	v_exp_f32_e32 v55, v54
	v_and_b32_e32 v62, 0xffff0000, v102
	v_mul_f32_e32 v54, 0xbfb8aa3b, v62
	v_exp_f32_e32 v54, v54
	v_pk_add_f32 v[58:59], v[58:59], 1.0 op_sel_hi:[1,0]
	s_waitcnt vmcnt(5)
	v_lshlrev_b32_e32 v60, 16, v98
	v_mul_f32_e32 v58, v58, v59
	v_rcp_f32_e32 v58, v58
	v_pk_add_f32 v[54:55], v[54:55], 1.0 op_sel_hi:[1,0]
	v_add_f32_e32 v56, v56, v80
	v_mul_f32_e32 v54, v54, v55
	v_rcp_f32_e32 v54, v54
	v_mul_f32_e32 v55, v58, v61
	v_mul_f32_e32 v55, v55, v60
	v_lshlrev_b32_e32 v60, 16, v103
	v_mul_f32_e32 v56, 0xbfb8aa3b, v56
	v_and_b32_e32 v58, 0xffff0000, v98
	v_mul_f32_e32 v54, v54, v62
	v_exp_f32_e32 v59, v56
	v_mul_f32_e32 v56, 0xbfb8aa3b, v60
	v_mul_f32_e32 v54, v54, v58
	v_exp_f32_e32 v58, v56
	v_add_f32_e32 v56, v57, v81
	v_and_b32_e32 v61, 0xffff0000, v103
	v_mul_f32_e32 v56, 0xbfb8aa3b, v56
	v_exp_f32_e32 v57, v56
	v_mul_f32_e32 v56, 0xbfb8aa3b, v61
	v_exp_f32_e32 v56, v56
	v_pk_add_f32 v[58:59], v[58:59], 1.0 op_sel_hi:[1,0]
	v_cvt_pk_bf16_f32 v54, v55, v54
	v_lshlrev_b32_e32 v55, 16, v99
	v_mul_f32_e32 v58, v58, v59
	v_pk_add_f32 v[56:57], v[56:57], 1.0 op_sel_hi:[1,0]
	v_rcp_f32_e32 v58, v58
	v_mul_f32_e32 v56, v56, v57
	v_rcp_f32_e32 v56, v56
	v_add_f32_e32 v50, v50, v70
	v_mul_f32_e32 v57, v58, v60
	v_mul_f32_e32 v55, v57, v55
	v_and_b32_e32 v57, 0xffff0000, v99
	v_mul_f32_e32 v56, v56, v61
	v_lshlrev_b32_e32 v59, 16, v104
	v_mul_f32_e32 v50, 0xbfb8aa3b, v50
	v_mul_f32_e32 v56, v56, v57
	v_exp_f32_e32 v57, v50
	v_mul_f32_e32 v50, 0xbfb8aa3b, v59
	v_cvt_pk_bf16_f32 v55, v55, v56
	v_exp_f32_e32 v56, v50
	v_add_f32_e32 v50, v51, v71
	v_and_b32_e32 v60, 0xffff0000, v104
	v_mul_f32_e32 v50, 0xbfb8aa3b, v50
	v_exp_f32_e32 v51, v50
	v_mul_f32_e32 v50, 0xbfb8aa3b, v60
	v_exp_f32_e32 v50, v50
	v_pk_add_f32 v[56:57], v[56:57], 1.0 op_sel_hi:[1,0]
	v_lshlrev_b32_e32 v58, 16, v100
	v_mul_f32_e32 v56, v56, v57
	v_pk_add_f32 v[50:51], v[50:51], 1.0 op_sel_hi:[1,0]
	v_rcp_f32_e32 v56, v56
	v_mul_f32_e32 v50, v50, v51
	v_rcp_f32_e32 v50, v50
	v_add_f32_e32 v46, v46, v94
	v_mul_f32_e32 v51, v56, v59
	v_and_b32_e32 v56, 0xffff0000, v100
	v_mul_f32_e32 v50, v50, v60
	v_mul_f32_e32 v50, v50, v56
	v_mul_f32_e32 v51, v51, v58
	v_cvt_pk_bf16_f32 v56, v51, v50
	v_add_f32_e32 v50, v52, v72
	v_lshlrev_b32_e32 v58, 16, v105
	v_mul_f32_e32 v50, 0xbfb8aa3b, v50
	v_exp_f32_e32 v51, v50
	v_mul_f32_e32 v50, 0xbfb8aa3b, v58
	v_add_f32_e32 v52, v53, v73
	v_exp_f32_e32 v50, v50
	v_and_b32_e32 v59, 0xffff0000, v105
	v_mul_f32_e32 v52, 0xbfb8aa3b, v52
	v_exp_f32_e32 v53, v52
	v_mul_f32_e32 v52, 0xbfb8aa3b, v59
	v_exp_f32_e32 v52, v52
	v_pk_add_f32 v[50:51], v[50:51], 1.0 op_sel_hi:[1,0]
	v_lshlrev_b32_e32 v57, 16, v101
	v_mul_f32_e32 v50, v50, v51
	v_rcp_f32_e32 v60, v50
	v_pk_add_f32 v[50:51], v[52:53], 1.0 op_sel_hi:[1,0]
	v_and_b32_e32 v52, 0xffff0000, v101
	v_mul_f32_e32 v50, v50, v51
	v_rcp_f32_e32 v50, v50
	v_mul_f32_e32 v51, v60, v58
	s_waitcnt vmcnt(2)
	v_lshlrev_b32_e32 v53, 16, v90
	v_mul_f32_e32 v46, 0xbfb8aa3b, v46
	v_mul_f32_e32 v50, v50, v59
	v_mul_f32_e32 v50, v50, v52
	v_mul_f32_e32 v51, v51, v57
	v_cvt_pk_bf16_f32 v57, v51, v50
	v_exp_f32_e32 v50, v46
	v_mul_f32_e32 v46, 0xbfb8aa3b, v53
	global_store_dwordx4 v[108:109], v[54:57], off offset:2304
	v_exp_f32_e32 v51, v46
	v_add_f32_e32 v46, v47, v95
	v_and_b32_e32 v54, 0xffff0000, v90
	v_mul_f32_e32 v46, 0xbfb8aa3b, v46
	v_mul_f32_e32 v47, 0xbfb8aa3b, v54
	v_exp_f32_e32 v46, v46
	v_exp_f32_e32 v47, v47
	v_pk_add_f32 v[50:51], v[50:51], 1.0 op_sel_hi:[1,0]
	v_lshlrev_b32_e32 v52, 16, v82
	v_mul_f32_e32 v50, v50, v51
	v_pk_add_f32 v[46:47], v[46:47], 1.0 op_sel_hi:[1,0]
	v_rcp_f32_e32 v50, v50
	v_mul_f32_e32 v46, v46, v47
	v_rcp_f32_e32 v46, v46
	v_add_f32_e32 v48, v48, v96
	v_mul_f32_e32 v47, v50, v53
	v_mul_f32_e32 v47, v47, v52
	v_and_b32_e32 v50, 0xffff0000, v82
	v_mul_f32_e32 v46, v46, v54
	v_lshlrev_b32_e32 v52, 16, v91
	v_mul_f32_e32 v48, 0xbfb8aa3b, v48
	v_mul_f32_e32 v46, v46, v50
	v_exp_f32_e32 v50, v48
	v_mul_f32_e32 v48, 0xbfb8aa3b, v52
	v_exp_f32_e32 v51, v48
	v_add_f32_e32 v48, v49, v97
	v_and_b32_e32 v53, 0xffff0000, v91
	v_mul_f32_e32 v48, 0xbfb8aa3b, v48
	v_mul_f32_e32 v49, 0xbfb8aa3b, v53
	v_exp_f32_e32 v48, v48
	v_exp_f32_e32 v49, v49
	v_pk_add_f32 v[50:51], v[50:51], 1.0 op_sel_hi:[1,0]
	v_cvt_pk_bf16_f32 v46, v47, v46
	v_lshlrev_b32_e32 v47, 16, v83
	v_mul_f32_e32 v50, v50, v51
	v_pk_add_f32 v[48:49], v[48:49], 1.0 op_sel_hi:[1,0]
	v_rcp_f32_e32 v50, v50
	v_mul_f32_e32 v48, v48, v49
	v_rcp_f32_e32 v48, v48
	v_add_f32_e32 v42, v42, v86
	v_mul_f32_e32 v49, v50, v52
	v_mul_f32_e32 v47, v49, v47
	v_and_b32_e32 v49, 0xffff0000, v83
	v_mul_f32_e32 v48, v48, v53
	v_mul_f32_e32 v48, v48, v49
	v_lshlrev_b32_e32 v51, 16, v92
	v_mul_f32_e32 v42, 0xbfb8aa3b, v42
	v_cvt_pk_bf16_f32 v47, v47, v48
	v_exp_f32_e32 v48, v42
	v_mul_f32_e32 v42, 0xbfb8aa3b, v51
	v_exp_f32_e32 v49, v42
	v_add_f32_e32 v42, v43, v87
	v_and_b32_e32 v52, 0xffff0000, v92
	v_mul_f32_e32 v42, 0xbfb8aa3b, v42
	v_mul_f32_e32 v43, 0xbfb8aa3b, v52
	v_exp_f32_e32 v42, v42
	v_exp_f32_e32 v43, v43
	v_pk_add_f32 v[48:49], v[48:49], 1.0 op_sel_hi:[1,0]
	v_lshlrev_b32_e32 v50, 16, v84
	v_mul_f32_e32 v48, v48, v49
	v_pk_add_f32 v[42:43], v[42:43], 1.0 op_sel_hi:[1,0]
	v_rcp_f32_e32 v48, v48
	v_mul_f32_e32 v42, v42, v43
	v_rcp_f32_e32 v42, v42
	v_lshlrev_b32_e32 v49, 16, v85
	v_mul_f32_e32 v43, v48, v51
	v_and_b32_e32 v48, 0xffff0000, v84
	v_mul_f32_e32 v42, v42, v52
	v_mul_f32_e32 v42, v42, v48
	v_mul_f32_e32 v43, v43, v50
	v_cvt_pk_bf16_f32 v48, v43, v42
	v_add_f32_e32 v42, v44, v88
	v_lshlrev_b32_e32 v50, 16, v93
	v_mul_f32_e32 v42, 0xbfb8aa3b, v42
	v_mul_f32_e32 v43, 0xbfb8aa3b, v50
	v_exp_f32_e32 v42, v42
	v_exp_f32_e32 v43, v43
	v_add_f32_e32 v44, v45, v89
	v_and_b32_e32 v51, 0xffff0000, v93
	v_mul_f32_e32 v44, 0xbfb8aa3b, v44
	v_mul_f32_e32 v45, 0xbfb8aa3b, v51
	v_exp_f32_e32 v44, v44
	v_exp_f32_e32 v45, v45
	v_pk_add_f32 v[42:43], v[42:43], 1.0 op_sel_hi:[1,0]
	v_add_f32_e32 v38, v38, v78
	v_mul_f32_e32 v42, v42, v43
	v_rcp_f32_e32 v52, v42
	v_pk_add_f32 v[42:43], v[44:45], 1.0 op_sel_hi:[1,0]
	v_and_b32_e32 v44, 0xffff0000, v85
	v_mul_f32_e32 v42, v42, v43
	v_rcp_f32_e32 v42, v42
	v_mul_f32_e32 v43, v52, v50
	v_mul_f32_e32 v43, v43, v49
	v_mul_f32_e32 v38, 0xbfb8aa3b, v38
	v_mul_f32_e32 v42, v42, v51
	v_mul_f32_e32 v42, v42, v44
	v_cvt_pk_bf16_f32 v49, v43, v42
	v_add_u32_e32 v42, 0xa0, v170
	v_mad_i64_i32 v[42:43], s[28:29], v42, s40, v[172:173]
	v_lshl_add_u64 v[44:45], v[42:43], 0, s[26:27]
	global_store_dwordx4 v[106:107], v[46:49], off offset:2048
	s_waitcnt vmcnt(3)
	v_and_b32_e32 v50, 0xffff0000, v74
	v_add_f32_e32 v40, v40, v80
	v_lshl_add_u64 v[46:47], v[44:45], 0, v[174:175]
	v_lshlrev_b32_e32 v49, 16, v74
	global_load_dwordx4 v[82:85], v[46:47], off
	v_exp_f32_e32 v46, v38
	v_mul_f32_e32 v38, 0xbfb8aa3b, v49
	v_exp_f32_e32 v47, v38
	v_add_f32_e32 v38, v39, v79
	v_mul_f32_e32 v38, 0xbfb8aa3b, v38
	v_mul_f32_e32 v39, 0xbfb8aa3b, v50
	v_exp_f32_e32 v38, v38
	v_exp_f32_e32 v39, v39
	v_pk_add_f32 v[46:47], v[46:47], 1.0 op_sel_hi:[1,0]
	v_lshlrev_b32_e32 v48, 16, v66
	v_mul_f32_e32 v46, v46, v47
	v_pk_add_f32 v[38:39], v[38:39], 1.0 op_sel_hi:[1,0]
	v_rcp_f32_e32 v46, v46
	v_mul_f32_e32 v38, v38, v39
	v_rcp_f32_e32 v38, v38
	v_mul_f32_e32 v40, 0xbfb8aa3b, v40
	v_mul_f32_e32 v39, v46, v49
	v_mul_f32_e32 v39, v39, v48
	v_and_b32_e32 v46, 0xffff0000, v66
	v_mul_f32_e32 v38, v38, v50
	v_lshlrev_b32_e32 v48, 16, v75
	v_mul_f32_e32 v38, v38, v46
	v_exp_f32_e32 v46, v40
	v_mul_f32_e32 v40, 0xbfb8aa3b, v48
	v_exp_f32_e32 v47, v40
	v_add_f32_e32 v40, v41, v81
	v_and_b32_e32 v49, 0xffff0000, v75
	v_mul_f32_e32 v40, 0xbfb8aa3b, v40
	v_mul_f32_e32 v41, 0xbfb8aa3b, v49
	v_exp_f32_e32 v40, v40
	v_exp_f32_e32 v41, v41
	v_pk_add_f32 v[46:47], v[46:47], 1.0 op_sel_hi:[1,0]
	v_cvt_pk_bf16_f32 v38, v39, v38
	v_lshlrev_b32_e32 v39, 16, v67
	v_mul_f32_e32 v46, v46, v47
	v_pk_add_f32 v[40:41], v[40:41], 1.0 op_sel_hi:[1,0]
	v_rcp_f32_e32 v46, v46
	v_mul_f32_e32 v40, v40, v41
	v_rcp_f32_e32 v40, v40
	v_add_f32_e32 v34, v34, v70
	v_mul_f32_e32 v41, v46, v48
	v_mul_f32_e32 v39, v41, v39
	v_and_b32_e32 v41, 0xffff0000, v67
	v_mul_f32_e32 v40, v40, v49
	v_mul_f32_e32 v40, v40, v41
	v_lshlrev_b32_e32 v47, 16, v76
	v_mul_f32_e32 v34, 0xbfb8aa3b, v34
	v_cvt_pk_bf16_f32 v39, v39, v40
	v_exp_f32_e32 v40, v34
	v_mul_f32_e32 v34, 0xbfb8aa3b, v47
	v_exp_f32_e32 v41, v34
	v_add_f32_e32 v34, v35, v71
	v_and_b32_e32 v48, 0xffff0000, v76
	v_mul_f32_e32 v34, 0xbfb8aa3b, v34
	v_mul_f32_e32 v35, 0xbfb8aa3b, v48
	v_exp_f32_e32 v34, v34
	v_exp_f32_e32 v35, v35
	v_pk_add_f32 v[40:41], v[40:41], 1.0 op_sel_hi:[1,0]
	v_lshlrev_b32_e32 v46, 16, v68
	v_mul_f32_e32 v40, v40, v41
	v_pk_add_f32 v[34:35], v[34:35], 1.0 op_sel_hi:[1,0]
	v_rcp_f32_e32 v40, v40
	v_mul_f32_e32 v34, v34, v35
	v_rcp_f32_e32 v34, v34
	v_lshlrev_b32_e32 v41, 16, v69
	v_mul_f32_e32 v35, v40, v47
	v_and_b32_e32 v40, 0xffff0000, v68
	v_mul_f32_e32 v34, v34, v48
	v_mul_f32_e32 v34, v34, v40
	v_mul_f32_e32 v35, v35, v46
	v_cvt_pk_bf16_f32 v40, v35, v34
	v_add_f32_e32 v34, v36, v72
	v_lshlrev_b32_e32 v46, 16, v77
	v_mul_f32_e32 v34, 0xbfb8aa3b, v34
	v_mul_f32_e32 v35, 0xbfb8aa3b, v46
	v_exp_f32_e32 v34, v34
	v_exp_f32_e32 v35, v35
	v_add_f32_e32 v36, v37, v73
	v_and_b32_e32 v47, 0xffff0000, v77
	v_mul_f32_e32 v36, 0xbfb8aa3b, v36
	v_mul_f32_e32 v37, 0xbfb8aa3b, v47
	v_exp_f32_e32 v36, v36
	v_exp_f32_e32 v37, v37
	v_pk_add_f32 v[34:35], v[34:35], 1.0 op_sel_hi:[1,0]
	v_lshl_add_u64 v[76:77], v[42:43], 0, v[174:175]
	v_mul_f32_e32 v34, v34, v35
	v_rcp_f32_e32 v48, v34
	v_pk_add_f32 v[34:35], v[36:37], 1.0 op_sel_hi:[1,0]
	v_and_b32_e32 v36, 0xffff0000, v69
	v_mul_f32_e32 v34, v34, v35
	v_rcp_f32_e32 v34, v34
	v_mul_f32_e32 v35, v48, v46
	v_mul_f32_e32 v35, v35, v41
	s_waitcnt vmcnt(0)
	v_lshlrev_b32_e32 v88, 16, v82
	v_mul_f32_e32 v34, v34, v47
	v_mul_f32_e32 v34, v34, v36
	v_cvt_pk_bf16_f32 v41, v35, v34
	global_store_dwordx4 v[106:107], v[38:41], off offset:2304
	global_load_dwordx4 v[62:65], v[176:177], off
	global_load_dwordx4 v[78:81], v[76:77], off offset:2048
	global_load_dwordx4 v[54:57], v[176:177], off offset:16
	global_load_dwordx4 v[70:73], v[76:77], off offset:2304
	s_nop 0
	global_load_dwordx4 v[38:41], v[176:177], off offset:528
	global_load_dwordx4 v[46:49], v[176:177], off offset:512
	v_add_u32_e32 v36, 0xb0, v170
	v_mad_i64_i32 v[36:37], s[28:29], v36, s40, v[172:173]
	v_lshl_add_u64 v[34:35], v[44:45], 0, v[178:179]
	v_lshl_add_u64 v[42:43], v[36:37], 0, s[26:27]
	v_lshl_add_u64 v[44:45], v[42:43], 0, v[174:175]
	global_load_dwordx4 v[66:69], v[34:35], off
	global_load_dwordx4 v[50:53], v[44:45], off
	v_and_b32_e32 v82, 0xffff0000, v82
	v_lshl_add_u64 v[34:35], v[42:43], 0, v[178:179]
	v_lshl_add_u64 v[74:75], v[36:37], 0, v[174:175]
	global_load_dwordx4 v[34:37], v[34:35], off
	s_nop 0
	global_load_dwordx4 v[58:61], v[74:75], off offset:2048
	global_load_dwordx4 v[42:45], v[74:75], off offset:2304
	s_waitcnt vmcnt(10)
	v_add_f32_e32 v30, v30, v62
	s_waitcnt vmcnt(9)
	v_lshlrev_b32_e32 v89, 16, v78
	v_mul_f32_e32 v30, 0xbfb8aa3b, v30
	v_exp_f32_e32 v87, v30
	v_mul_f32_e32 v30, 0xbfb8aa3b, v89
	v_exp_f32_e32 v86, v30
	v_add_f32_e32 v30, v31, v63
	v_and_b32_e32 v78, 0xffff0000, v78
	v_mul_f32_e32 v30, 0xbfb8aa3b, v30
	v_exp_f32_e32 v31, v30
	v_mul_f32_e32 v30, 0xbfb8aa3b, v78
	v_exp_f32_e32 v30, v30
	v_pk_add_f32 v[86:87], v[86:87], 1.0 op_sel_hi:[1,0]
	v_add_f32_e32 v32, v32, v64
	v_mul_f32_e32 v86, v86, v87
	v_pk_add_f32 v[30:31], v[30:31], 1.0 op_sel_hi:[1,0]
	v_rcp_f32_e32 v86, v86
	v_mul_f32_e32 v30, v30, v31
	v_rcp_f32_e32 v30, v30
	v_mul_f32_e32 v32, 0xbfb8aa3b, v32
	v_exp_f32_e32 v87, v32
	v_mul_f32_e32 v31, v86, v89
	v_mul_f32_e32 v30, v30, v78
	v_mul_f32_e32 v30, v30, v82
	v_lshlrev_b32_e32 v82, 16, v79
	v_mul_f32_e32 v32, 0xbfb8aa3b, v82
	v_exp_f32_e32 v86, v32
	v_add_f32_e32 v32, v33, v65
	v_mul_f32_e32 v31, v31, v88
	v_and_b32_e32 v88, 0xffff0000, v79
	v_mul_f32_e32 v32, 0xbfb8aa3b, v32
	v_exp_f32_e32 v33, v32
	v_mul_f32_e32 v32, 0xbfb8aa3b, v88
	v_exp_f32_e32 v32, v32
	v_pk_add_f32 v[78:79], v[86:87], 1.0 op_sel_hi:[1,0]
	v_cvt_pk_bf16_f32 v30, v31, v30
	v_lshlrev_b32_e32 v31, 16, v83
	v_mul_f32_e32 v78, v78, v79
	v_pk_add_f32 v[32:33], v[32:33], 1.0 op_sel_hi:[1,0]
	v_rcp_f32_e32 v78, v78
	v_mul_f32_e32 v32, v32, v33
	v_rcp_f32_e32 v32, v32
	s_waitcnt vmcnt(8)
	v_add_f32_e32 v26, v26, v54
	v_mul_f32_e32 v33, v78, v82
	v_mul_f32_e32 v31, v33, v31
	v_and_b32_e32 v33, 0xffff0000, v83
	v_mul_f32_e32 v32, v32, v88
	v_lshlrev_b32_e32 v79, 16, v80
	v_mul_f32_e32 v26, 0xbfb8aa3b, v26
	v_mul_f32_e32 v32, v32, v33
	v_exp_f32_e32 v33, v26
	v_mul_f32_e32 v26, 0xbfb8aa3b, v79
	v_cvt_pk_bf16_f32 v31, v31, v32
	v_exp_f32_e32 v32, v26
	v_add_f32_e32 v26, v27, v55
	v_and_b32_e32 v80, 0xffff0000, v80
	v_mul_f32_e32 v26, 0xbfb8aa3b, v26
	v_exp_f32_e32 v27, v26
	v_mul_f32_e32 v26, 0xbfb8aa3b, v80
	v_exp_f32_e32 v26, v26
	v_pk_add_f32 v[32:33], v[32:33], 1.0 op_sel_hi:[1,0]
	v_lshlrev_b32_e32 v78, 16, v84
	v_mul_f32_e32 v32, v32, v33
	v_pk_add_f32 v[26:27], v[26:27], 1.0 op_sel_hi:[1,0]
	v_rcp_f32_e32 v32, v32
	v_mul_f32_e32 v26, v26, v27
	v_rcp_f32_e32 v26, v26
	v_lshlrev_b32_e32 v33, 16, v85
	v_mul_f32_e32 v27, v32, v79
	v_and_b32_e32 v32, 0xffff0000, v84
	v_mul_f32_e32 v26, v26, v80
	v_mul_f32_e32 v26, v26, v32
	v_mul_f32_e32 v27, v27, v78
	v_cvt_pk_bf16_f32 v32, v27, v26
	v_add_f32_e32 v26, v28, v56
	v_lshlrev_b32_e32 v78, 16, v81
	v_mul_f32_e32 v26, 0xbfb8aa3b, v26
	v_exp_f32_e32 v27, v26
	v_mul_f32_e32 v26, 0xbfb8aa3b, v78
	v_add_f32_e32 v28, v29, v57
	v_exp_f32_e32 v26, v26
	v_and_b32_e32 v79, 0xffff0000, v81
	v_mul_f32_e32 v28, 0xbfb8aa3b, v28
	v_exp_f32_e32 v29, v28
	v_mul_f32_e32 v28, 0xbfb8aa3b, v79
	v_exp_f32_e32 v28, v28
	v_pk_add_f32 v[26:27], v[26:27], 1.0 op_sel_hi:[1,0]
	s_waitcnt vmcnt(5)
	v_add_f32_e32 v22, v22, v46
	v_mul_f32_e32 v26, v26, v27
	v_rcp_f32_e32 v80, v26
	v_pk_add_f32 v[26:27], v[28:29], 1.0 op_sel_hi:[1,0]
	v_and_b32_e32 v28, 0xffff0000, v85
	v_mul_f32_e32 v26, v26, v27
	v_rcp_f32_e32 v26, v26
	v_mul_f32_e32 v27, v80, v78
	v_mul_f32_e32 v27, v27, v33
	v_lshlrev_b32_e32 v29, 16, v70
	v_mul_f32_e32 v26, v26, v79
	v_mul_f32_e32 v22, 0xbfb8aa3b, v22
	v_mul_f32_e32 v26, v26, v28
	v_cvt_pk_bf16_f32 v33, v27, v26
	v_exp_f32_e32 v27, v22
	v_mul_f32_e32 v22, 0xbfb8aa3b, v29
	v_exp_f32_e32 v26, v22
	v_add_f32_e32 v22, v23, v47
	global_store_dwordx4 v[76:77], v[30:33], off offset:2048
	v_mul_f32_e32 v22, 0xbfb8aa3b, v22
	v_exp_f32_e32 v23, v22
	v_and_b32_e32 v30, 0xffff0000, v70
	v_mul_f32_e32 v22, 0xbfb8aa3b, v30
	v_exp_f32_e32 v22, v22
	v_pk_add_f32 v[26:27], v[26:27], 1.0 op_sel_hi:[1,0]
	s_waitcnt vmcnt(5)
	v_lshlrev_b32_e32 v28, 16, v66
	v_mul_f32_e32 v26, v26, v27
	v_rcp_f32_e32 v26, v26
	v_pk_add_f32 v[22:23], v[22:23], 1.0 op_sel_hi:[1,0]
	v_add_f32_e32 v24, v24, v48
	v_mul_f32_e32 v22, v22, v23
	v_rcp_f32_e32 v22, v22
	v_mul_f32_e32 v23, v26, v29
	v_mul_f32_e32 v23, v23, v28
	v_lshlrev_b32_e32 v28, 16, v71
	v_mul_f32_e32 v24, 0xbfb8aa3b, v24
	v_and_b32_e32 v26, 0xffff0000, v66
	v_mul_f32_e32 v22, v22, v30
	v_exp_f32_e32 v27, v24
	v_mul_f32_e32 v24, 0xbfb8aa3b, v28
	v_mul_f32_e32 v22, v22, v26
	v_exp_f32_e32 v26, v24
	v_add_f32_e32 v24, v25, v49
	v_and_b32_e32 v29, 0xffff0000, v71
	v_mul_f32_e32 v24, 0xbfb8aa3b, v24
	v_exp_f32_e32 v25, v24
	v_mul_f32_e32 v24, 0xbfb8aa3b, v29
	v_exp_f32_e32 v24, v24
	v_pk_add_f32 v[26:27], v[26:27], 1.0 op_sel_hi:[1,0]
	v_cvt_pk_bf16_f32 v22, v23, v22
	v_lshlrev_b32_e32 v23, 16, v67
	v_mul_f32_e32 v26, v26, v27
	v_pk_add_f32 v[24:25], v[24:25], 1.0 op_sel_hi:[1,0]
	v_rcp_f32_e32 v26, v26
	v_mul_f32_e32 v24, v24, v25
	v_rcp_f32_e32 v24, v24
	v_add_f32_e32 v18, v18, v38
	v_mul_f32_e32 v25, v26, v28
	v_mul_f32_e32 v23, v25, v23
	v_and_b32_e32 v25, 0xffff0000, v67
	v_mul_f32_e32 v24, v24, v29
	v_lshlrev_b32_e32 v27, 16, v72
	v_mul_f32_e32 v18, 0xbfb8aa3b, v18
	v_mul_f32_e32 v24, v24, v25
	v_exp_f32_e32 v25, v18
	v_mul_f32_e32 v18, 0xbfb8aa3b, v27
	v_cvt_pk_bf16_f32 v23, v23, v24
	v_exp_f32_e32 v24, v18
	v_add_f32_e32 v18, v19, v39
	v_and_b32_e32 v28, 0xffff0000, v72
	v_mul_f32_e32 v18, 0xbfb8aa3b, v18
	v_exp_f32_e32 v19, v18
	v_mul_f32_e32 v18, 0xbfb8aa3b, v28
	v_exp_f32_e32 v18, v18
	v_pk_add_f32 v[24:25], v[24:25], 1.0 op_sel_hi:[1,0]
	v_lshlrev_b32_e32 v26, 16, v68
	v_mul_f32_e32 v24, v24, v25
	v_pk_add_f32 v[18:19], v[18:19], 1.0 op_sel_hi:[1,0]
	v_rcp_f32_e32 v24, v24
	v_mul_f32_e32 v18, v18, v19
	v_rcp_f32_e32 v18, v18
	v_add_f32_e32 v14, v14, v62
	v_mul_f32_e32 v19, v24, v27
	v_and_b32_e32 v24, 0xffff0000, v68
	v_mul_f32_e32 v18, v18, v28
	v_mul_f32_e32 v18, v18, v24
	v_mul_f32_e32 v19, v19, v26
	v_cvt_pk_bf16_f32 v24, v19, v18
	v_add_f32_e32 v18, v20, v40
	v_lshlrev_b32_e32 v26, 16, v73
	v_mul_f32_e32 v18, 0xbfb8aa3b, v18
	v_exp_f32_e32 v19, v18
	v_mul_f32_e32 v18, 0xbfb8aa3b, v26
	v_add_f32_e32 v20, v21, v41
	v_exp_f32_e32 v18, v18
	v_and_b32_e32 v27, 0xffff0000, v73
	v_mul_f32_e32 v20, 0xbfb8aa3b, v20
	v_exp_f32_e32 v21, v20
	v_mul_f32_e32 v20, 0xbfb8aa3b, v27
	v_exp_f32_e32 v20, v20
	v_pk_add_f32 v[18:19], v[18:19], 1.0 op_sel_hi:[1,0]
	v_lshlrev_b32_e32 v25, 16, v69
	v_mul_f32_e32 v18, v18, v19
	v_rcp_f32_e32 v28, v18
	v_pk_add_f32 v[18:19], v[20:21], 1.0 op_sel_hi:[1,0]
	v_and_b32_e32 v20, 0xffff0000, v69
	v_mul_f32_e32 v18, v18, v19
	v_rcp_f32_e32 v18, v18
	v_mul_f32_e32 v19, v28, v26
	s_waitcnt vmcnt(2)
	v_lshlrev_b32_e32 v21, 16, v58
	v_mul_f32_e32 v14, 0xbfb8aa3b, v14
	v_mul_f32_e32 v18, v18, v27
	v_mul_f32_e32 v18, v18, v20
	v_mul_f32_e32 v19, v19, v25
	v_cvt_pk_bf16_f32 v25, v19, v18
	v_exp_f32_e32 v18, v14
	v_mul_f32_e32 v14, 0xbfb8aa3b, v21
	global_store_dwordx4 v[76:77], v[22:25], off offset:2304
	v_exp_f32_e32 v19, v14
	v_add_f32_e32 v14, v15, v63
	v_and_b32_e32 v22, 0xffff0000, v58
	v_mul_f32_e32 v14, 0xbfb8aa3b, v14
	v_mul_f32_e32 v15, 0xbfb8aa3b, v22
	v_exp_f32_e32 v14, v14
	v_exp_f32_e32 v15, v15
	v_pk_add_f32 v[18:19], v[18:19], 1.0 op_sel_hi:[1,0]
	v_lshlrev_b32_e32 v20, 16, v50
	v_mul_f32_e32 v18, v18, v19
	v_pk_add_f32 v[14:15], v[14:15], 1.0 op_sel_hi:[1,0]
	v_rcp_f32_e32 v18, v18
	v_mul_f32_e32 v14, v14, v15
	v_rcp_f32_e32 v14, v14
	v_add_f32_e32 v16, v16, v64
	v_mul_f32_e32 v15, v18, v21
	v_mul_f32_e32 v15, v15, v20
	v_and_b32_e32 v18, 0xffff0000, v50
	v_mul_f32_e32 v14, v14, v22
	v_lshlrev_b32_e32 v20, 16, v59
	v_mul_f32_e32 v16, 0xbfb8aa3b, v16
	v_mul_f32_e32 v14, v14, v18
	v_exp_f32_e32 v18, v16
	v_mul_f32_e32 v16, 0xbfb8aa3b, v20
	v_exp_f32_e32 v19, v16
	v_add_f32_e32 v16, v17, v65
	v_and_b32_e32 v21, 0xffff0000, v59
	v_mul_f32_e32 v16, 0xbfb8aa3b, v16
	v_mul_f32_e32 v17, 0xbfb8aa3b, v21
	v_exp_f32_e32 v16, v16
	v_exp_f32_e32 v17, v17
	v_pk_add_f32 v[18:19], v[18:19], 1.0 op_sel_hi:[1,0]
	v_cvt_pk_bf16_f32 v14, v15, v14
	v_lshlrev_b32_e32 v15, 16, v51
	v_mul_f32_e32 v18, v18, v19
	v_pk_add_f32 v[16:17], v[16:17], 1.0 op_sel_hi:[1,0]
	v_rcp_f32_e32 v18, v18
	v_mul_f32_e32 v16, v16, v17
	v_rcp_f32_e32 v16, v16
	v_add_f32_e32 v10, v10, v54
	v_mul_f32_e32 v17, v18, v20
	v_mul_f32_e32 v15, v17, v15
	v_and_b32_e32 v17, 0xffff0000, v51
	v_mul_f32_e32 v16, v16, v21
	v_mul_f32_e32 v16, v16, v17
	v_lshlrev_b32_e32 v19, 16, v60
	v_mul_f32_e32 v10, 0xbfb8aa3b, v10
	v_cvt_pk_bf16_f32 v15, v15, v16
	v_exp_f32_e32 v16, v10
	v_mul_f32_e32 v10, 0xbfb8aa3b, v19
	v_exp_f32_e32 v17, v10
	v_add_f32_e32 v10, v11, v55
	v_and_b32_e32 v20, 0xffff0000, v60
	v_mul_f32_e32 v10, 0xbfb8aa3b, v10
	v_mul_f32_e32 v11, 0xbfb8aa3b, v20
	v_exp_f32_e32 v10, v10
	v_exp_f32_e32 v11, v11
	v_pk_add_f32 v[16:17], v[16:17], 1.0 op_sel_hi:[1,0]
	v_lshlrev_b32_e32 v18, 16, v52
	v_mul_f32_e32 v16, v16, v17
	v_pk_add_f32 v[10:11], v[10:11], 1.0 op_sel_hi:[1,0]
	v_rcp_f32_e32 v16, v16
	v_mul_f32_e32 v10, v10, v11
	v_rcp_f32_e32 v10, v10
	v_add_f32_e32 v6, v6, v46
	v_mul_f32_e32 v11, v16, v19
	v_and_b32_e32 v16, 0xffff0000, v52
	v_mul_f32_e32 v10, v10, v20
	v_mul_f32_e32 v10, v10, v16
	v_mul_f32_e32 v11, v11, v18
	v_cvt_pk_bf16_f32 v16, v11, v10
	v_add_f32_e32 v10, v12, v56
	v_lshlrev_b32_e32 v18, 16, v61
	v_mul_f32_e32 v10, 0xbfb8aa3b, v10
	v_mul_f32_e32 v11, 0xbfb8aa3b, v18
	v_exp_f32_e32 v10, v10
	v_exp_f32_e32 v11, v11
	v_add_f32_e32 v12, v13, v57
	v_and_b32_e32 v19, 0xffff0000, v61
	v_mul_f32_e32 v12, 0xbfb8aa3b, v12
	v_mul_f32_e32 v13, 0xbfb8aa3b, v19
	v_exp_f32_e32 v12, v12
	v_exp_f32_e32 v13, v13
	v_pk_add_f32 v[10:11], v[10:11], 1.0 op_sel_hi:[1,0]
	v_lshlrev_b32_e32 v17, 16, v53
	v_mul_f32_e32 v10, v10, v11
	v_rcp_f32_e32 v20, v10
	v_pk_add_f32 v[10:11], v[12:13], 1.0 op_sel_hi:[1,0]
	v_and_b32_e32 v12, 0xffff0000, v53
	v_mul_f32_e32 v10, v10, v11
	v_rcp_f32_e32 v10, v10
	v_mul_f32_e32 v11, v20, v18
	s_waitcnt vmcnt(2)
	v_lshlrev_b32_e32 v13, 16, v42
	v_mul_f32_e32 v6, 0xbfb8aa3b, v6
	v_mul_f32_e32 v10, v10, v19
	v_mul_f32_e32 v10, v10, v12
	v_mul_f32_e32 v11, v11, v17
	v_cvt_pk_bf16_f32 v17, v11, v10
	v_exp_f32_e32 v10, v6
	v_mul_f32_e32 v6, 0xbfb8aa3b, v13
	global_store_dwordx4 v[74:75], v[14:17], off offset:2048
	v_exp_f32_e32 v11, v6
	v_add_f32_e32 v6, v7, v47
	v_and_b32_e32 v14, 0xffff0000, v42
	v_mul_f32_e32 v6, 0xbfb8aa3b, v6
	v_mul_f32_e32 v7, 0xbfb8aa3b, v14
	v_exp_f32_e32 v6, v6
	v_exp_f32_e32 v7, v7
	v_pk_add_f32 v[10:11], v[10:11], 1.0 op_sel_hi:[1,0]
	v_lshlrev_b32_e32 v12, 16, v34
	v_mul_f32_e32 v10, v10, v11
	v_pk_add_f32 v[6:7], v[6:7], 1.0 op_sel_hi:[1,0]
	v_rcp_f32_e32 v10, v10
	v_mul_f32_e32 v6, v6, v7
	v_rcp_f32_e32 v6, v6
	v_add_f32_e32 v8, v8, v48
	v_mul_f32_e32 v7, v10, v13
	v_mul_f32_e32 v7, v7, v12
	v_and_b32_e32 v10, 0xffff0000, v34
	v_mul_f32_e32 v6, v6, v14
	v_lshlrev_b32_e32 v12, 16, v43
	v_mul_f32_e32 v8, 0xbfb8aa3b, v8
	v_mul_f32_e32 v6, v6, v10
	v_exp_f32_e32 v10, v8
	v_mul_f32_e32 v8, 0xbfb8aa3b, v12
	v_exp_f32_e32 v11, v8
	v_add_f32_e32 v8, v9, v49
	v_and_b32_e32 v13, 0xffff0000, v43
	v_mul_f32_e32 v8, 0xbfb8aa3b, v8
	v_mul_f32_e32 v9, 0xbfb8aa3b, v13
	v_exp_f32_e32 v8, v8
	v_exp_f32_e32 v9, v9
	v_pk_add_f32 v[10:11], v[10:11], 1.0 op_sel_hi:[1,0]
	v_cvt_pk_bf16_f32 v6, v7, v6
	v_lshlrev_b32_e32 v7, 16, v35
	v_mul_f32_e32 v10, v10, v11
	v_pk_add_f32 v[8:9], v[8:9], 1.0 op_sel_hi:[1,0]
	v_rcp_f32_e32 v10, v10
	v_mul_f32_e32 v8, v8, v9
	v_rcp_f32_e32 v8, v8
	v_add_f32_e32 v2, v2, v38
	v_mul_f32_e32 v9, v10, v12
	v_mul_f32_e32 v7, v9, v7
	v_and_b32_e32 v9, 0xffff0000, v35
	v_mul_f32_e32 v8, v8, v13
	v_mul_f32_e32 v8, v8, v9
	v_lshlrev_b32_e32 v11, 16, v44
	v_mul_f32_e32 v2, 0xbfb8aa3b, v2
	v_cvt_pk_bf16_f32 v7, v7, v8
	v_exp_f32_e32 v8, v2
	v_mul_f32_e32 v2, 0xbfb8aa3b, v11
	v_exp_f32_e32 v9, v2
	v_add_f32_e32 v2, v3, v39
	v_and_b32_e32 v12, 0xffff0000, v44
	v_mul_f32_e32 v2, 0xbfb8aa3b, v2
	v_mul_f32_e32 v3, 0xbfb8aa3b, v12
	v_exp_f32_e32 v2, v2
	v_exp_f32_e32 v3, v3
	v_pk_add_f32 v[8:9], v[8:9], 1.0 op_sel_hi:[1,0]
	v_lshlrev_b32_e32 v10, 16, v36
	v_mul_f32_e32 v8, v8, v9
	v_pk_add_f32 v[2:3], v[2:3], 1.0 op_sel_hi:[1,0]
	v_rcp_f32_e32 v8, v8
	v_mul_f32_e32 v2, v2, v3
	v_rcp_f32_e32 v2, v2
	v_lshlrev_b32_e32 v9, 16, v37
	v_mul_f32_e32 v3, v8, v11
	v_and_b32_e32 v8, 0xffff0000, v36
	v_mul_f32_e32 v2, v2, v12
	v_mul_f32_e32 v2, v2, v8
	v_mul_f32_e32 v3, v3, v10
	v_cvt_pk_bf16_f32 v8, v3, v2
	v_add_f32_e32 v2, v4, v40
	v_lshlrev_b32_e32 v10, 16, v45
	v_mul_f32_e32 v2, 0xbfb8aa3b, v2
	v_mul_f32_e32 v3, 0xbfb8aa3b, v10
	v_exp_f32_e32 v2, v2
	v_exp_f32_e32 v3, v3
	v_add_f32_e32 v4, v5, v41
	v_and_b32_e32 v11, 0xffff0000, v45
	v_mul_f32_e32 v4, 0xbfb8aa3b, v4
	v_mul_f32_e32 v5, 0xbfb8aa3b, v11
	v_exp_f32_e32 v4, v4
	v_exp_f32_e32 v5, v5
	v_pk_add_f32 v[2:3], v[2:3], 1.0 op_sel_hi:[1,0]
	s_nop 0
	v_mul_f32_e32 v2, v2, v3
	v_rcp_f32_e32 v12, v2
	v_pk_add_f32 v[2:3], v[4:5], 1.0 op_sel_hi:[1,0]
	v_and_b32_e32 v4, 0xffff0000, v37
	v_mul_f32_e32 v2, v2, v3
	v_rcp_f32_e32 v2, v2
	v_mul_f32_e32 v3, v12, v10
	v_mul_f32_e32 v3, v3, v9
	v_mul_f32_e32 v2, v2, v11
	v_mul_f32_e32 v2, v2, v4
	v_cvt_pk_bf16_f32 v9, v3, v2
	global_store_dwordx4 v[74:75], v[6:9], off offset:2304
	s_barrier
	s_cbranch_scc1 .LBB0_466

.LBB0_460:
	v_mov_b32_e32 v24, v0
	s_add_i32 s28, s31, s28
	v_ashrrev_i32_e32 v3, 31, v24
	v_lshrrev_b32_e32 v3, 26, v3
	v_add_u32_e32 v3, v24, v3
	v_ashrrev_i32_e32 v12, 6, v3
	v_bfe_i32 v3, v24, 27, 1
	v_lshlrev_b32_e32 v2, 4, v24
	v_lshrrev_b32_e32 v3, 22, v3
	v_add_u32_e32 v3, v2, v3
	v_and_b32_e32 v3, 0xfffffc00, v3
	v_sub_u32_e32 v3, v2, v3
	v_lshrrev_b32_e32 v4, 4, v3
	v_bitop3_b32 v4, v4, v3, 32 bitop3:0x6c
	v_ashrrev_i32_e32 v3, 31, v3
	v_lshrrev_b32_e32 v3, 26, v3
	v_lshlrev_b32_e32 v5, 3, v12
	v_add_u32_e32 v3, v4, v3
	v_and_b32_e32 v5, -16, v5
	s_waitcnt vmcnt(10)
	v_ashrrev_i32_e32 v19, 6, v3
	v_add_u32_e32 v3, v19, v5
	v_lshlrev_b32_e32 v5, 5, v12
	v_and_b32_e32 v20, 32, v5
	v_mul_i32_i24_e32 v5, 64, v19
	v_sub_u32_e32 v4, v4, v5
	v_ashrrev_i16_sdwa v4, v185, sext(v4) dst_sel:DWORD dst_unused:UNUSED_PAD src0_sel:DWORD src1_sel:BYTE_0
	v_lshlrev_b32_e32 v5, 1, v3
	v_bfe_i32 v13, v4, 0, 16
	v_and_b32_e32 v14, 0x1fffe0, v3
	v_and_b32_e32 v15, 24, v5
	v_lshrrev_b32_e32 v5, 2, v3
	v_and_b32_e32 v17, 3, v19
	s_ashr_i32 s29, s28, 31
	v_add_u32_e32 v4, v20, v13
	v_and_b32_e32 v16, 4, v5
	v_or_b32_e32 v5, v14, v17
	v_mul_lo_u32 v3, v3, s33
	s_lshr_b32 s29, s29, 27
	v_or3_b32 v5, v5, v15, v16
	v_add_lshl_u32 v130, v4, v3, 1
	v_lshlrev_b32_e32 v3, 1, v4
	v_add_u32_e32 v2, 0x2000, v2
	s_add_i32 s29, s28, s29
	v_lshl_add_u32 v170, v5, 11, v3
	v_ashrrev_i32_e32 v3, 31, v2
	s_and_b32 s30, s29, 0xffe0
	v_lshrrev_b32_e32 v3, 22, v3
	s_sub_i32 s28, s28, s30
	v_add_u32_e32 v3, v2, v3
	s_bfe_i32 s30, s28, 0x80000
	v_ashrrev_i32_e32 v18, 10, v3
	s_bfe_u32 s30, s30, 0x3000c
	v_mul_i32_i24_e32 v3, 0x400, v18
	s_add_i32 s30, s28, s30
	v_sub_u32_e32 v2, v2, v3
	s_bfe_i32 s31, s30, 0x80000
	s_and_b32 s30, s30, 0xf8
	v_lshrrev_b32_e32 v3, 4, v2
	s_sub_i32 s28, s28, s30
	v_bitop3_b32 v2, v3, v2, 32 bitop3:0x6c
	s_sext_i32_i16 s31, s31
	s_sext_i32_i8 s28, s28
	v_ashrrev_i32_e32 v4, 31, v2
	s_lshl_b32 s29, s29, 6
	s_lshl_b32 s43, s28, 8
	s_lshl_b32 s28, s31, 5
	v_lshrrev_b32_e32 v4, 26, v4
	s_and_b32 s29, s29, 0xfffff800
	s_and_b32 s28, s28, 0xffffff00
	v_readfirstlane_b32 s44, v24
	v_lshlrev_b32_e32 v3, 3, v18
	v_add_u32_e32 v4, v2, v4
	s_add_i32 s43, s43, s29
	v_and_b32_e32 v3, -16, v3
	s_waitcnt vmcnt(9)
	v_ashrrev_i32_e32 v27, 6, v4
	v_and_b32_e32 v4, 0xc0, v4
	s_ashr_i32 s51, s44, 6
	s_ashr_i32 s29, s28, 31
	s_ashr_i32 s45, s44, 8
	v_add_u32_e32 v3, v27, v3
	v_sub_u32_e32 v2, v2, v4
	s_lshl_b32 s46, s51, 10
	s_lshl_b64 s[34:35], s[28:29], 11
	v_lshlrev_b32_e32 v5, 5, v18
	v_ashrrev_i16_sdwa v2, v185, sext(v2) dst_sel:DWORD dst_unused:UNUSED_PAD src0_sel:DWORD src1_sel:BYTE_0
	v_lshlrev_b32_e32 v4, 1, v3
	s_add_u32 s38, s4, s34
	v_and_b32_e32 v28, 32, v5
	v_bfe_i32 v21, v2, 0, 16
	v_and_b32_e32 v22, 0x1fffe0, v3
	v_and_b32_e32 v23, 24, v4
	v_lshrrev_b32_e32 v4, 2, v3
	v_and_b32_e32 v26, 3, v27
	s_addc_u32 s39, s5, s35
	s_add_i32 s47, s46, 0
	v_add_u32_e32 v2, v28, v21
	v_and_b32_e32 v25, 4, v4
	v_or_b32_e32 v4, v22, v26
	v_mul_lo_u32 v3, v3, s33
	s_add_i32 m0, s47, 0x10000
	v_or3_b32 v4, v4, v23, v25
	v_add_lshl_u32 v132, v2, v3, 1
	v_lshlrev_b32_e32 v2, 1, v2
	s_mul_i32 s36, s43, 0x2400
	global_load_lds_dwordx4 v170, s[38:39]
	s_add_i32 m0, s47, 0x12000
	v_lshl_add_u32 v2, v4, 11, v2
	s_mul_hi_i32 s37, s43, 0x2400
	s_add_u32 s30, s2, s36
	global_load_lds_dwordx4 v2, s[38:39]
	s_addc_u32 s31, s3, s37
	s_mov_b32 m0, s47
	s_add_i32 s48, s47, 0x2000
	global_load_lds_dwordx4 v130, s[30:31]
	s_mov_b32 m0, s48
	s_add_u32 s52, s38, 0x40000
	global_load_lds_dwordx4 v132, s[30:31]
	s_addc_u32 s53, s39, 0
	s_add_i32 m0, s47, 0x14000
	v_mov_b32_e32 v3, v171
	global_load_lds_dwordx4 v170, s[52:53]
	s_add_i32 m0, s47, 0x16000
	v_mov_b32_e32 v131, v171
	global_load_lds_dwordx4 v2, s[52:53]
	s_add_u32 s52, s30, 0x120000
	s_addc_u32 s53, s31, 0
	s_add_i32 s49, s47, 0x4000
	s_mov_b32 m0, s49
	s_add_i32 s50, s47, 0x6000
	global_load_lds_dwordx4 v130, s[52:53]
	s_mov_b32 m0, s50
	v_mov_b32_e32 v133, v171
	global_load_lds_dwordx4 v132, s[52:53]
	v_lshl_add_u64 v[10:11], s[38:39], 0, v[170:171]
	v_lshl_add_u64 v[8:9], s[38:39], 0, v[2:3]
	v_lshl_add_u64 v[6:7], s[30:31], 0, v[130:131]
	s_cmp_lg_u32 s45, 1
	v_lshl_add_u64 v[4:5], s[30:31], 0, v[132:133]
	s_cbranch_scc1 .LBB0_462
	s_setprio 1
	s_barrier

.LBB0_463:
	s_add_i32 s39, 0, 0x10000
	v_add_u32_e32 v143, s39, v142
	ds_read_b128 v[150:153], v143
	ds_read_b128 v[154:157], v143 offset:1024
	ds_read_b128 v[158:161], v143 offset:2048
	ds_read_b128 v[162:165], v143 offset:3072
	v_lshl_add_u64 v[144:145], s[34:35], 0, v[134:135]
	s_add_i32 s38, s47, 0xc000
	v_lshl_add_u64 v[202:203], v[144:145], 0, s[10:11]
	s_mov_b32 m0, s38
	v_lshl_add_u64 v[218:219], s[34:35], 0, v[136:137]
	s_add_i32 s37, s47, 0xe000
	ds_read_b128 v[166:169], v148
	ds_read_b128 v[172:175], v148 offset:1024
	ds_read_b128 v[176:179], v148 offset:2048
	ds_read_b128 v[180:183], v148 offset:3072
	ds_read_b128 v[186:189], v148 offset:4096
	ds_read_b128 v[190:193], v148 offset:5120
	ds_read_b128 v[194:197], v148 offset:6144
	ds_read_b128 v[198:201], v148 offset:7168
	global_load_lds_dwordx4 v[202:203], off
	v_lshl_add_u64 v[202:203], v[218:219], 0, s[10:11]
	s_mov_b32 m0, s37
	s_nop 0
	global_load_lds_dwordx4 v[202:203], off
	s_waitcnt lgkmcnt(8)
	s_barrier
	s_waitcnt lgkmcnt(0)
	s_waitcnt lgkmcnt(0)
	v_mfma_f32_16x16x32_bf16 v[126:129], v[150:153], v[166:169], v[126:129]
	v_mfma_f32_16x16x32_bf16 v[122:125], v[158:161], v[166:169], v[122:125]
	v_mfma_f32_16x16x32_bf16 v[118:121], v[150:153], v[176:179], v[118:121]
	v_mfma_f32_16x16x32_bf16 v[114:117], v[158:161], v[176:179], v[114:117]
	v_mfma_f32_16x16x32_bf16 v[110:113], v[150:153], v[186:189], v[110:113]
	v_mfma_f32_16x16x32_bf16 v[106:109], v[158:161], v[186:189], v[106:109]
	v_mfma_f32_16x16x32_bf16 v[102:105], v[150:153], v[194:197], v[102:105]
	v_mfma_f32_16x16x32_bf16 v[98:101], v[158:161], v[194:197], v[98:101]
	v_mfma_f32_16x16x32_bf16 v[126:129], v[154:157], v[172:175], v[126:129]
	v_mfma_f32_16x16x32_bf16 v[122:125], v[162:165], v[172:175], v[122:125]
	v_mfma_f32_16x16x32_bf16 v[118:121], v[154:157], v[180:183], v[118:121]
	v_mfma_f32_16x16x32_bf16 v[114:117], v[162:165], v[180:183], v[114:117]
	v_mfma_f32_16x16x32_bf16 v[110:113], v[154:157], v[190:193], v[110:113]
	v_mfma_f32_16x16x32_bf16 v[106:109], v[162:165], v[190:193], v[106:109]
	v_mfma_f32_16x16x32_bf16 v[102:105], v[154:157], v[198:201], v[102:105]
	v_mfma_f32_16x16x32_bf16 v[98:101], v[162:165], v[198:201], v[98:101]
	s_barrier
	s_add_i32 s53, 0, 0x14000
	v_lshl_add_u64 v[220:221], s[34:35], 0, v[138:139]
	s_add_i32 s39, s39, s46
	v_add_u32_e32 v143, s53, v142
	v_lshl_add_u64 v[222:223], v[220:221], 0, s[12:13]
	s_mov_b32 m0, s39
	ds_read_b128 v[202:205], v143
	ds_read_b128 v[206:209], v143 offset:1024
	ds_read_b128 v[210:213], v143 offset:2048
	ds_read_b128 v[214:217], v143 offset:3072
	global_load_lds_dwordx4 v[222:223], off
	v_lshl_add_u64 v[222:223], s[34:35], 0, v[140:141]
	v_lshl_add_u64 v[224:225], v[222:223], 0, s[12:13]
	s_add_i32 m0, s39, 0x2000
	s_nop 0
	global_load_lds_dwordx4 v[224:225], off
	s_barrier
	s_waitcnt lgkmcnt(0)
	s_waitcnt lgkmcnt(0)
	v_mfma_f32_16x16x32_bf16 v[94:97], v[202:205], v[166:169], v[94:97]
	v_mfma_f32_16x16x32_bf16 v[90:93], v[210:213], v[166:169], v[90:93]
	v_mfma_f32_16x16x32_bf16 v[86:89], v[202:205], v[176:179], v[86:89]
	v_mfma_f32_16x16x32_bf16 v[82:85], v[210:213], v[176:179], v[82:85]
	v_mfma_f32_16x16x32_bf16 v[78:81], v[202:205], v[186:189], v[78:81]
	v_mfma_f32_16x16x32_bf16 v[74:77], v[210:213], v[186:189], v[74:77]
	v_mfma_f32_16x16x32_bf16 v[70:73], v[202:205], v[194:197], v[70:73]
	v_mfma_f32_16x16x32_bf16 v[66:69], v[210:213], v[194:197], v[66:69]
	v_mfma_f32_16x16x32_bf16 v[94:97], v[206:209], v[172:175], v[94:97]
	v_mfma_f32_16x16x32_bf16 v[90:93], v[214:217], v[172:175], v[90:93]
	v_mfma_f32_16x16x32_bf16 v[86:89], v[206:209], v[180:183], v[86:89]
	v_mfma_f32_16x16x32_bf16 v[82:85], v[214:217], v[180:183], v[82:85]
	v_mfma_f32_16x16x32_bf16 v[78:81], v[206:209], v[190:193], v[78:81]
	v_mfma_f32_16x16x32_bf16 v[74:77], v[214:217], v[190:193], v[74:77]
	v_mfma_f32_16x16x32_bf16 v[70:73], v[206:209], v[198:201], v[70:73]
	v_mfma_f32_16x16x32_bf16 v[66:69], v[214:217], v[198:201], v[66:69]
	s_mov_b32 m0, s47
	v_lshl_add_u64 v[224:225], v[144:145], 0, s[14:15]
	s_barrier
	ds_read_b128 v[166:169], v148 offset:16384
	ds_read_b128 v[172:175], v148 offset:17408
	ds_read_b128 v[176:179], v148 offset:18432
	ds_read_b128 v[180:183], v148 offset:19456
	ds_read_b128 v[186:189], v148 offset:20480
	ds_read_b128 v[190:193], v148 offset:21504
	ds_read_b128 v[194:197], v148 offset:22528
	ds_read_b128 v[198:201], v148 offset:23552
	global_load_lds_dwordx4 v[224:225], off
	v_lshl_add_u64 v[224:225], v[218:219], 0, s[14:15]
	s_mov_b32 m0, s48
	s_nop 0
	global_load_lds_dwordx4 v[224:225], off
	s_barrier
	s_waitcnt lgkmcnt(0)
	s_waitcnt lgkmcnt(0)
	v_mfma_f32_16x16x32_bf16 v[62:65], v[150:153], v[166:169], v[62:65]
	v_mfma_f32_16x16x32_bf16 v[58:61], v[158:161], v[166:169], v[58:61]
	v_mfma_f32_16x16x32_bf16 v[54:57], v[150:153], v[176:179], v[54:57]
	v_mfma_f32_16x16x32_bf16 v[50:53], v[158:161], v[176:179], v[50:53]
	v_mfma_f32_16x16x32_bf16 v[46:49], v[150:153], v[186:189], v[46:49]
	v_mfma_f32_16x16x32_bf16 v[42:45], v[158:161], v[186:189], v[42:45]
	v_mfma_f32_16x16x32_bf16 v[38:41], v[150:153], v[194:197], v[38:41]
	v_mfma_f32_16x16x32_bf16 v[34:37], v[158:161], v[194:197], v[34:37]
	v_mfma_f32_16x16x32_bf16 v[62:65], v[154:157], v[172:175], v[62:65]
	v_mfma_f32_16x16x32_bf16 v[58:61], v[162:165], v[172:175], v[58:61]
	v_mfma_f32_16x16x32_bf16 v[54:57], v[154:157], v[180:183], v[54:57]
	v_mfma_f32_16x16x32_bf16 v[50:53], v[162:165], v[180:183], v[50:53]
	v_mfma_f32_16x16x32_bf16 v[46:49], v[154:157], v[190:193], v[46:49]
	v_mfma_f32_16x16x32_bf16 v[42:45], v[162:165], v[190:193], v[42:45]
	v_mfma_f32_16x16x32_bf16 v[38:41], v[154:157], v[198:201], v[38:41]
	v_mfma_f32_16x16x32_bf16 v[34:37], v[162:165], v[198:201], v[34:37]
	s_barrier
	s_add_i32 s39, s53, s46
	v_lshl_add_u64 v[150:151], v[220:221], 0, s[16:17]
	s_mov_b32 m0, s39
	s_nop 0
	global_load_lds_dwordx4 v[150:151], off
	v_lshl_add_u64 v[150:151], v[222:223], 0, s[16:17]
	s_add_i32 m0, s39, 0x2000
	s_nop 0
	global_load_lds_dwordx4 v[150:151], off
	s_waitcnt vmcnt(6)
	s_barrier
	v_mfma_f32_16x16x32_bf16 v[30:33], v[202:205], v[166:169], v[30:33]
	v_mfma_f32_16x16x32_bf16 v[26:29], v[210:213], v[166:169], v[26:29]
	v_mfma_f32_16x16x32_bf16 v[22:25], v[202:205], v[176:179], v[22:25]
	v_mfma_f32_16x16x32_bf16 v[18:21], v[210:213], v[176:179], v[18:21]
	v_mfma_f32_16x16x32_bf16 v[14:17], v[202:205], v[186:189], v[14:17]
	v_mfma_f32_16x16x32_bf16 v[10:13], v[210:213], v[186:189], v[10:13]
	v_mfma_f32_16x16x32_bf16 v[6:9], v[202:205], v[194:197], v[6:9]
	v_mfma_f32_16x16x32_bf16 v[2:5], v[210:213], v[194:197], v[2:5]
	v_mfma_f32_16x16x32_bf16 v[30:33], v[206:209], v[172:175], v[30:33]
	v_mfma_f32_16x16x32_bf16 v[26:29], v[214:217], v[172:175], v[26:29]
	v_mfma_f32_16x16x32_bf16 v[22:25], v[206:209], v[180:183], v[22:25]
	v_mfma_f32_16x16x32_bf16 v[18:21], v[214:217], v[180:183], v[18:21]
	v_mfma_f32_16x16x32_bf16 v[14:17], v[206:209], v[190:193], v[14:17]
	v_mfma_f32_16x16x32_bf16 v[10:13], v[214:217], v[190:193], v[10:13]
	v_mfma_f32_16x16x32_bf16 v[6:9], v[206:209], v[198:201], v[6:9]
	v_mfma_f32_16x16x32_bf16 v[2:5], v[214:217], v[198:201], v[2:5]
	s_add_i32 s39, 0, 0x18000
	v_add_u32_e32 v143, s39, v142
	s_barrier
	ds_read_b128 v[150:153], v143
	ds_read_b128 v[154:157], v143 offset:1024
	ds_read_b128 v[158:161], v143 offset:2048
	ds_read_b128 v[162:165], v143 offset:3072
	s_mov_b32 m0, s49
	v_lshl_add_u64 v[202:203], v[144:145], 0, s[18:19]
	ds_read_b128 v[166:169], v148 offset:32768
	ds_read_b128 v[172:175], v148 offset:33792
	ds_read_b128 v[176:179], v148 offset:34816
	ds_read_b128 v[180:183], v148 offset:35840
	ds_read_b128 v[186:189], v148 offset:36864
	ds_read_b128 v[190:193], v148 offset:37888
	ds_read_b128 v[194:197], v148 offset:38912
	ds_read_b128 v[198:201], v148 offset:39936
	global_load_lds_dwordx4 v[202:203], off
	v_lshl_add_u64 v[202:203], v[218:219], 0, s[18:19]
	s_mov_b32 m0, s50
	s_nop 0
	global_load_lds_dwordx4 v[202:203], off
	s_waitcnt lgkmcnt(8)
	s_barrier
	s_waitcnt lgkmcnt(0)
	s_waitcnt lgkmcnt(0)
	v_mfma_f32_16x16x32_bf16 v[126:129], v[150:153], v[166:169], v[126:129]
	v_mfma_f32_16x16x32_bf16 v[122:125], v[158:161], v[166:169], v[122:125]
	v_mfma_f32_16x16x32_bf16 v[118:121], v[150:153], v[176:179], v[118:121]
	v_mfma_f32_16x16x32_bf16 v[114:117], v[158:161], v[176:179], v[114:117]
	v_mfma_f32_16x16x32_bf16 v[110:113], v[150:153], v[186:189], v[110:113]
	v_mfma_f32_16x16x32_bf16 v[106:109], v[158:161], v[186:189], v[106:109]
	v_mfma_f32_16x16x32_bf16 v[102:105], v[150:153], v[194:197], v[102:105]
	v_mfma_f32_16x16x32_bf16 v[98:101], v[158:161], v[194:197], v[98:101]
	v_mfma_f32_16x16x32_bf16 v[126:129], v[154:157], v[172:175], v[126:129]
	v_mfma_f32_16x16x32_bf16 v[122:125], v[162:165], v[172:175], v[122:125]
	v_mfma_f32_16x16x32_bf16 v[118:121], v[154:157], v[180:183], v[118:121]
	v_mfma_f32_16x16x32_bf16 v[114:117], v[162:165], v[180:183], v[114:117]
	v_mfma_f32_16x16x32_bf16 v[110:113], v[154:157], v[190:193], v[110:113]
	v_mfma_f32_16x16x32_bf16 v[106:109], v[162:165], v[190:193], v[106:109]
	v_mfma_f32_16x16x32_bf16 v[102:105], v[154:157], v[198:201], v[102:105]
	v_mfma_f32_16x16x32_bf16 v[98:101], v[162:165], v[198:201], v[98:101]
	s_barrier
	s_add_i32 s53, 0, 0x1c000
	s_add_i32 s39, s39, s46
	v_add_u32_e32 v143, s53, v142
	v_lshl_add_u64 v[224:225], v[220:221], 0, s[20:21]
	s_mov_b32 m0, s39
	ds_read_b128 v[202:205], v143
	ds_read_b128 v[206:209], v143 offset:1024
	ds_read_b128 v[210:213], v143 offset:2048
	ds_read_b128 v[214:217], v143 offset:3072
	global_load_lds_dwordx4 v[224:225], off
	v_lshl_add_u64 v[224:225], v[222:223], 0, s[20:21]
	s_add_i32 m0, s39, 0x2000
	s_nop 0
	global_load_lds_dwordx4 v[224:225], off
	s_barrier
	s_waitcnt lgkmcnt(0)
	s_waitcnt lgkmcnt(0)
	v_mfma_f32_16x16x32_bf16 v[94:97], v[202:205], v[166:169], v[94:97]
	v_mfma_f32_16x16x32_bf16 v[90:93], v[210:213], v[166:169], v[90:93]
	v_mfma_f32_16x16x32_bf16 v[86:89], v[202:205], v[176:179], v[86:89]
	v_mfma_f32_16x16x32_bf16 v[82:85], v[210:213], v[176:179], v[82:85]
	v_mfma_f32_16x16x32_bf16 v[78:81], v[202:205], v[186:189], v[78:81]
	v_mfma_f32_16x16x32_bf16 v[74:77], v[210:213], v[186:189], v[74:77]
	v_mfma_f32_16x16x32_bf16 v[70:73], v[202:205], v[194:197], v[70:73]
	v_mfma_f32_16x16x32_bf16 v[66:69], v[210:213], v[194:197], v[66:69]
	v_mfma_f32_16x16x32_bf16 v[94:97], v[206:209], v[172:175], v[94:97]
	v_mfma_f32_16x16x32_bf16 v[90:93], v[214:217], v[172:175], v[90:93]
	v_mfma_f32_16x16x32_bf16 v[86:89], v[206:209], v[180:183], v[86:89]
	v_mfma_f32_16x16x32_bf16 v[82:85], v[214:217], v[180:183], v[82:85]
	v_mfma_f32_16x16x32_bf16 v[78:81], v[206:209], v[190:193], v[78:81]
	v_mfma_f32_16x16x32_bf16 v[74:77], v[214:217], v[190:193], v[74:77]
	v_mfma_f32_16x16x32_bf16 v[70:73], v[206:209], v[198:201], v[70:73]
	v_mfma_f32_16x16x32_bf16 v[66:69], v[214:217], v[198:201], v[66:69]
	s_mov_b32 m0, s51
	v_lshl_add_u64 v[144:145], v[144:145], 0, s[22:23]
	s_barrier
	ds_read_b128 v[166:169], v148 offset:49152
	ds_read_b128 v[172:175], v148 offset:50176
	ds_read_b128 v[176:179], v148 offset:51200
	ds_read_b128 v[180:183], v148 offset:52224
	ds_read_b128 v[186:189], v148 offset:53248
	ds_read_b128 v[190:193], v148 offset:54272
	ds_read_b128 v[194:197], v148 offset:55296
	ds_read_b128 v[198:201], v148 offset:56320
	global_load_lds_dwordx4 v[144:145], off
	v_lshl_add_u64 v[144:145], v[218:219], 0, s[22:23]
	s_mov_b32 m0, s52
	s_nop 0
	global_load_lds_dwordx4 v[144:145], off
	s_barrier
	s_waitcnt lgkmcnt(0)
	s_waitcnt lgkmcnt(0)
	v_mfma_f32_16x16x32_bf16 v[62:65], v[150:153], v[166:169], v[62:65]
	v_mfma_f32_16x16x32_bf16 v[58:61], v[158:161], v[166:169], v[58:61]
	v_mfma_f32_16x16x32_bf16 v[54:57], v[150:153], v[176:179], v[54:57]
	v_mfma_f32_16x16x32_bf16 v[50:53], v[158:161], v[176:179], v[50:53]
	v_mfma_f32_16x16x32_bf16 v[46:49], v[150:153], v[186:189], v[46:49]
	v_mfma_f32_16x16x32_bf16 v[42:45], v[158:161], v[186:189], v[42:45]
	v_mfma_f32_16x16x32_bf16 v[38:41], v[150:153], v[194:197], v[38:41]
	v_mfma_f32_16x16x32_bf16 v[34:37], v[158:161], v[194:197], v[34:37]
	v_mfma_f32_16x16x32_bf16 v[62:65], v[154:157], v[172:175], v[62:65]
	v_mfma_f32_16x16x32_bf16 v[58:61], v[162:165], v[172:175], v[58:61]
	v_mfma_f32_16x16x32_bf16 v[54:57], v[154:157], v[180:183], v[54:57]
	v_mfma_f32_16x16x32_bf16 v[50:53], v[162:165], v[180:183], v[50:53]
	v_mfma_f32_16x16x32_bf16 v[46:49], v[154:157], v[190:193], v[46:49]
	v_mfma_f32_16x16x32_bf16 v[42:45], v[162:165], v[190:193], v[42:45]
	v_mfma_f32_16x16x32_bf16 v[38:41], v[154:157], v[198:201], v[38:41]
	v_mfma_f32_16x16x32_bf16 v[34:37], v[162:165], v[198:201], v[34:37]
	s_barrier
	s_add_i32 s39, s53, s46
	v_lshl_add_u64 v[144:145], v[220:221], 0, s[24:25]
	s_mov_b32 m0, s39
	s_nop 0
	global_load_lds_dwordx4 v[144:145], off
	v_lshl_add_u64 v[144:145], v[222:223], 0, s[24:25]
	s_add_i32 m0, s39, 0x2000
	s_nop 0
	global_load_lds_dwordx4 v[144:145], off
	s_waitcnt vmcnt(6)
	s_barrier
	v_mfma_f32_16x16x32_bf16 v[30:33], v[202:205], v[166:169], v[30:33]
	v_mfma_f32_16x16x32_bf16 v[26:29], v[210:213], v[166:169], v[26:29]
	v_mfma_f32_16x16x32_bf16 v[22:25], v[202:205], v[176:179], v[22:25]
	v_mfma_f32_16x16x32_bf16 v[18:21], v[210:213], v[176:179], v[18:21]
	v_mfma_f32_16x16x32_bf16 v[14:17], v[202:205], v[186:189], v[14:17]
	v_mfma_f32_16x16x32_bf16 v[10:13], v[210:213], v[186:189], v[10:13]
	v_mfma_f32_16x16x32_bf16 v[6:9], v[202:205], v[194:197], v[6:9]
	v_mfma_f32_16x16x32_bf16 v[2:5], v[210:213], v[194:197], v[2:5]
	v_mfma_f32_16x16x32_bf16 v[30:33], v[206:209], v[172:175], v[30:33]
	v_mfma_f32_16x16x32_bf16 v[26:29], v[214:217], v[172:175], v[26:29]
	v_mfma_f32_16x16x32_bf16 v[22:25], v[206:209], v[180:183], v[22:25]
	v_mfma_f32_16x16x32_bf16 v[18:21], v[214:217], v[180:183], v[18:21]
	v_mfma_f32_16x16x32_bf16 v[14:17], v[206:209], v[190:193], v[14:17]
	v_mfma_f32_16x16x32_bf16 v[10:13], v[214:217], v[190:193], v[10:13]
	v_mfma_f32_16x16x32_bf16 v[6:9], v[206:209], v[198:201], v[6:9]
	v_mfma_f32_16x16x32_bf16 v[2:5], v[214:217], v[198:201], v[2:5]
	s_add_i32 s36, s36, 2
	s_add_u32 s34, s34, 0x100
	s_addc_u32 s35, s35, 0
	s_cmp_gt_u32 s36, 11
	s_barrier
	s_cbranch_scc0 .LBB0_463
	s_add_u32 s30, s30, 0x120780
	v_add_u32_e32 v149, 0, v142
	s_addc_u32 s31, s31, 0
	s_mov_b32 m0, s38
	v_add_u32_e32 v150, 0x10000, v149
	v_lshl_add_u64 v[130:131], s[30:31], 0, v[130:131]
	ds_read_b128 v[134:137], v150
	ds_read_b128 v[138:141], v150 offset:1024
	ds_read_b128 v[142:145], v150 offset:2048
	ds_read_b128 v[150:153], v150 offset:3072
	ds_read_b128 v[154:157], v148
	ds_read_b128 v[158:161], v148 offset:1024
	ds_read_b128 v[162:165], v148 offset:2048
	ds_read_b128 v[166:169], v148 offset:3072
	ds_read_b128 v[172:175], v148 offset:4096
	ds_read_b128 v[176:179], v148 offset:5120
	ds_read_b128 v[180:183], v148 offset:6144
	ds_read_b128 v[186:189], v148 offset:7168
	global_load_lds_dwordx4 v[130:131], off
	v_lshl_add_u64 v[130:131], s[30:31], 0, v[132:133]
	s_mov_b32 m0, s37
	s_nop 0
	global_load_lds_dwordx4 v[130:131], off
	s_barrier
	s_waitcnt lgkmcnt(0)
	s_waitcnt lgkmcnt(0)
	v_mfma_f32_16x16x32_bf16 v[126:129], v[134:137], v[154:157], v[126:129]
	v_mfma_f32_16x16x32_bf16 v[122:125], v[142:145], v[154:157], v[122:125]
	v_mfma_f32_16x16x32_bf16 v[102:105], v[134:137], v[180:183], v[102:105]
	v_mfma_f32_16x16x32_bf16 v[98:101], v[142:145], v[180:183], v[98:101]
	v_mfma_f32_16x16x32_bf16 v[126:129], v[138:141], v[158:161], v[126:129]
	v_mfma_f32_16x16x32_bf16 v[122:125], v[150:153], v[158:161], v[122:125]
	v_mfma_f32_16x16x32_bf16 v[118:121], v[134:137], v[162:165], v[118:121]
	v_mfma_f32_16x16x32_bf16 v[114:117], v[142:145], v[162:165], v[114:117]
	v_mfma_f32_16x16x32_bf16 v[110:113], v[134:137], v[172:175], v[110:113]
	v_mfma_f32_16x16x32_bf16 v[106:109], v[142:145], v[172:175], v[106:109]
	v_mfma_f32_16x16x32_bf16 v[102:105], v[138:141], v[186:189], v[102:105]
	v_mfma_f32_16x16x32_bf16 v[98:101], v[150:153], v[186:189], v[98:101]
	v_mfma_f32_16x16x32_bf16 v[118:121], v[138:141], v[166:169], v[118:121]
	v_mfma_f32_16x16x32_bf16 v[114:117], v[150:153], v[166:169], v[114:117]
	v_mfma_f32_16x16x32_bf16 v[110:113], v[138:141], v[176:179], v[110:113]
	v_mfma_f32_16x16x32_bf16 v[106:109], v[150:153], v[176:179], v[106:109]
	v_add_u32_e32 v170, 0x14000, v149
	s_barrier
	ds_read_b128 v[130:133], v170
	ds_read_b128 v[190:193], v170 offset:1024
	ds_read_b128 v[194:197], v170 offset:2048
	ds_read_b128 v[198:201], v170 offset:3072
	s_barrier
	s_waitcnt lgkmcnt(0)
	s_waitcnt lgkmcnt(0)
	v_mfma_f32_16x16x32_bf16 v[86:89], v[130:133], v[162:165], v[86:89]
	v_mfma_f32_16x16x32_bf16 v[82:85], v[194:197], v[162:165], v[82:85]
	v_mfma_f32_16x16x32_bf16 v[70:73], v[130:133], v[180:183], v[70:73]
	v_mfma_f32_16x16x32_bf16 v[66:69], v[194:197], v[180:183], v[66:69]
	v_mfma_f32_16x16x32_bf16 v[94:97], v[130:133], v[154:157], v[94:97]
	v_mfma_f32_16x16x32_bf16 v[90:93], v[194:197], v[154:157], v[90:93]
	v_mfma_f32_16x16x32_bf16 v[86:89], v[190:193], v[166:169], v[86:89]
	v_mfma_f32_16x16x32_bf16 v[82:85], v[198:201], v[166:169], v[82:85]
	v_mfma_f32_16x16x32_bf16 v[78:81], v[130:133], v[172:175], v[78:81]
	v_mfma_f32_16x16x32_bf16 v[74:77], v[194:197], v[172:175], v[74:77]
	v_mfma_f32_16x16x32_bf16 v[70:73], v[190:193], v[186:189], v[70:73]
	v_mfma_f32_16x16x32_bf16 v[66:69], v[198:201], v[186:189], v[66:69]
	v_mfma_f32_16x16x32_bf16 v[202:205], v[190:193], v[158:161], v[94:97]
	v_mfma_f32_16x16x32_bf16 v[154:157], v[198:201], v[158:161], v[90:93]
	v_mfma_f32_16x16x32_bf16 v[158:161], v[190:193], v[176:179], v[78:81]
	v_mfma_f32_16x16x32_bf16 v[172:175], v[198:201], v[176:179], v[74:77]
	s_barrier
	s_nop 0
	ds_read_b128 v[74:77], v148 offset:16384
	ds_read_b128 v[78:81], v148 offset:17408
	ds_read_b128 v[90:93], v148 offset:18432
	ds_read_b128 v[94:97], v148 offset:19456
	ds_read_b128 v[162:165], v148 offset:20480
	ds_read_b128 v[166:169], v148 offset:21504
	ds_read_b128 v[176:179], v148 offset:22528
	ds_read_b128 v[180:183], v148 offset:23552
	s_waitcnt vmcnt(4)
	s_barrier
	s_waitcnt lgkmcnt(0)
	s_waitcnt lgkmcnt(0)
	v_mfma_f32_16x16x32_bf16 v[62:65], v[134:137], v[74:77], v[62:65]
	v_mfma_f32_16x16x32_bf16 v[58:61], v[142:145], v[74:77], v[58:61]
	v_mfma_f32_16x16x32_bf16 v[54:57], v[134:137], v[90:93], v[54:57]
	v_mfma_f32_16x16x32_bf16 v[50:53], v[142:145], v[90:93], v[50:53]
	v_mfma_f32_16x16x32_bf16 v[38:41], v[134:137], v[176:179], v[38:41]
	v_mfma_f32_16x16x32_bf16 v[34:37], v[142:145], v[176:179], v[34:37]
	v_mfma_f32_16x16x32_bf16 v[62:65], v[138:141], v[78:81], v[62:65]
	v_mfma_f32_16x16x32_bf16 v[58:61], v[150:153], v[78:81], v[58:61]
	v_mfma_f32_16x16x32_bf16 v[54:57], v[138:141], v[94:97], v[54:57]
	v_mfma_f32_16x16x32_bf16 v[50:53], v[150:153], v[94:97], v[50:53]
	v_mfma_f32_16x16x32_bf16 v[46:49], v[134:137], v[162:165], v[46:49]
	v_mfma_f32_16x16x32_bf16 v[42:45], v[142:145], v[162:165], v[42:45]
	v_mfma_f32_16x16x32_bf16 v[38:41], v[138:141], v[180:183], v[38:41]
	v_mfma_f32_16x16x32_bf16 v[34:37], v[150:153], v[180:183], v[34:37]
	v_mfma_f32_16x16x32_bf16 v[186:189], v[138:141], v[166:169], v[46:49]
	v_mfma_f32_16x16x32_bf16 v[206:209], v[150:153], v[166:169], v[42:45]
	v_mfma_f32_16x16x32_bf16 v[22:25], v[130:133], v[90:93], v[22:25]
	v_mfma_f32_16x16x32_bf16 v[18:21], v[194:197], v[90:93], v[18:21]
	v_mfma_f32_16x16x32_bf16 v[6:9], v[130:133], v[176:179], v[6:9]
	v_mfma_f32_16x16x32_bf16 v[2:5], v[194:197], v[176:179], v[2:5]
	v_mfma_f32_16x16x32_bf16 v[30:33], v[130:133], v[74:77], v[30:33]
	v_mfma_f32_16x16x32_bf16 v[26:29], v[194:197], v[74:77], v[26:29]
	v_mfma_f32_16x16x32_bf16 v[22:25], v[190:193], v[94:97], v[22:25]
	v_mfma_f32_16x16x32_bf16 v[18:21], v[198:201], v[94:97], v[18:21]
	v_mfma_f32_16x16x32_bf16 v[14:17], v[130:133], v[162:165], v[14:17]
	v_mfma_f32_16x16x32_bf16 v[10:13], v[194:197], v[162:165], v[10:13]
	v_mfma_f32_16x16x32_bf16 v[6:9], v[190:193], v[180:183], v[6:9]
	v_mfma_f32_16x16x32_bf16 v[2:5], v[198:201], v[180:183], v[2:5]
	v_mfma_f32_16x16x32_bf16 v[134:137], v[190:193], v[78:81], v[30:33]
	v_mfma_f32_16x16x32_bf16 v[138:141], v[198:201], v[78:81], v[26:29]
	v_mfma_f32_16x16x32_bf16 v[210:213], v[190:193], v[166:169], v[14:17]
	v_mfma_f32_16x16x32_bf16 v[214:217], v[198:201], v[166:169], v[10:13]
	v_add_u32_e32 v26, 0x18000, v149
	s_barrier
	ds_read_b128 v[10:13], v26
	ds_read_b128 v[14:17], v26 offset:1024
	ds_read_b128 v[130:133], v26 offset:2048
	ds_read_b128 v[176:179], v26 offset:3072
	ds_read_b128 v[26:29], v148 offset:32768
	ds_read_b128 v[30:33], v148 offset:33792
	ds_read_b128 v[42:45], v148 offset:34816
	ds_read_b128 v[46:49], v148 offset:35840
	ds_read_b128 v[180:183], v148 offset:36864
	ds_read_b128 v[190:193], v148 offset:37888
	ds_read_b128 v[194:197], v148 offset:38912
	ds_read_b128 v[198:201], v148 offset:39936
	s_waitcnt vmcnt(2)
	s_barrier
	s_waitcnt lgkmcnt(0)
	s_waitcnt lgkmcnt(0)
	v_mfma_f32_16x16x32_bf16 v[74:77], v[10:13], v[26:29], v[126:129]
	v_mfma_f32_16x16x32_bf16 v[166:169], v[14:17], v[30:33], v[74:77]
	v_mfma_f32_16x16x32_bf16 v[74:77], v[130:133], v[26:29], v[122:125]
	v_mfma_f32_16x16x32_bf16 v[162:165], v[176:179], v[30:33], v[74:77]
	v_mfma_f32_16x16x32_bf16 v[74:77], v[10:13], v[42:45], v[118:121]
	v_mfma_f32_16x16x32_bf16 v[126:129], v[14:17], v[46:49], v[74:77]
	v_mfma_f32_16x16x32_bf16 v[74:77], v[130:133], v[42:45], v[114:117]
	v_mfma_f32_16x16x32_bf16 v[122:125], v[176:179], v[46:49], v[74:77]
	v_mfma_f32_16x16x32_bf16 v[74:77], v[10:13], v[180:183], v[110:113]
	v_mfma_f32_16x16x32_bf16 v[94:97], v[14:17], v[190:193], v[74:77]
	v_mfma_f32_16x16x32_bf16 v[74:77], v[130:133], v[180:183], v[106:109]
	v_mfma_f32_16x16x32_bf16 v[90:93], v[176:179], v[190:193], v[74:77]
	v_mfma_f32_16x16x32_bf16 v[74:77], v[10:13], v[194:197], v[102:105]
	v_mfma_f32_16x16x32_bf16 v[78:81], v[14:17], v[198:201], v[74:77]
	v_mfma_f32_16x16x32_bf16 v[74:77], v[130:133], v[194:197], v[98:101]
	v_mfma_f32_16x16x32_bf16 v[74:77], v[176:179], v[198:201], v[74:77]
	s_nop 0
	v_add_u32_e32 v98, 0x1c000, v149
	s_barrier
	ds_read_b128 v[106:109], v98
	ds_read_b128 v[110:113], v98 offset:1024
	ds_read_b128 v[114:117], v98 offset:2048
	ds_read_b128 v[118:121], v98 offset:3072
	s_waitcnt vmcnt(0)
	s_barrier
	s_waitcnt lgkmcnt(0)
	s_waitcnt lgkmcnt(0)
	v_mfma_f32_16x16x32_bf16 v[98:101], v[106:109], v[26:29], v[202:205]
	v_mfma_f32_16x16x32_bf16 v[26:29], v[114:117], v[26:29], v[154:157]
	v_mfma_f32_16x16x32_bf16 v[142:145], v[118:121], v[30:33], v[26:29]
	v_mfma_f32_16x16x32_bf16 v[26:29], v[106:109], v[42:45], v[86:89]
	v_mfma_f32_16x16x32_bf16 v[102:105], v[110:113], v[46:49], v[26:29]
	v_mfma_f32_16x16x32_bf16 v[26:29], v[114:117], v[42:45], v[82:85]
	v_mfma_f32_16x16x32_bf16 v[150:153], v[110:113], v[30:33], v[98:101]
	v_mfma_f32_16x16x32_bf16 v[98:101], v[118:121], v[46:49], v[26:29]
	v_mfma_f32_16x16x32_bf16 v[26:29], v[106:109], v[180:183], v[158:161]
	v_mfma_f32_16x16x32_bf16 v[86:89], v[110:113], v[190:193], v[26:29]
	v_mfma_f32_16x16x32_bf16 v[26:29], v[114:117], v[180:183], v[172:175]
	v_mfma_f32_16x16x32_bf16 v[82:85], v[118:121], v[190:193], v[26:29]
	v_mfma_f32_16x16x32_bf16 v[26:29], v[106:109], v[194:197], v[70:73]
	v_mfma_f32_16x16x32_bf16 v[70:73], v[110:113], v[198:201], v[26:29]
	v_mfma_f32_16x16x32_bf16 v[26:29], v[114:117], v[194:197], v[66:69]
	v_mfma_f32_16x16x32_bf16 v[66:69], v[118:121], v[198:201], v[26:29]
	s_barrier
	ds_read_b128 v[154:157], v148 offset:49152
	ds_read_b128 v[158:161], v148 offset:50176
	ds_read_b128 v[172:175], v148 offset:51200
	ds_read_b128 v[180:183], v148 offset:52224
	ds_read_b128 v[190:193], v148 offset:53248
	ds_read_b128 v[194:197], v148 offset:54272
	ds_read_b128 v[198:201], v148 offset:55296
	ds_read_b128 v[202:205], v148 offset:56320
	s_barrier
	s_waitcnt lgkmcnt(0)
	s_waitcnt lgkmcnt(0)
	v_mfma_f32_16x16x32_bf16 v[26:29], v[10:13], v[154:157], v[62:65]
	v_mfma_f32_16x16x32_bf16 v[62:65], v[14:17], v[158:161], v[26:29]
	v_mfma_f32_16x16x32_bf16 v[26:29], v[130:133], v[154:157], v[58:61]
	v_mfma_f32_16x16x32_bf16 v[58:61], v[176:179], v[158:161], v[26:29]
	v_mfma_f32_16x16x32_bf16 v[26:29], v[10:13], v[172:175], v[54:57]
	v_mfma_f32_16x16x32_bf16 v[46:49], v[14:17], v[180:183], v[26:29]
	v_mfma_f32_16x16x32_bf16 v[26:29], v[130:133], v[172:175], v[50:53]
	v_mfma_f32_16x16x32_bf16 v[42:45], v[176:179], v[180:183], v[26:29]
	v_mfma_f32_16x16x32_bf16 v[26:29], v[10:13], v[190:193], v[186:189]
	v_mfma_f32_16x16x32_bf16 v[10:13], v[10:13], v[198:201], v[38:41]
	v_mfma_f32_16x16x32_bf16 v[30:33], v[14:17], v[194:197], v[26:29]
	v_mfma_f32_16x16x32_bf16 v[26:29], v[130:133], v[190:193], v[206:209]
	v_mfma_f32_16x16x32_bf16 v[14:17], v[14:17], v[202:205], v[10:13]
	v_mfma_f32_16x16x32_bf16 v[10:13], v[130:133], v[198:201], v[34:37]
	v_mfma_f32_16x16x32_bf16 v[26:29], v[176:179], v[194:197], v[26:29]
	v_mfma_f32_16x16x32_bf16 v[10:13], v[176:179], v[202:205], v[10:13]
	v_mfma_f32_16x16x32_bf16 v[34:37], v[106:109], v[154:157], v[134:137]
	v_mfma_f32_16x16x32_bf16 v[54:57], v[110:113], v[158:161], v[34:37]
	v_mfma_f32_16x16x32_bf16 v[34:37], v[114:117], v[154:157], v[138:141]
	v_mfma_f32_16x16x32_bf16 v[18:21], v[114:117], v[172:175], v[18:21]
	v_mfma_f32_16x16x32_bf16 v[50:53], v[118:121], v[158:161], v[34:37]
	v_mfma_f32_16x16x32_bf16 v[22:25], v[106:109], v[172:175], v[22:25]
	v_mfma_f32_16x16x32_bf16 v[34:37], v[118:121], v[180:183], v[18:21]
	v_mfma_f32_16x16x32_bf16 v[18:21], v[106:109], v[190:193], v[210:213]
	v_mfma_f32_16x16x32_bf16 v[38:41], v[110:113], v[180:183], v[22:25]
	v_mfma_f32_16x16x32_bf16 v[22:25], v[110:113], v[194:197], v[18:21]
	v_mfma_f32_16x16x32_bf16 v[18:21], v[114:117], v[190:193], v[214:217]
	v_mfma_f32_16x16x32_bf16 v[6:9], v[106:109], v[198:201], v[6:9]
	v_mfma_f32_16x16x32_bf16 v[2:5], v[114:117], v[198:201], v[2:5]
	v_mfma_f32_16x16x32_bf16 v[18:21], v[118:121], v[194:197], v[18:21]
	v_mfma_f32_16x16x32_bf16 v[6:9], v[110:113], v[202:205], v[6:9]
	v_mfma_f32_16x16x32_bf16 v[2:5], v[118:121], v[202:205], v[2:5]
	s_cmpk_lt_u32 s44, 0x100
	s_barrier
	s_cbranch_scc0 .LBB0_455
	s_barrier
	s_branch .LBB0_455

.LBB0_614:
	v_mov_b32_e32 v23, v0
	s_add_i32 s4, s34, s4
	v_ashrrev_i32_e32 v3, 31, v23
	v_lshrrev_b32_e32 v3, 26, v3
	v_add_u32_e32 v3, v23, v3
	v_ashrrev_i32_e32 v12, 6, v3
	v_bfe_i32 v3, v23, 27, 1
	v_lshlrev_b32_e32 v2, 4, v23
	v_lshrrev_b32_e32 v3, 22, v3
	v_add_u32_e32 v3, v2, v3
	v_and_b32_e32 v3, 0xfffffc00, v3
	v_sub_u32_e32 v3, v2, v3
	v_lshrrev_b32_e32 v4, 4, v3
	v_bitop3_b32 v4, v4, v3, 32 bitop3:0x6c
	v_ashrrev_i32_e32 v3, 31, v3
	v_lshrrev_b32_e32 v3, 26, v3
	v_lshlrev_b32_e32 v5, 3, v12
	v_add_u32_e32 v3, v4, v3
	v_and_b32_e32 v5, -16, v5
	s_waitcnt vmcnt(10)
	v_ashrrev_i32_e32 v19, 6, v3
	v_add_u32_e32 v3, v19, v5
	v_lshlrev_b32_e32 v5, 5, v12
	v_and_b32_e32 v20, 32, v5
	v_mul_i32_i24_e32 v5, 64, v19
	v_sub_u32_e32 v4, v4, v5
	v_ashrrev_i16_sdwa v4, v157, sext(v4) dst_sel:DWORD dst_unused:UNUSED_PAD src0_sel:DWORD src1_sel:BYTE_0
	v_lshlrev_b32_e32 v5, 1, v3
	v_bfe_i32 v13, v4, 0, 16
	v_and_b32_e32 v14, 0xfffe0, v3
	v_and_b32_e32 v15, 24, v5
	v_lshrrev_b32_e32 v5, 2, v3
	v_and_b32_e32 v17, 3, v19
	s_ashr_i32 s5, s4, 31
	v_add_u32_e32 v4, v20, v13
	v_and_b32_e32 v16, 4, v5
	v_or_b32_e32 v5, v14, v17
	v_mul_lo_u32 v3, v3, s43
	s_lshr_b32 s5, s5, 27
	v_or3_b32 v5, v5, v15, v16
	v_add_lshl_u32 v130, v4, v3, 1
	v_lshlrev_b32_e32 v3, 1, v4
	v_add_u32_e32 v2, 0x2000, v2
	s_add_i32 s5, s4, s5
	v_lshl_add_u32 v146, v5, 12, v3
	v_ashrrev_i32_e32 v3, 31, v2
	s_and_b32 s12, s5, 0xffe0
	v_lshrrev_b32_e32 v3, 22, v3
	s_sub_i32 s4, s4, s12
	v_add_u32_e32 v3, v2, v3
	s_bfe_i32 s12, s4, 0x80000
	v_ashrrev_i32_e32 v18, 10, v3
	s_bfe_u32 s12, s12, 0x3000c
	v_mul_i32_i24_e32 v3, 0x400, v18
	s_add_i32 s12, s4, s12
	v_sub_u32_e32 v2, v2, v3
	s_bfe_i32 s34, s12, 0x80000
	s_and_b32 s12, s12, 0xf8
	v_lshrrev_b32_e32 v3, 4, v2
	s_sub_i32 s4, s4, s12
	v_bitop3_b32 v2, v3, v2, 32 bitop3:0x6c
	s_sext_i32_i16 s34, s34
	s_sext_i32_i8 s4, s4
	v_ashrrev_i32_e32 v4, 31, v2
	s_lshl_b32 s47, s4, 8
	s_lshl_b32 s4, s34, 5
	v_lshrrev_b32_e32 v4, 26, v4
	s_lshl_b32 s5, s5, 6
	s_and_b32 s34, s4, 0xffffff00
	v_readfirstlane_b32 s48, v23
	v_lshlrev_b32_e32 v3, 3, v18
	v_add_u32_e32 v4, v2, v4
	s_and_b32 s5, s5, 0xfffff800
	s_ashr_i32 s12, s48, 6
	v_and_b32_e32 v3, -16, v3
	s_waitcnt vmcnt(9)
	v_ashrrev_i32_e32 v27, 6, v4
	v_and_b32_e32 v4, 0xc0, v4
	s_ashr_i32 s35, s34, 31
	s_add_i32 s47, s47, s5
	v_add_u32_e32 v3, v27, v3
	v_sub_u32_e32 v2, v2, v4
	s_ashr_i32 s54, s48, 8
	s_lshl_b32 s49, s12, 10
	s_lshl_b64 s[36:37], s[34:35], 12
	v_lshlrev_b32_e32 v5, 5, v18
	v_ashrrev_i16_sdwa v2, v157, sext(v2) dst_sel:DWORD dst_unused:UNUSED_PAD src0_sel:DWORD src1_sel:BYTE_0
	v_lshlrev_b32_e32 v4, 1, v3
	s_add_u32 s40, s33, s36
	v_and_b32_e32 v28, 32, v5
	v_bfe_i32 v21, v2, 0, 16
	v_and_b32_e32 v22, 0xfffe0, v3
	v_and_b32_e32 v24, 24, v4
	v_lshrrev_b32_e32 v4, 2, v3
	v_and_b32_e32 v26, 3, v27
	s_addc_u32 s41, s42, s37
	s_add_i32 s50, s49, 0
	v_add_u32_e32 v2, v28, v21
	v_and_b32_e32 v25, 4, v4
	v_or_b32_e32 v4, v22, v26
	v_mul_lo_u32 v3, v3, s43
	s_add_i32 m0, s50, 0x10000
	v_or3_b32 v4, v4, v24, v25
	v_add_lshl_u32 v132, v2, v3, 1
	v_lshlrev_b32_e32 v2, 1, v2
	s_mul_i32 s38, s47, 0x2400
	global_load_lds_dwordx4 v146, s[40:41]
	s_add_i32 m0, s50, 0x12000
	v_lshl_add_u32 v2, v4, 12, v2
	s_mul_hi_i32 s39, s47, 0x2400
	s_add_u32 s4, s60, s38
	global_load_lds_dwordx4 v2, s[40:41]
	s_addc_u32 s5, s61, s39
	s_mov_b32 m0, s50
	s_add_i32 s51, s50, 0x2000
	global_load_lds_dwordx4 v130, s[4:5]
	s_mov_b32 m0, s51
	s_add_u32 s52, s40, 0x80000
	global_load_lds_dwordx4 v132, s[4:5]
	s_addc_u32 s53, s41, 0
	s_add_i32 m0, s50, 0x14000
	v_mov_b32_e32 v3, v147
	global_load_lds_dwordx4 v146, s[52:53]
	s_add_i32 m0, s50, 0x16000
	s_add_u32 s56, s4, 0x120000
	global_load_lds_dwordx4 v2, s[52:53]
	s_addc_u32 s57, s5, 0
	s_add_i32 s52, s50, 0x4000
	s_mov_b32 m0, s52
	s_add_i32 s53, s50, 0x6000
	global_load_lds_dwordx4 v130, s[56:57]
	s_mov_b32 m0, s53
	v_mov_b32_e32 v131, v147
	global_load_lds_dwordx4 v132, s[56:57]
	v_mov_b32_e32 v133, v147
	v_lshl_add_u64 v[10:11], s[40:41], 0, v[146:147]
	v_lshl_add_u64 v[8:9], s[40:41], 0, v[2:3]
	v_lshl_add_u64 v[6:7], s[4:5], 0, v[130:131]
	s_cmp_lg_u32 s54, 1
	v_lshl_add_u64 v[4:5], s[4:5], 0, v[132:133]
	s_cbranch_scc1 .LBB0_616
	s_setprio 1
	s_barrier

.LBB0_617:
	s_add_i32 s41, 0, 0x10000
	v_add_u32_e32 v143, s41, v142
	ds_read_b128 v[150:153], v143
	ds_read_b128 v[160:163], v143 offset:1024
	ds_read_b128 v[164:167], v143 offset:2048
	ds_read_b128 v[168:171], v143 offset:3072
	v_lshl_add_u64 v[144:145], s[36:37], 0, v[134:135]
	s_add_i32 s40, s50, 0xc000
	v_lshl_add_u64 v[154:155], v[144:145], 0, s[16:17]
	s_mov_b32 m0, s40
	ds_read_b128 v[172:175], v146
	ds_read_b128 v[176:179], v146 offset:1024
	ds_read_b128 v[180:183], v146 offset:2048
	ds_read_b128 v[186:189], v146 offset:3072
	ds_read_b128 v[190:193], v146 offset:4096
	ds_read_b128 v[194:197], v146 offset:5120
	ds_read_b128 v[198:201], v146 offset:6144
	ds_read_b128 v[202:205], v146 offset:7168
	global_load_lds_dwordx4 v[154:155], off
	v_lshl_add_u64 v[154:155], s[36:37], 0, v[136:137]
	s_add_i32 s39, s50, 0xe000
	v_lshl_add_u64 v[206:207], v[154:155], 0, s[16:17]
	s_mov_b32 m0, s39
	s_nop 0
	global_load_lds_dwordx4 v[206:207], off
	s_waitcnt lgkmcnt(8)
	s_barrier
	s_waitcnt lgkmcnt(0)
	s_waitcnt lgkmcnt(0)
	v_mfma_f32_16x16x32_bf16 v[126:129], v[150:153], v[172:175], v[126:129]
	v_mfma_f32_16x16x32_bf16 v[122:125], v[164:167], v[172:175], v[122:125]
	v_mfma_f32_16x16x32_bf16 v[118:121], v[150:153], v[180:183], v[118:121]
	v_mfma_f32_16x16x32_bf16 v[114:117], v[164:167], v[180:183], v[114:117]
	v_mfma_f32_16x16x32_bf16 v[110:113], v[150:153], v[190:193], v[110:113]
	v_mfma_f32_16x16x32_bf16 v[106:109], v[164:167], v[190:193], v[106:109]
	v_mfma_f32_16x16x32_bf16 v[102:105], v[150:153], v[198:201], v[102:105]
	v_mfma_f32_16x16x32_bf16 v[98:101], v[164:167], v[198:201], v[98:101]
	v_mfma_f32_16x16x32_bf16 v[126:129], v[160:163], v[176:179], v[126:129]
	v_mfma_f32_16x16x32_bf16 v[122:125], v[168:171], v[176:179], v[122:125]
	v_mfma_f32_16x16x32_bf16 v[118:121], v[160:163], v[186:189], v[118:121]
	v_mfma_f32_16x16x32_bf16 v[114:117], v[168:171], v[186:189], v[114:117]
	v_mfma_f32_16x16x32_bf16 v[110:113], v[160:163], v[194:197], v[110:113]
	v_mfma_f32_16x16x32_bf16 v[106:109], v[168:171], v[194:197], v[106:109]
	v_mfma_f32_16x16x32_bf16 v[102:105], v[160:163], v[202:205], v[102:105]
	v_mfma_f32_16x16x32_bf16 v[98:101], v[168:171], v[202:205], v[98:101]
	s_barrier
	s_add_i32 s56, 0, 0x14000
	v_lshl_add_u64 v[222:223], s[36:37], 0, v[138:139]
	s_add_i32 s41, s41, s49
	v_add_u32_e32 v143, s56, v142
	v_lshl_add_u64 v[224:225], v[222:223], 0, s[18:19]
	s_mov_b32 m0, s41
	ds_read_b128 v[206:209], v143
	ds_read_b128 v[210:213], v143 offset:1024
	ds_read_b128 v[214:217], v143 offset:2048
	ds_read_b128 v[218:221], v143 offset:3072
	global_load_lds_dwordx4 v[224:225], off
	v_lshl_add_u64 v[224:225], s[36:37], 0, v[140:141]
	v_lshl_add_u64 v[226:227], v[224:225], 0, s[18:19]
	s_add_i32 m0, s41, 0x2000
	s_nop 0
	global_load_lds_dwordx4 v[226:227], off
	s_barrier
	s_waitcnt lgkmcnt(0)
	s_waitcnt lgkmcnt(0)
	v_mfma_f32_16x16x32_bf16 v[94:97], v[206:209], v[172:175], v[94:97]
	v_mfma_f32_16x16x32_bf16 v[90:93], v[214:217], v[172:175], v[90:93]
	v_mfma_f32_16x16x32_bf16 v[86:89], v[206:209], v[180:183], v[86:89]
	v_mfma_f32_16x16x32_bf16 v[82:85], v[214:217], v[180:183], v[82:85]
	v_mfma_f32_16x16x32_bf16 v[78:81], v[206:209], v[190:193], v[78:81]
	v_mfma_f32_16x16x32_bf16 v[74:77], v[214:217], v[190:193], v[74:77]
	v_mfma_f32_16x16x32_bf16 v[70:73], v[206:209], v[198:201], v[70:73]
	v_mfma_f32_16x16x32_bf16 v[66:69], v[214:217], v[198:201], v[66:69]
	v_mfma_f32_16x16x32_bf16 v[94:97], v[210:213], v[176:179], v[94:97]
	v_mfma_f32_16x16x32_bf16 v[90:93], v[218:221], v[176:179], v[90:93]
	v_mfma_f32_16x16x32_bf16 v[86:89], v[210:213], v[186:189], v[86:89]
	v_mfma_f32_16x16x32_bf16 v[82:85], v[218:221], v[186:189], v[82:85]
	v_mfma_f32_16x16x32_bf16 v[78:81], v[210:213], v[194:197], v[78:81]
	v_mfma_f32_16x16x32_bf16 v[74:77], v[218:221], v[194:197], v[74:77]
	v_mfma_f32_16x16x32_bf16 v[70:73], v[210:213], v[202:205], v[70:73]
	v_mfma_f32_16x16x32_bf16 v[66:69], v[218:221], v[202:205], v[66:69]
	s_mov_b32 m0, s50
	v_lshl_add_u64 v[226:227], v[144:145], 0, s[20:21]
	s_barrier
	ds_read_b128 v[172:175], v146 offset:16384
	ds_read_b128 v[176:179], v146 offset:17408
	ds_read_b128 v[180:183], v146 offset:18432
	ds_read_b128 v[186:189], v146 offset:19456
	ds_read_b128 v[190:193], v146 offset:20480
	ds_read_b128 v[194:197], v146 offset:21504
	ds_read_b128 v[198:201], v146 offset:22528
	ds_read_b128 v[202:205], v146 offset:23552
	global_load_lds_dwordx4 v[226:227], off
	v_lshl_add_u64 v[226:227], v[154:155], 0, s[20:21]
	s_mov_b32 m0, s51
	s_nop 0
	global_load_lds_dwordx4 v[226:227], off
	s_barrier
	s_waitcnt lgkmcnt(0)
	s_waitcnt lgkmcnt(0)
	v_mfma_f32_16x16x32_bf16 v[62:65], v[150:153], v[172:175], v[62:65]
	v_mfma_f32_16x16x32_bf16 v[58:61], v[164:167], v[172:175], v[58:61]
	v_mfma_f32_16x16x32_bf16 v[54:57], v[150:153], v[180:183], v[54:57]
	v_mfma_f32_16x16x32_bf16 v[50:53], v[164:167], v[180:183], v[50:53]
	v_mfma_f32_16x16x32_bf16 v[46:49], v[150:153], v[190:193], v[46:49]
	v_mfma_f32_16x16x32_bf16 v[42:45], v[164:167], v[190:193], v[42:45]
	v_mfma_f32_16x16x32_bf16 v[38:41], v[150:153], v[198:201], v[38:41]
	v_mfma_f32_16x16x32_bf16 v[34:37], v[164:167], v[198:201], v[34:37]
	v_mfma_f32_16x16x32_bf16 v[62:65], v[160:163], v[176:179], v[62:65]
	v_mfma_f32_16x16x32_bf16 v[58:61], v[168:171], v[176:179], v[58:61]
	v_mfma_f32_16x16x32_bf16 v[54:57], v[160:163], v[186:189], v[54:57]
	v_mfma_f32_16x16x32_bf16 v[50:53], v[168:171], v[186:189], v[50:53]
	v_mfma_f32_16x16x32_bf16 v[46:49], v[160:163], v[194:197], v[46:49]
	v_mfma_f32_16x16x32_bf16 v[42:45], v[168:171], v[194:197], v[42:45]
	v_mfma_f32_16x16x32_bf16 v[38:41], v[160:163], v[202:205], v[38:41]
	v_mfma_f32_16x16x32_bf16 v[34:37], v[168:171], v[202:205], v[34:37]
	s_barrier
	s_add_i32 s41, s56, s49
	v_lshl_add_u64 v[150:151], v[222:223], 0, s[22:23]
	s_mov_b32 m0, s41
	s_nop 0
	global_load_lds_dwordx4 v[150:151], off
	v_lshl_add_u64 v[150:151], v[224:225], 0, s[22:23]
	s_add_i32 m0, s41, 0x2000
	s_nop 0
	global_load_lds_dwordx4 v[150:151], off
	s_waitcnt vmcnt(6)
	s_barrier
	v_mfma_f32_16x16x32_bf16 v[30:33], v[206:209], v[172:175], v[30:33]
	v_mfma_f32_16x16x32_bf16 v[26:29], v[214:217], v[172:175], v[26:29]
	v_mfma_f32_16x16x32_bf16 v[22:25], v[206:209], v[180:183], v[22:25]
	v_mfma_f32_16x16x32_bf16 v[18:21], v[214:217], v[180:183], v[18:21]
	v_mfma_f32_16x16x32_bf16 v[14:17], v[206:209], v[190:193], v[14:17]
	v_mfma_f32_16x16x32_bf16 v[10:13], v[214:217], v[190:193], v[10:13]
	v_mfma_f32_16x16x32_bf16 v[6:9], v[206:209], v[198:201], v[6:9]
	v_mfma_f32_16x16x32_bf16 v[2:5], v[214:217], v[198:201], v[2:5]
	v_mfma_f32_16x16x32_bf16 v[30:33], v[210:213], v[176:179], v[30:33]
	v_mfma_f32_16x16x32_bf16 v[26:29], v[218:221], v[176:179], v[26:29]
	v_mfma_f32_16x16x32_bf16 v[22:25], v[210:213], v[186:189], v[22:25]
	v_mfma_f32_16x16x32_bf16 v[18:21], v[218:221], v[186:189], v[18:21]
	v_mfma_f32_16x16x32_bf16 v[14:17], v[210:213], v[194:197], v[14:17]
	v_mfma_f32_16x16x32_bf16 v[10:13], v[218:221], v[194:197], v[10:13]
	v_mfma_f32_16x16x32_bf16 v[6:9], v[210:213], v[202:205], v[6:9]
	v_mfma_f32_16x16x32_bf16 v[2:5], v[218:221], v[202:205], v[2:5]
	s_add_i32 s41, 0, 0x18000
	v_add_u32_e32 v143, s41, v142
	s_barrier
	ds_read_b128 v[150:153], v143
	ds_read_b128 v[160:163], v143 offset:1024
	ds_read_b128 v[164:167], v143 offset:2048
	ds_read_b128 v[168:171], v143 offset:3072
	s_mov_b32 m0, s52
	v_lshl_add_u64 v[206:207], v[144:145], 0, s[24:25]
	ds_read_b128 v[172:175], v146 offset:32768
	ds_read_b128 v[176:179], v146 offset:33792
	ds_read_b128 v[180:183], v146 offset:34816
	ds_read_b128 v[186:189], v146 offset:35840
	ds_read_b128 v[190:193], v146 offset:36864
	ds_read_b128 v[194:197], v146 offset:37888
	ds_read_b128 v[198:201], v146 offset:38912
	ds_read_b128 v[202:205], v146 offset:39936
	global_load_lds_dwordx4 v[206:207], off
	v_lshl_add_u64 v[206:207], v[154:155], 0, s[24:25]
	s_mov_b32 m0, s53
	s_nop 0
	global_load_lds_dwordx4 v[206:207], off
	s_waitcnt lgkmcnt(8)
	s_barrier
	s_waitcnt lgkmcnt(0)
	s_waitcnt lgkmcnt(0)
	v_mfma_f32_16x16x32_bf16 v[126:129], v[150:153], v[172:175], v[126:129]
	v_mfma_f32_16x16x32_bf16 v[122:125], v[164:167], v[172:175], v[122:125]
	v_mfma_f32_16x16x32_bf16 v[118:121], v[150:153], v[180:183], v[118:121]
	v_mfma_f32_16x16x32_bf16 v[114:117], v[164:167], v[180:183], v[114:117]
	v_mfma_f32_16x16x32_bf16 v[110:113], v[150:153], v[190:193], v[110:113]
	v_mfma_f32_16x16x32_bf16 v[106:109], v[164:167], v[190:193], v[106:109]
	v_mfma_f32_16x16x32_bf16 v[102:105], v[150:153], v[198:201], v[102:105]
	v_mfma_f32_16x16x32_bf16 v[98:101], v[164:167], v[198:201], v[98:101]
	v_mfma_f32_16x16x32_bf16 v[126:129], v[160:163], v[176:179], v[126:129]
	v_mfma_f32_16x16x32_bf16 v[122:125], v[168:171], v[176:179], v[122:125]
	v_mfma_f32_16x16x32_bf16 v[118:121], v[160:163], v[186:189], v[118:121]
	v_mfma_f32_16x16x32_bf16 v[114:117], v[168:171], v[186:189], v[114:117]
	v_mfma_f32_16x16x32_bf16 v[110:113], v[160:163], v[194:197], v[110:113]
	v_mfma_f32_16x16x32_bf16 v[106:109], v[168:171], v[194:197], v[106:109]
	v_mfma_f32_16x16x32_bf16 v[102:105], v[160:163], v[202:205], v[102:105]
	v_mfma_f32_16x16x32_bf16 v[98:101], v[168:171], v[202:205], v[98:101]
	s_barrier
	s_add_i32 s56, 0, 0x1c000
	s_add_i32 s41, s41, s49
	v_add_u32_e32 v143, s56, v142
	v_lshl_add_u64 v[226:227], v[222:223], 0, s[26:27]
	s_mov_b32 m0, s41
	ds_read_b128 v[206:209], v143
	ds_read_b128 v[210:213], v143 offset:1024
	ds_read_b128 v[214:217], v143 offset:2048
	ds_read_b128 v[218:221], v143 offset:3072
	global_load_lds_dwordx4 v[226:227], off
	v_lshl_add_u64 v[226:227], v[224:225], 0, s[26:27]
	s_add_i32 m0, s41, 0x2000
	s_nop 0
	global_load_lds_dwordx4 v[226:227], off
	s_barrier
	s_waitcnt lgkmcnt(0)
	s_waitcnt lgkmcnt(0)
	v_mfma_f32_16x16x32_bf16 v[94:97], v[206:209], v[172:175], v[94:97]
	v_mfma_f32_16x16x32_bf16 v[90:93], v[214:217], v[172:175], v[90:93]
	v_mfma_f32_16x16x32_bf16 v[86:89], v[206:209], v[180:183], v[86:89]
	v_mfma_f32_16x16x32_bf16 v[82:85], v[214:217], v[180:183], v[82:85]
	v_mfma_f32_16x16x32_bf16 v[78:81], v[206:209], v[190:193], v[78:81]
	v_mfma_f32_16x16x32_bf16 v[74:77], v[214:217], v[190:193], v[74:77]
	v_mfma_f32_16x16x32_bf16 v[70:73], v[206:209], v[198:201], v[70:73]
	v_mfma_f32_16x16x32_bf16 v[66:69], v[214:217], v[198:201], v[66:69]
	v_mfma_f32_16x16x32_bf16 v[94:97], v[210:213], v[176:179], v[94:97]
	v_mfma_f32_16x16x32_bf16 v[90:93], v[218:221], v[176:179], v[90:93]
	v_mfma_f32_16x16x32_bf16 v[86:89], v[210:213], v[186:189], v[86:89]
	v_mfma_f32_16x16x32_bf16 v[82:85], v[218:221], v[186:189], v[82:85]
	v_mfma_f32_16x16x32_bf16 v[78:81], v[210:213], v[194:197], v[78:81]
	v_mfma_f32_16x16x32_bf16 v[74:77], v[218:221], v[194:197], v[74:77]
	v_mfma_f32_16x16x32_bf16 v[70:73], v[210:213], v[202:205], v[70:73]
	v_mfma_f32_16x16x32_bf16 v[66:69], v[218:221], v[202:205], v[66:69]
	s_mov_b32 m0, s54
	v_lshl_add_u64 v[144:145], v[144:145], 0, s[28:29]
	s_barrier
	ds_read_b128 v[172:175], v146 offset:49152
	ds_read_b128 v[176:179], v146 offset:50176
	ds_read_b128 v[180:183], v146 offset:51200
	ds_read_b128 v[186:189], v146 offset:52224
	ds_read_b128 v[190:193], v146 offset:53248
	ds_read_b128 v[194:197], v146 offset:54272
	ds_read_b128 v[198:201], v146 offset:55296
	ds_read_b128 v[202:205], v146 offset:56320
	global_load_lds_dwordx4 v[144:145], off
	v_lshl_add_u64 v[144:145], v[154:155], 0, s[28:29]
	s_mov_b32 m0, s55
	s_nop 0
	global_load_lds_dwordx4 v[144:145], off
	s_barrier
	s_waitcnt lgkmcnt(0)
	s_waitcnt lgkmcnt(0)
	v_mfma_f32_16x16x32_bf16 v[62:65], v[150:153], v[172:175], v[62:65]
	v_mfma_f32_16x16x32_bf16 v[58:61], v[164:167], v[172:175], v[58:61]
	v_mfma_f32_16x16x32_bf16 v[54:57], v[150:153], v[180:183], v[54:57]
	v_mfma_f32_16x16x32_bf16 v[50:53], v[164:167], v[180:183], v[50:53]
	v_mfma_f32_16x16x32_bf16 v[46:49], v[150:153], v[190:193], v[46:49]
	v_mfma_f32_16x16x32_bf16 v[42:45], v[164:167], v[190:193], v[42:45]
	v_mfma_f32_16x16x32_bf16 v[38:41], v[150:153], v[198:201], v[38:41]
	v_mfma_f32_16x16x32_bf16 v[34:37], v[164:167], v[198:201], v[34:37]
	v_mfma_f32_16x16x32_bf16 v[62:65], v[160:163], v[176:179], v[62:65]
	v_mfma_f32_16x16x32_bf16 v[58:61], v[168:171], v[176:179], v[58:61]
	v_mfma_f32_16x16x32_bf16 v[54:57], v[160:163], v[186:189], v[54:57]
	v_mfma_f32_16x16x32_bf16 v[50:53], v[168:171], v[186:189], v[50:53]
	v_mfma_f32_16x16x32_bf16 v[46:49], v[160:163], v[194:197], v[46:49]
	v_mfma_f32_16x16x32_bf16 v[42:45], v[168:171], v[194:197], v[42:45]
	v_mfma_f32_16x16x32_bf16 v[38:41], v[160:163], v[202:205], v[38:41]
	v_mfma_f32_16x16x32_bf16 v[34:37], v[168:171], v[202:205], v[34:37]
	s_barrier
	s_add_i32 s41, s56, s49
	v_lshl_add_u64 v[144:145], v[222:223], 0, s[30:31]
	s_mov_b32 m0, s41
	s_nop 0
	global_load_lds_dwordx4 v[144:145], off
	v_lshl_add_u64 v[144:145], v[224:225], 0, s[30:31]
	s_add_i32 m0, s41, 0x2000
	s_nop 0
	global_load_lds_dwordx4 v[144:145], off
	s_waitcnt vmcnt(6)
	s_barrier
	v_mfma_f32_16x16x32_bf16 v[30:33], v[206:209], v[172:175], v[30:33]
	v_mfma_f32_16x16x32_bf16 v[26:29], v[214:217], v[172:175], v[26:29]
	v_mfma_f32_16x16x32_bf16 v[22:25], v[206:209], v[180:183], v[22:25]
	v_mfma_f32_16x16x32_bf16 v[18:21], v[214:217], v[180:183], v[18:21]
	v_mfma_f32_16x16x32_bf16 v[14:17], v[206:209], v[190:193], v[14:17]
	v_mfma_f32_16x16x32_bf16 v[10:13], v[214:217], v[190:193], v[10:13]
	v_mfma_f32_16x16x32_bf16 v[6:9], v[206:209], v[198:201], v[6:9]
	v_mfma_f32_16x16x32_bf16 v[2:5], v[214:217], v[198:201], v[2:5]
	v_mfma_f32_16x16x32_bf16 v[30:33], v[210:213], v[176:179], v[30:33]
	v_mfma_f32_16x16x32_bf16 v[26:29], v[218:221], v[176:179], v[26:29]
	v_mfma_f32_16x16x32_bf16 v[22:25], v[210:213], v[186:189], v[22:25]
	v_mfma_f32_16x16x32_bf16 v[18:21], v[218:221], v[186:189], v[18:21]
	v_mfma_f32_16x16x32_bf16 v[14:17], v[210:213], v[194:197], v[14:17]
	v_mfma_f32_16x16x32_bf16 v[10:13], v[218:221], v[194:197], v[10:13]
	v_mfma_f32_16x16x32_bf16 v[6:9], v[210:213], v[202:205], v[6:9]
	v_mfma_f32_16x16x32_bf16 v[2:5], v[218:221], v[202:205], v[2:5]
	s_add_i32 s38, s38, 2
	s_add_u32 s36, s36, 0x100
	s_addc_u32 s37, s37, 0
	s_cmp_gt_u32 s38, 27
	s_barrier
	s_cbranch_scc0 .LBB0_617
	s_add_u32 s4, s4, 0x120f80
	v_add_u32_e32 v149, 0, v142
	s_addc_u32 s5, s5, 0
	s_mov_b32 m0, s40
	v_add_u32_e32 v150, 0x10000, v149
	v_lshl_add_u64 v[130:131], s[4:5], 0, v[130:131]
	ds_read_b128 v[134:137], v150
	ds_read_b128 v[138:141], v150 offset:1024
	ds_read_b128 v[142:145], v150 offset:2048
	ds_read_b128 v[150:153], v150 offset:3072
	ds_read_b128 v[160:163], v146
	ds_read_b128 v[164:167], v146 offset:1024
	ds_read_b128 v[168:171], v146 offset:2048
	ds_read_b128 v[172:175], v146 offset:3072
	ds_read_b128 v[176:179], v146 offset:4096
	ds_read_b128 v[180:183], v146 offset:5120
	ds_read_b128 v[186:189], v146 offset:6144
	ds_read_b128 v[190:193], v146 offset:7168
	global_load_lds_dwordx4 v[130:131], off
	v_lshl_add_u64 v[130:131], s[4:5], 0, v[132:133]
	s_mov_b32 m0, s39
	s_nop 0
	global_load_lds_dwordx4 v[130:131], off
	s_barrier
	s_waitcnt lgkmcnt(0)
	s_waitcnt lgkmcnt(0)
	v_mfma_f32_16x16x32_bf16 v[126:129], v[134:137], v[160:163], v[126:129]
	v_mfma_f32_16x16x32_bf16 v[122:125], v[142:145], v[160:163], v[122:125]
	v_mfma_f32_16x16x32_bf16 v[102:105], v[134:137], v[186:189], v[102:105]
	v_mfma_f32_16x16x32_bf16 v[98:101], v[142:145], v[186:189], v[98:101]
	v_mfma_f32_16x16x32_bf16 v[126:129], v[138:141], v[164:167], v[126:129]
	v_mfma_f32_16x16x32_bf16 v[122:125], v[150:153], v[164:167], v[122:125]
	v_mfma_f32_16x16x32_bf16 v[118:121], v[134:137], v[168:171], v[118:121]
	v_mfma_f32_16x16x32_bf16 v[114:117], v[142:145], v[168:171], v[114:117]
	v_mfma_f32_16x16x32_bf16 v[110:113], v[134:137], v[176:179], v[110:113]
	v_mfma_f32_16x16x32_bf16 v[106:109], v[142:145], v[176:179], v[106:109]
	v_mfma_f32_16x16x32_bf16 v[102:105], v[138:141], v[190:193], v[102:105]
	v_mfma_f32_16x16x32_bf16 v[98:101], v[150:153], v[190:193], v[98:101]
	v_mfma_f32_16x16x32_bf16 v[118:121], v[138:141], v[172:175], v[118:121]
	v_mfma_f32_16x16x32_bf16 v[114:117], v[150:153], v[172:175], v[114:117]
	v_mfma_f32_16x16x32_bf16 v[130:133], v[138:141], v[180:183], v[110:113]
	v_mfma_f32_16x16x32_bf16 v[194:197], v[150:153], v[180:183], v[106:109]
	v_add_u32_e32 v154, 0x14000, v149
	s_barrier
	ds_read_b128 v[106:109], v154
	ds_read_b128 v[110:113], v154 offset:1024
	ds_read_b128 v[198:201], v154 offset:2048
	ds_read_b128 v[202:205], v154 offset:3072
	s_barrier
	s_waitcnt lgkmcnt(0)
	s_waitcnt lgkmcnt(0)
	v_mfma_f32_16x16x32_bf16 v[86:89], v[106:109], v[168:171], v[86:89]
	v_mfma_f32_16x16x32_bf16 v[82:85], v[198:201], v[168:171], v[82:85]
	v_mfma_f32_16x16x32_bf16 v[70:73], v[106:109], v[186:189], v[70:73]
	v_mfma_f32_16x16x32_bf16 v[66:69], v[198:201], v[186:189], v[66:69]
	v_mfma_f32_16x16x32_bf16 v[94:97], v[106:109], v[160:163], v[94:97]
	v_mfma_f32_16x16x32_bf16 v[90:93], v[198:201], v[160:163], v[90:93]
	v_mfma_f32_16x16x32_bf16 v[86:89], v[110:113], v[172:175], v[86:89]
	v_mfma_f32_16x16x32_bf16 v[82:85], v[202:205], v[172:175], v[82:85]
	v_mfma_f32_16x16x32_bf16 v[78:81], v[106:109], v[176:179], v[78:81]
	v_mfma_f32_16x16x32_bf16 v[74:77], v[198:201], v[176:179], v[74:77]
	v_mfma_f32_16x16x32_bf16 v[70:73], v[110:113], v[190:193], v[70:73]
	v_mfma_f32_16x16x32_bf16 v[66:69], v[202:205], v[190:193], v[66:69]
	v_mfma_f32_16x16x32_bf16 v[206:209], v[110:113], v[164:167], v[94:97]
	v_mfma_f32_16x16x32_bf16 v[160:163], v[202:205], v[164:167], v[90:93]
	v_mfma_f32_16x16x32_bf16 v[164:167], v[110:113], v[180:183], v[78:81]
	v_mfma_f32_16x16x32_bf16 v[168:171], v[202:205], v[180:183], v[74:77]
	s_barrier
	s_nop 0
	ds_read_b128 v[74:77], v146 offset:16384
	ds_read_b128 v[78:81], v146 offset:17408
	ds_read_b128 v[90:93], v146 offset:18432
	ds_read_b128 v[94:97], v146 offset:19456
	ds_read_b128 v[172:175], v146 offset:20480
	ds_read_b128 v[176:179], v146 offset:21504
	ds_read_b128 v[180:183], v146 offset:22528
	ds_read_b128 v[186:189], v146 offset:23552
	s_waitcnt vmcnt(4)
	s_barrier
	s_waitcnt lgkmcnt(0)
	s_waitcnt lgkmcnt(0)
	v_mfma_f32_16x16x32_bf16 v[62:65], v[134:137], v[74:77], v[62:65]
	v_mfma_f32_16x16x32_bf16 v[58:61], v[142:145], v[74:77], v[58:61]
	v_mfma_f32_16x16x32_bf16 v[54:57], v[134:137], v[90:93], v[54:57]
	v_mfma_f32_16x16x32_bf16 v[50:53], v[142:145], v[90:93], v[50:53]
	v_mfma_f32_16x16x32_bf16 v[38:41], v[134:137], v[180:183], v[38:41]
	v_mfma_f32_16x16x32_bf16 v[34:37], v[142:145], v[180:183], v[34:37]
	v_mfma_f32_16x16x32_bf16 v[62:65], v[138:141], v[78:81], v[62:65]
	v_mfma_f32_16x16x32_bf16 v[58:61], v[150:153], v[78:81], v[58:61]
	v_mfma_f32_16x16x32_bf16 v[54:57], v[138:141], v[94:97], v[54:57]
	v_mfma_f32_16x16x32_bf16 v[50:53], v[150:153], v[94:97], v[50:53]
	v_mfma_f32_16x16x32_bf16 v[46:49], v[134:137], v[172:175], v[46:49]
	v_mfma_f32_16x16x32_bf16 v[42:45], v[142:145], v[172:175], v[42:45]
	v_mfma_f32_16x16x32_bf16 v[38:41], v[138:141], v[186:189], v[38:41]
	v_mfma_f32_16x16x32_bf16 v[34:37], v[150:153], v[186:189], v[34:37]
	v_mfma_f32_16x16x32_bf16 v[190:193], v[138:141], v[176:179], v[46:49]
	v_mfma_f32_16x16x32_bf16 v[210:213], v[150:153], v[176:179], v[42:45]
	v_mfma_f32_16x16x32_bf16 v[22:25], v[106:109], v[90:93], v[22:25]
	v_mfma_f32_16x16x32_bf16 v[18:21], v[198:201], v[90:93], v[18:21]
	v_mfma_f32_16x16x32_bf16 v[6:9], v[106:109], v[180:183], v[6:9]
	v_mfma_f32_16x16x32_bf16 v[2:5], v[198:201], v[180:183], v[2:5]
	v_mfma_f32_16x16x32_bf16 v[30:33], v[106:109], v[74:77], v[30:33]
	v_mfma_f32_16x16x32_bf16 v[26:29], v[198:201], v[74:77], v[26:29]
	v_mfma_f32_16x16x32_bf16 v[22:25], v[110:113], v[94:97], v[22:25]
	v_mfma_f32_16x16x32_bf16 v[18:21], v[202:205], v[94:97], v[18:21]
	v_mfma_f32_16x16x32_bf16 v[14:17], v[106:109], v[172:175], v[14:17]
	v_mfma_f32_16x16x32_bf16 v[10:13], v[198:201], v[172:175], v[10:13]
	v_mfma_f32_16x16x32_bf16 v[6:9], v[110:113], v[186:189], v[6:9]
	v_mfma_f32_16x16x32_bf16 v[2:5], v[202:205], v[186:189], v[2:5]
	v_mfma_f32_16x16x32_bf16 v[138:141], v[110:113], v[78:81], v[30:33]
	v_mfma_f32_16x16x32_bf16 v[150:153], v[202:205], v[78:81], v[26:29]
	v_mfma_f32_16x16x32_bf16 v[214:217], v[110:113], v[176:179], v[14:17]
	v_mfma_f32_16x16x32_bf16 v[172:175], v[202:205], v[176:179], v[10:13]
	v_add_u32_e32 v26, 0x18000, v149
	s_barrier
	ds_read_b128 v[10:13], v26
	ds_read_b128 v[14:17], v26 offset:1024
	ds_read_b128 v[176:179], v26 offset:2048
	ds_read_b128 v[180:183], v26 offset:3072
	ds_read_b128 v[26:29], v146 offset:32768
	ds_read_b128 v[30:33], v146 offset:33792
	ds_read_b128 v[42:45], v146 offset:34816
	ds_read_b128 v[46:49], v146 offset:35840
	ds_read_b128 v[186:189], v146 offset:36864
	ds_read_b128 v[198:201], v146 offset:37888
	ds_read_b128 v[202:205], v146 offset:38912
	ds_read_b128 v[218:221], v146 offset:39936
	s_waitcnt vmcnt(2)
	s_barrier
	s_waitcnt lgkmcnt(0)
	s_waitcnt lgkmcnt(0)
	v_mfma_f32_16x16x32_bf16 v[74:77], v[10:13], v[26:29], v[126:129]
	v_mfma_f32_16x16x32_bf16 v[142:145], v[14:17], v[30:33], v[74:77]
	v_mfma_f32_16x16x32_bf16 v[74:77], v[176:179], v[26:29], v[122:125]
	v_mfma_f32_16x16x32_bf16 v[134:137], v[180:183], v[30:33], v[74:77]
	v_mfma_f32_16x16x32_bf16 v[74:77], v[10:13], v[42:45], v[118:121]
	v_mfma_f32_16x16x32_bf16 v[110:113], v[14:17], v[46:49], v[74:77]
	v_mfma_f32_16x16x32_bf16 v[74:77], v[176:179], v[42:45], v[114:117]
	v_mfma_f32_16x16x32_bf16 v[106:109], v[180:183], v[46:49], v[74:77]
	v_mfma_f32_16x16x32_bf16 v[74:77], v[10:13], v[186:189], v[130:133]
	v_mfma_f32_16x16x32_bf16 v[94:97], v[14:17], v[198:201], v[74:77]
	v_mfma_f32_16x16x32_bf16 v[74:77], v[176:179], v[186:189], v[194:197]
	v_mfma_f32_16x16x32_bf16 v[90:93], v[180:183], v[198:201], v[74:77]
	v_mfma_f32_16x16x32_bf16 v[74:77], v[10:13], v[202:205], v[102:105]
	v_mfma_f32_16x16x32_bf16 v[78:81], v[14:17], v[218:221], v[74:77]
	v_mfma_f32_16x16x32_bf16 v[74:77], v[176:179], v[202:205], v[98:101]
	v_mfma_f32_16x16x32_bf16 v[74:77], v[180:183], v[218:221], v[74:77]
	s_nop 0
	v_add_u32_e32 v98, 0x1c000, v149
	s_barrier
	ds_read_b128 v[114:117], v98
	ds_read_b128 v[118:121], v98 offset:1024
	ds_read_b128 v[130:133], v98 offset:2048
	ds_read_b128 v[194:197], v98 offset:3072
	s_waitcnt vmcnt(0)
	s_barrier
	s_waitcnt lgkmcnt(0)
	s_waitcnt lgkmcnt(0)
	v_mfma_f32_16x16x32_bf16 v[98:101], v[114:117], v[26:29], v[206:209]
	v_mfma_f32_16x16x32_bf16 v[26:29], v[130:133], v[26:29], v[160:163]
	v_mfma_f32_16x16x32_bf16 v[122:125], v[194:197], v[30:33], v[26:29]
	v_mfma_f32_16x16x32_bf16 v[26:29], v[114:117], v[42:45], v[86:89]
	v_mfma_f32_16x16x32_bf16 v[102:105], v[118:121], v[46:49], v[26:29]
	v_mfma_f32_16x16x32_bf16 v[26:29], v[130:133], v[42:45], v[82:85]
	v_mfma_f32_16x16x32_bf16 v[126:129], v[118:121], v[30:33], v[98:101]
	v_mfma_f32_16x16x32_bf16 v[98:101], v[194:197], v[46:49], v[26:29]
	v_mfma_f32_16x16x32_bf16 v[26:29], v[114:117], v[186:189], v[164:167]
	v_mfma_f32_16x16x32_bf16 v[86:89], v[118:121], v[198:201], v[26:29]
	v_mfma_f32_16x16x32_bf16 v[26:29], v[130:133], v[186:189], v[168:171]
	v_mfma_f32_16x16x32_bf16 v[82:85], v[194:197], v[198:201], v[26:29]
	v_mfma_f32_16x16x32_bf16 v[26:29], v[114:117], v[202:205], v[70:73]
	v_mfma_f32_16x16x32_bf16 v[70:73], v[118:121], v[218:221], v[26:29]
	v_mfma_f32_16x16x32_bf16 v[26:29], v[130:133], v[202:205], v[66:69]
	v_mfma_f32_16x16x32_bf16 v[66:69], v[194:197], v[218:221], v[26:29]
	s_barrier
	ds_read_b128 v[160:163], v146 offset:49152
	ds_read_b128 v[164:167], v146 offset:50176
	ds_read_b128 v[168:171], v146 offset:51200
	ds_read_b128 v[186:189], v146 offset:52224
	ds_read_b128 v[198:201], v146 offset:53248
	ds_read_b128 v[202:205], v146 offset:54272
	ds_read_b128 v[206:209], v146 offset:55296
	ds_read_b128 v[218:221], v146 offset:56320
	s_barrier
	s_waitcnt lgkmcnt(0)
	s_waitcnt lgkmcnt(0)
	v_mfma_f32_16x16x32_bf16 v[26:29], v[10:13], v[160:163], v[62:65]
	v_mfma_f32_16x16x32_bf16 v[62:65], v[14:17], v[164:167], v[26:29]
	v_mfma_f32_16x16x32_bf16 v[26:29], v[176:179], v[160:163], v[58:61]
	v_mfma_f32_16x16x32_bf16 v[58:61], v[180:183], v[164:167], v[26:29]
	v_mfma_f32_16x16x32_bf16 v[26:29], v[10:13], v[168:171], v[54:57]
	v_mfma_f32_16x16x32_bf16 v[46:49], v[14:17], v[186:189], v[26:29]
	v_mfma_f32_16x16x32_bf16 v[26:29], v[176:179], v[168:171], v[50:53]
	v_mfma_f32_16x16x32_bf16 v[42:45], v[180:183], v[186:189], v[26:29]
	v_mfma_f32_16x16x32_bf16 v[26:29], v[10:13], v[198:201], v[190:193]
	v_mfma_f32_16x16x32_bf16 v[10:13], v[10:13], v[206:209], v[38:41]
	v_mfma_f32_16x16x32_bf16 v[30:33], v[14:17], v[202:205], v[26:29]
	v_mfma_f32_16x16x32_bf16 v[26:29], v[176:179], v[198:201], v[210:213]
	v_mfma_f32_16x16x32_bf16 v[14:17], v[14:17], v[218:221], v[10:13]
	v_mfma_f32_16x16x32_bf16 v[10:13], v[176:179], v[206:209], v[34:37]
	v_mfma_f32_16x16x32_bf16 v[26:29], v[180:183], v[202:205], v[26:29]
	v_mfma_f32_16x16x32_bf16 v[10:13], v[180:183], v[218:221], v[10:13]
	v_mfma_f32_16x16x32_bf16 v[34:37], v[114:117], v[160:163], v[138:141]
	v_mfma_f32_16x16x32_bf16 v[54:57], v[118:121], v[164:167], v[34:37]
	v_mfma_f32_16x16x32_bf16 v[34:37], v[130:133], v[160:163], v[150:153]
	v_mfma_f32_16x16x32_bf16 v[18:21], v[130:133], v[168:171], v[18:21]
	v_mfma_f32_16x16x32_bf16 v[50:53], v[194:197], v[164:167], v[34:37]
	v_mfma_f32_16x16x32_bf16 v[22:25], v[114:117], v[168:171], v[22:25]
	v_mfma_f32_16x16x32_bf16 v[34:37], v[194:197], v[186:189], v[18:21]
	v_mfma_f32_16x16x32_bf16 v[18:21], v[114:117], v[198:201], v[214:217]
	v_mfma_f32_16x16x32_bf16 v[38:41], v[118:121], v[186:189], v[22:25]
	v_mfma_f32_16x16x32_bf16 v[22:25], v[118:121], v[202:205], v[18:21]
	v_mfma_f32_16x16x32_bf16 v[18:21], v[130:133], v[198:201], v[172:175]
	v_mfma_f32_16x16x32_bf16 v[6:9], v[114:117], v[206:209], v[6:9]
	v_mfma_f32_16x16x32_bf16 v[2:5], v[130:133], v[206:209], v[2:5]
	v_mfma_f32_16x16x32_bf16 v[18:21], v[194:197], v[202:205], v[18:21]
	v_mfma_f32_16x16x32_bf16 v[6:9], v[118:121], v[218:221], v[6:9]
	v_mfma_f32_16x16x32_bf16 v[2:5], v[194:197], v[218:221], v[2:5]
	s_cmpk_lt_u32 s48, 0x100
	s_barrier
	s_cbranch_scc0 .LBB0_620
	s_barrier
.LBB0_620:
	s_setprio 0
	v_readlane_b32 s80, v242, 21
	v_lshlrev_b32_e32 v114, 3, v158
	v_or_b32_e32 v115, s47, v148
	v_readlane_b32 s81, v242, 22
	v_add_u32_e32 v150, s35, v115
	v_lshl_or_b32 v114, s12, 5, v114
	v_readlane_b32 s82, v242, 23
	v_readlane_b32 s83, v242, 24
	s_mov_b64 s[36:37], s[80:81]
	v_or_b32_e32 v148, s34, v114
	v_add_u32_e32 v114, 0xffffc000, v150
	v_ashrrev_i32_e32 v151, 31, v150
	v_cmp_gt_i32_e32 vcc, s45, v150
	s_mov_b64 s[38:39], s[82:83]
	v_mov_b32_e32 v118, s39
	v_cndmask_b32_e32 v115, 0, v151, vcc
	v_cndmask_b32_e32 v114, v114, v150, vcc
	v_mov_b32_e32 v119, s37
	v_mov_b32_e32 v120, s38
	v_mov_b32_e32 v121, s36
	v_ashrrev_i32_e32 v149, 31, v148
	v_cndmask_b32_e32 v117, v118, v119, vcc
	v_cndmask_b32_e32 v116, v120, v121, vcc
	v_lshlrev_b64 v[114:115], 12, v[114:115]
	v_lshl_add_u64 v[114:115], v[116:117], 0, v[114:115]
	v_lshlrev_b64 v[152:153], 2, v[148:149]
	v_lshl_add_u64 v[114:115], v[114:115], 0, v[152:153]
	global_load_dwordx4 v[160:163], v[114:115], off
	global_load_dwordx4 v[164:167], v[114:115], off offset:16
	global_load_dwordx4 v[168:171], v[114:115], off offset:512
	global_load_dwordx4 v[172:175], v[114:115], off offset:528
	v_or_b32_e32 v154, 16, v150
	v_add_u32_e32 v114, 0xffffc010, v150
	v_ashrrev_i32_e32 v155, 31, v154
	v_cmp_gt_i32_e32 vcc, s45, v154
	v_readlane_b32 s84, v242, 25
	v_readlane_b32 s85, v242, 26
	v_cndmask_b32_e32 v115, 0, v155, vcc
	v_cndmask_b32_e32 v114, v114, v154, vcc
	v_cndmask_b32_e32 v117, v118, v119, vcc
	v_cndmask_b32_e32 v116, v120, v121, vcc
	v_lshlrev_b64 v[114:115], 12, v[114:115]
	v_lshl_add_u64 v[114:115], v[116:117], 0, v[114:115]
	v_lshl_add_u64 v[118:119], v[114:115], 0, v[152:153]
	global_load_dwordx4 v[130:133], v[118:119], off offset:16
	global_load_dwordx4 v[138:141], v[118:119], off
	global_load_dwordx4 v[114:117], v[118:119], off offset:528
	s_nop 0
	global_load_dwordx4 v[118:121], v[118:119], off offset:512
	v_cmp_eq_u32_e32 vcc, 0, v158
	v_readlane_b32 s86, v242, 27
	v_readlane_b32 s87, v242, 28
	v_readlane_b32 s88, v242, 29
	v_readlane_b32 s89, v242, 30
	v_readlane_b32 s90, v242, 31
	v_readlane_b32 s91, v242, 32
	v_readlane_b32 s92, v242, 33
	v_readlane_b32 s93, v242, 34
	v_readlane_b32 s94, v242, 35
	v_readlane_b32 s95, v242, 36
	s_waitcnt vmcnt(0)
	v_pk_add_f32 v[144:145], v[144:145], v[162:163]
	v_pk_add_f32 v[142:143], v[142:143], v[160:161]
	v_pk_add_f32 v[136:137], v[136:137], v[166:167]
	v_pk_add_f32 v[134:135], v[134:135], v[164:165]
	v_pk_add_f32 v[158:159], v[128:129], v[170:171]
	v_pk_add_f32 v[160:161], v[126:127], v[168:169]
	v_pk_add_f32 v[124:125], v[124:125], v[174:175]
	v_pk_add_f32 v[122:123], v[122:123], v[172:173]
	v_cvt_pk_bf16_f32 v126, v142, v143
	v_cvt_pk_bf16_f32 v127, v144, v145
	v_cvt_pk_bf16_f32 v128, v134, v135
	v_cvt_pk_bf16_f32 v129, v136, v137
	v_cvt_pk_bf16_f32 v134, v160, v161
	v_cvt_pk_bf16_f32 v135, v158, v159
	s_nop 0
	v_cvt_pk_bf16_f32 v136, v122, v123
	v_cvt_pk_bf16_f32 v137, v124, v125
	v_and_b32_e32 v123, 0xffff0000, v126
	v_and_b32_e32 v125, 0xffff0000, v127
	v_and_b32_e32 v143, 0xffff0000, v128
	v_and_b32_e32 v145, 0xffff0000, v129
	v_and_b32_e32 v158, 0xffff0000, v134
	v_and_b32_e32 v160, 0xffff0000, v135
	v_and_b32_e32 v162, 0xffff0000, v136
	v_and_b32_e32 v164, 0xffff0000, v137
	v_lshlrev_b32_e32 v122, 16, v126
	v_lshlrev_b32_e32 v124, 16, v127
	v_lshlrev_b32_e32 v142, 16, v128
	v_lshlrev_b32_e32 v144, 16, v129
	v_lshlrev_b32_e32 v146, 16, v134
	v_lshlrev_b32_e32 v159, 16, v135
	v_lshlrev_b32_e32 v161, 16, v136
	v_lshlrev_b32_e32 v163, 16, v137
	v_mul_f32_e32 v123, v123, v123
	v_mul_f32_e32 v125, v125, v125
	v_mul_f32_e32 v143, v143, v143
	v_mul_f32_e32 v145, v145, v145
	v_mul_f32_e32 v158, v158, v158
	v_mul_f32_e32 v160, v160, v160
	v_mul_f32_e32 v162, v162, v162
	v_mul_f32_e32 v164, v164, v164
	v_fmac_f32_e32 v123, v122, v122
	v_fmac_f32_e32 v125, v124, v124
	v_fmac_f32_e32 v143, v142, v142
	v_fmac_f32_e32 v145, v144, v144
	v_fmac_f32_e32 v158, v146, v146
	v_fmac_f32_e32 v160, v159, v159
	v_fmac_f32_e32 v162, v161, v161
	v_fmac_f32_e32 v164, v163, v163
	v_add_f32_e32 v122, v123, v125
	v_add_f32_e32 v123, v143, v145
	v_add_f32_e32 v124, v158, v160
	v_add_f32_e32 v125, v162, v164
	v_add_f32_e32 v122, v122, v123
	v_add_f32_e32 v123, v124, v125
	v_and_b32_e32 v124, 64, v156
	v_add_f32_e32 v123, v122, v123
	v_xor_b32_e32 v122, 16, v156
	v_add_u32_e32 v125, 64, v124
	v_cmp_lt_i32_e64 s[4:5], v122, v125
	v_lshlrev_b64 v[142:143], 11, v[150:151]
	v_lshl_add_u64 v[142:143], s[2:3], 0, v[142:143]
	v_cndmask_b32_e64 v122, v156, v122, s[4:5]
	v_lshlrev_b32_e32 v122, 2, v122
	ds_bpermute_b32 v124, v122, v123
	s_lshr_b32 s4, s34, 6
	s_and_b32 s4, s4, 12
	s_or_b32 s34, s4, s12
	v_lshl_add_u64 v[142:143], v[148:149], 1, v[142:143]
	s_waitcnt lgkmcnt(0)
	v_add_f32_e32 v124, v123, v124
	v_xor_b32_e32 v123, 32, v156
	v_cmp_lt_i32_e64 s[4:5], v123, v125
	global_store_dwordx4 v[142:143], v[126:129], off
	global_store_dwordx4 v[142:143], v[134:137], off offset:256
	v_cndmask_b32_e64 v123, v156, v123, s[4:5]
	v_lshlrev_b32_e32 v123, 2, v123
	ds_bpermute_b32 v125, v123, v124
	s_and_saveexec_b64 s[4:5], vcc
	s_cbranch_execz .LBB0_622
	v_lshlrev_b64 v[126:127], 6, v[150:151]
	v_lshl_add_u64 v[126:127], s[8:9], 0, v[126:127]
	s_lshl_b32 s12, s34, 2
	v_lshl_add_u64 v[126:127], v[126:127], 0, s[12:13]
	s_waitcnt lgkmcnt(0)
	v_add_f32_e32 v124, v124, v125
	global_store_dword v[126:127], v124, off

.LBB0_709:
	v_mov_b32_e32 v24, v0
	s_add_i32 s0, s34, s0
	v_ashrrev_i32_e32 v3, 31, v24
	v_lshrrev_b32_e32 v3, 26, v3
	v_add_u32_e32 v3, v24, v3
	v_ashrrev_i32_e32 v12, 6, v3
	v_bfe_i32 v3, v24, 27, 1
	v_lshlrev_b32_e32 v2, 4, v24
	v_lshrrev_b32_e32 v3, 22, v3
	v_add_u32_e32 v3, v2, v3
	v_and_b32_e32 v3, 0xfffffc00, v3
	v_sub_u32_e32 v3, v2, v3
	v_lshrrev_b32_e32 v4, 4, v3
	v_bitop3_b32 v4, v4, v3, 32 bitop3:0x6c
	v_ashrrev_i32_e32 v3, 31, v3
	v_lshrrev_b32_e32 v3, 26, v3
	v_add_u32_e32 v3, v4, v3
	v_ashrrev_i32_e32 v17, 6, v3
	v_lshlrev_b32_e32 v5, 3, v12
	v_mul_i32_i24_e32 v6, 64, v17
	v_and_b32_e32 v5, -16, v5
	v_sub_u32_e32 v4, v4, v6
	v_add_u32_e32 v3, v17, v5
	v_lshlrev_b32_e32 v5, 5, v12
	v_ashrrev_i16_sdwa v4, v187, sext(v4) dst_sel:DWORD dst_unused:UNUSED_PAD src0_sel:DWORD src1_sel:BYTE_0
	s_ashr_i32 s1, s0, 31
	v_and_b32_e32 v5, 32, v5
	s_waitcnt vmcnt(10)
	v_bfe_i32 v18, v4, 0, 16
	s_lshr_b32 s1, s1, 27
	v_lshlrev_b32_e32 v4, 1, v3
	v_add_lshl_u32 v5, v5, v18, 1
	v_add_u32_e32 v2, 0x2000, v2
	s_add_i32 s1, s0, s1
	v_and_b32_e32 v13, 0x1fffe0, v3
	v_and_b32_e32 v14, 24, v4
	v_lshrrev_b32_e32 v4, 2, v3
	v_lshl_add_u32 v130, v3, 11, v5
	v_ashrrev_i32_e32 v3, 31, v2
	s_and_b32 s12, s1, 0xffe0
	v_lshrrev_b32_e32 v3, 22, v3
	s_sub_i32 s0, s0, s12
	v_add_u32_e32 v3, v2, v3
	s_bfe_i32 s12, s0, 0x80000
	v_ashrrev_i32_e32 v19, 10, v3
	s_bfe_u32 s12, s12, 0x3000c
	v_mul_i32_i24_e32 v3, 0x400, v19
	s_add_i32 s12, s0, s12
	v_and_b32_e32 v16, 3, v17
	v_sub_u32_e32 v2, v2, v3
	s_bfe_i32 s34, s12, 0x80000
	s_and_b32 s12, s12, 0xf8
	v_and_b32_e32 v15, 4, v4
	v_or_b32_e32 v4, v13, v16
	v_lshrrev_b32_e32 v3, 4, v2
	s_sub_i32 s0, s0, s12
	v_or3_b32 v4, v4, v14, v15
	v_bitop3_b32 v2, v3, v2, 32 bitop3:0x6c
	s_sext_i32_i8 s0, s0
	s_lshl_b32 s1, s1, 6
	v_lshl_add_u32 v170, v4, 11, v5
	v_ashrrev_i32_e32 v4, 31, v2
	s_sext_i32_i16 s35, s34
	s_and_b32 s1, s1, 0xfffff800
	s_lshl_b32 s0, s0, 8
	v_lshrrev_b32_e32 v4, 26, v4
	s_add_i32 s34, s0, s1
	s_lshl_b32 s0, s35, 5
	v_add_u32_e32 v4, v2, v4
	s_and_b32 s0, s0, 0xffffff00
	v_readfirstlane_b32 s47, v24
	v_lshlrev_b32_e32 v3, 3, v19
	v_ashrrev_i32_e32 v25, 6, v4
	v_and_b32_e32 v4, 0xc0, v4
	s_ashr_i32 s12, s47, 6
	v_and_b32_e32 v3, -16, v3
	v_sub_u32_e32 v2, v2, v4
	s_ashr_i32 s35, s34, 31
	s_ashr_i32 s1, s0, 31
	v_add_u32_e32 v3, v25, v3
	v_ashrrev_i16_sdwa v2, v187, sext(v2) dst_sel:DWORD dst_unused:UNUSED_PAD src0_sel:DWORD src1_sel:BYTE_0
	s_ashr_i32 s52, s47, 8
	s_lshl_b32 s48, s12, 10
	s_lshl_b64 s[40:41], s[34:35], 11
	s_lshl_b64 s[38:39], s[0:1], 11
	s_waitcnt vmcnt(9)
	v_bfe_i32 v26, v2, 0, 16
	v_lshlrev_b32_e32 v2, 1, v3
	s_add_u32 s42, s33, s38
	v_lshlrev_b32_e32 v5, 5, v19
	v_and_b32_e32 v20, 0x1fffe0, v3
	v_and_b32_e32 v21, 24, v2
	v_lshrrev_b32_e32 v2, 2, v3
	v_and_b32_e32 v23, 3, v25
	s_addc_u32 s43, s44, s39
	s_add_i32 s35, s48, 0
	v_and_b32_e32 v5, 32, v5
	v_and_b32_e32 v22, 4, v2
	v_or_b32_e32 v2, v20, v23
	s_add_i32 m0, s35, 0x10000
	v_or3_b32 v2, v2, v21, v22
	v_add_lshl_u32 v4, v5, v26, 1
	global_load_lds_dwordx4 v170, s[42:43]
	s_add_i32 m0, s35, 0x12000
	v_lshl_add_u32 v2, v2, 11, v4
	s_add_u32 s36, s2, s40
	global_load_lds_dwordx4 v2, s[42:43]
	s_addc_u32 s37, s3, s41
	s_mov_b32 m0, s35
	s_add_i32 s49, s35, 0x2000
	v_lshl_add_u32 v132, v3, 11, v4
	global_load_lds_dwordx4 v130, s[36:37]
	s_mov_b32 m0, s49
	s_add_u32 s50, s42, 0x40000
	global_load_lds_dwordx4 v132, s[36:37]
	s_addc_u32 s51, s43, 0
	s_add_i32 m0, s35, 0x14000
	v_mov_b32_e32 v3, v171
	global_load_lds_dwordx4 v170, s[50:51]
	s_add_i32 m0, s35, 0x16000
	s_add_u32 s54, s36, 0x40000
	global_load_lds_dwordx4 v2, s[50:51]
	s_addc_u32 s55, s37, 0
	s_add_i32 s50, s35, 0x4000
	s_mov_b32 m0, s50
	s_add_i32 s51, s35, 0x6000
	global_load_lds_dwordx4 v130, s[54:55]
	s_mov_b32 m0, s51
	v_mov_b32_e32 v131, v171
	global_load_lds_dwordx4 v132, s[54:55]
	v_mov_b32_e32 v133, v171
	v_lshl_add_u64 v[10:11], s[42:43], 0, v[170:171]
	v_lshl_add_u64 v[8:9], s[42:43], 0, v[2:3]
	v_lshl_add_u64 v[6:7], s[36:37], 0, v[130:131]
	s_cmp_lg_u32 s52, 1
	v_lshl_add_u64 v[4:5], s[36:37], 0, v[132:133]
	s_cbranch_scc1 .LBB0_711
	s_setprio 1
	s_barrier

.LBB0_712:
	s_add_i32 s43, 0, 0x10000
	v_add_u32_e32 v158, s43, v145
	ds_read_b128 v[146:149], v158
	ds_read_b128 v[150:153], v158 offset:1024
	ds_read_b128 v[154:157], v158 offset:2048
	ds_read_b128 v[158:161], v158 offset:3072
	v_lshl_add_u64 v[216:217], s[38:39], 0, v[134:135]
	s_add_i32 s42, s35, 0xc000
	v_lshl_add_u64 v[200:201], v[216:217], 0, s[16:17]
	s_mov_b32 m0, s42
	v_lshl_add_u64 v[218:219], s[38:39], 0, v[136:137]
	s_add_i32 s41, s35, 0xe000
	ds_read_b128 v[162:165], v144
	ds_read_b128 v[166:169], v144 offset:1024
	ds_read_b128 v[172:175], v144 offset:2048
	ds_read_b128 v[176:179], v144 offset:3072
	ds_read_b128 v[180:183], v144 offset:4096
	ds_read_b128 v[188:191], v144 offset:5120
	ds_read_b128 v[192:195], v144 offset:6144
	ds_read_b128 v[196:199], v144 offset:7168
	global_load_lds_dwordx4 v[200:201], off
	v_lshl_add_u64 v[200:201], v[218:219], 0, s[16:17]
	s_mov_b32 m0, s41
	s_nop 0
	global_load_lds_dwordx4 v[200:201], off
	s_waitcnt lgkmcnt(8)
	s_barrier
	s_waitcnt lgkmcnt(0)
	s_waitcnt lgkmcnt(0)
	v_mfma_f32_16x16x32_bf16 v[126:129], v[146:149], v[162:165], v[126:129]
	v_mfma_f32_16x16x32_bf16 v[122:125], v[154:157], v[162:165], v[122:125]
	v_mfma_f32_16x16x32_bf16 v[118:121], v[146:149], v[172:175], v[118:121]
	v_mfma_f32_16x16x32_bf16 v[114:117], v[154:157], v[172:175], v[114:117]
	v_mfma_f32_16x16x32_bf16 v[110:113], v[146:149], v[180:183], v[110:113]
	v_mfma_f32_16x16x32_bf16 v[106:109], v[154:157], v[180:183], v[106:109]
	v_mfma_f32_16x16x32_bf16 v[102:105], v[146:149], v[192:195], v[102:105]
	v_mfma_f32_16x16x32_bf16 v[98:101], v[154:157], v[192:195], v[98:101]
	v_mfma_f32_16x16x32_bf16 v[126:129], v[150:153], v[166:169], v[126:129]
	v_mfma_f32_16x16x32_bf16 v[122:125], v[158:161], v[166:169], v[122:125]
	v_mfma_f32_16x16x32_bf16 v[118:121], v[150:153], v[176:179], v[118:121]
	v_mfma_f32_16x16x32_bf16 v[114:117], v[158:161], v[176:179], v[114:117]
	v_mfma_f32_16x16x32_bf16 v[110:113], v[150:153], v[188:191], v[110:113]
	v_mfma_f32_16x16x32_bf16 v[106:109], v[158:161], v[188:191], v[106:109]
	v_mfma_f32_16x16x32_bf16 v[102:105], v[150:153], v[196:199], v[102:105]
	v_mfma_f32_16x16x32_bf16 v[98:101], v[158:161], v[196:199], v[98:101]
	s_barrier
	s_add_i32 s54, 0, 0x14000
	v_lshl_add_u64 v[220:221], s[38:39], 0, v[138:139]
	s_add_i32 s43, s43, s48
	v_add_u32_e32 v170, s54, v145
	v_lshl_add_u64 v[222:223], v[220:221], 0, s[18:19]
	s_mov_b32 m0, s43
	ds_read_b128 v[200:203], v170
	ds_read_b128 v[204:207], v170 offset:1024
	ds_read_b128 v[208:211], v170 offset:2048
	ds_read_b128 v[212:215], v170 offset:3072
	global_load_lds_dwordx4 v[222:223], off
	v_lshl_add_u64 v[222:223], s[38:39], 0, v[140:141]
	v_lshl_add_u64 v[224:225], v[222:223], 0, s[18:19]
	s_add_i32 m0, s43, 0x2000
	s_nop 0
	global_load_lds_dwordx4 v[224:225], off
	s_barrier
	s_waitcnt lgkmcnt(0)
	s_waitcnt lgkmcnt(0)
	v_mfma_f32_16x16x32_bf16 v[94:97], v[200:203], v[162:165], v[94:97]
	v_mfma_f32_16x16x32_bf16 v[90:93], v[208:211], v[162:165], v[90:93]
	v_mfma_f32_16x16x32_bf16 v[86:89], v[200:203], v[172:175], v[86:89]
	v_mfma_f32_16x16x32_bf16 v[82:85], v[208:211], v[172:175], v[82:85]
	v_mfma_f32_16x16x32_bf16 v[78:81], v[200:203], v[180:183], v[78:81]
	v_mfma_f32_16x16x32_bf16 v[74:77], v[208:211], v[180:183], v[74:77]
	v_mfma_f32_16x16x32_bf16 v[70:73], v[200:203], v[192:195], v[70:73]
	v_mfma_f32_16x16x32_bf16 v[66:69], v[208:211], v[192:195], v[66:69]
	v_mfma_f32_16x16x32_bf16 v[94:97], v[204:207], v[166:169], v[94:97]
	v_mfma_f32_16x16x32_bf16 v[90:93], v[212:215], v[166:169], v[90:93]
	v_mfma_f32_16x16x32_bf16 v[86:89], v[204:207], v[176:179], v[86:89]
	v_mfma_f32_16x16x32_bf16 v[82:85], v[212:215], v[176:179], v[82:85]
	v_mfma_f32_16x16x32_bf16 v[78:81], v[204:207], v[188:191], v[78:81]
	v_mfma_f32_16x16x32_bf16 v[74:77], v[212:215], v[188:191], v[74:77]
	v_mfma_f32_16x16x32_bf16 v[70:73], v[204:207], v[196:199], v[70:73]
	v_mfma_f32_16x16x32_bf16 v[66:69], v[212:215], v[196:199], v[66:69]
	s_mov_b32 m0, s35
	v_lshl_add_u64 v[224:225], v[216:217], 0, s[20:21]
	s_barrier
	ds_read_b128 v[162:165], v144 offset:16384
	ds_read_b128 v[166:169], v144 offset:17408
	ds_read_b128 v[172:175], v144 offset:18432
	ds_read_b128 v[176:179], v144 offset:19456
	ds_read_b128 v[180:183], v144 offset:20480
	ds_read_b128 v[188:191], v144 offset:21504
	ds_read_b128 v[192:195], v144 offset:22528
	ds_read_b128 v[196:199], v144 offset:23552
	global_load_lds_dwordx4 v[224:225], off
	v_lshl_add_u64 v[224:225], v[218:219], 0, s[20:21]
	s_mov_b32 m0, s49
	s_nop 0
	global_load_lds_dwordx4 v[224:225], off
	s_barrier
	s_waitcnt lgkmcnt(0)
	s_waitcnt lgkmcnt(0)
	v_mfma_f32_16x16x32_bf16 v[62:65], v[146:149], v[162:165], v[62:65]
	v_mfma_f32_16x16x32_bf16 v[58:61], v[154:157], v[162:165], v[58:61]
	v_mfma_f32_16x16x32_bf16 v[54:57], v[146:149], v[172:175], v[54:57]
	v_mfma_f32_16x16x32_bf16 v[50:53], v[154:157], v[172:175], v[50:53]
	v_mfma_f32_16x16x32_bf16 v[46:49], v[146:149], v[180:183], v[46:49]
	v_mfma_f32_16x16x32_bf16 v[42:45], v[154:157], v[180:183], v[42:45]
	v_mfma_f32_16x16x32_bf16 v[38:41], v[146:149], v[192:195], v[38:41]
	v_mfma_f32_16x16x32_bf16 v[34:37], v[154:157], v[192:195], v[34:37]
	v_mfma_f32_16x16x32_bf16 v[62:65], v[150:153], v[166:169], v[62:65]
	v_mfma_f32_16x16x32_bf16 v[58:61], v[158:161], v[166:169], v[58:61]
	v_mfma_f32_16x16x32_bf16 v[54:57], v[150:153], v[176:179], v[54:57]
	v_mfma_f32_16x16x32_bf16 v[50:53], v[158:161], v[176:179], v[50:53]
	v_mfma_f32_16x16x32_bf16 v[46:49], v[150:153], v[188:191], v[46:49]
	v_mfma_f32_16x16x32_bf16 v[42:45], v[158:161], v[188:191], v[42:45]
	v_mfma_f32_16x16x32_bf16 v[38:41], v[150:153], v[196:199], v[38:41]
	v_mfma_f32_16x16x32_bf16 v[34:37], v[158:161], v[196:199], v[34:37]
	s_barrier
	s_add_i32 s43, s54, s48
	v_lshl_add_u64 v[146:147], v[220:221], 0, s[22:23]
	s_mov_b32 m0, s43
	s_nop 0
	global_load_lds_dwordx4 v[146:147], off
	v_lshl_add_u64 v[146:147], v[222:223], 0, s[22:23]
	s_add_i32 m0, s43, 0x2000
	s_nop 0
	global_load_lds_dwordx4 v[146:147], off
	s_waitcnt vmcnt(6)
	s_barrier
	v_mfma_f32_16x16x32_bf16 v[30:33], v[200:203], v[162:165], v[30:33]
	v_mfma_f32_16x16x32_bf16 v[26:29], v[208:211], v[162:165], v[26:29]
	v_mfma_f32_16x16x32_bf16 v[22:25], v[200:203], v[172:175], v[22:25]
	v_mfma_f32_16x16x32_bf16 v[18:21], v[208:211], v[172:175], v[18:21]
	v_mfma_f32_16x16x32_bf16 v[14:17], v[200:203], v[180:183], v[14:17]
	v_mfma_f32_16x16x32_bf16 v[10:13], v[208:211], v[180:183], v[10:13]
	v_mfma_f32_16x16x32_bf16 v[6:9], v[200:203], v[192:195], v[6:9]
	v_mfma_f32_16x16x32_bf16 v[2:5], v[208:211], v[192:195], v[2:5]
	v_mfma_f32_16x16x32_bf16 v[30:33], v[204:207], v[166:169], v[30:33]
	v_mfma_f32_16x16x32_bf16 v[26:29], v[212:215], v[166:169], v[26:29]
	v_mfma_f32_16x16x32_bf16 v[22:25], v[204:207], v[176:179], v[22:25]
	v_mfma_f32_16x16x32_bf16 v[18:21], v[212:215], v[176:179], v[18:21]
	v_mfma_f32_16x16x32_bf16 v[14:17], v[204:207], v[188:191], v[14:17]
	v_mfma_f32_16x16x32_bf16 v[10:13], v[212:215], v[188:191], v[10:13]
	v_mfma_f32_16x16x32_bf16 v[6:9], v[204:207], v[196:199], v[6:9]
	v_mfma_f32_16x16x32_bf16 v[2:5], v[212:215], v[196:199], v[2:5]
	s_add_i32 s43, 0, 0x18000
	v_add_u32_e32 v158, s43, v145
	s_barrier
	ds_read_b128 v[146:149], v158
	ds_read_b128 v[150:153], v158 offset:1024
	ds_read_b128 v[154:157], v158 offset:2048
	ds_read_b128 v[158:161], v158 offset:3072
	s_mov_b32 m0, s50
	v_lshl_add_u64 v[200:201], v[216:217], 0, s[24:25]
	ds_read_b128 v[162:165], v144 offset:32768
	ds_read_b128 v[166:169], v144 offset:33792
	ds_read_b128 v[172:175], v144 offset:34816
	ds_read_b128 v[176:179], v144 offset:35840
	ds_read_b128 v[180:183], v144 offset:36864
	ds_read_b128 v[188:191], v144 offset:37888
	ds_read_b128 v[192:195], v144 offset:38912
	ds_read_b128 v[196:199], v144 offset:39936
	global_load_lds_dwordx4 v[200:201], off
	v_lshl_add_u64 v[200:201], v[218:219], 0, s[24:25]
	s_mov_b32 m0, s51
	s_nop 0
	global_load_lds_dwordx4 v[200:201], off
	s_waitcnt lgkmcnt(8)
	s_barrier
	s_waitcnt lgkmcnt(0)
	s_waitcnt lgkmcnt(0)
	v_mfma_f32_16x16x32_bf16 v[126:129], v[146:149], v[162:165], v[126:129]
	v_mfma_f32_16x16x32_bf16 v[122:125], v[154:157], v[162:165], v[122:125]
	v_mfma_f32_16x16x32_bf16 v[118:121], v[146:149], v[172:175], v[118:121]
	v_mfma_f32_16x16x32_bf16 v[114:117], v[154:157], v[172:175], v[114:117]
	v_mfma_f32_16x16x32_bf16 v[110:113], v[146:149], v[180:183], v[110:113]
	v_mfma_f32_16x16x32_bf16 v[106:109], v[154:157], v[180:183], v[106:109]
	v_mfma_f32_16x16x32_bf16 v[102:105], v[146:149], v[192:195], v[102:105]
	v_mfma_f32_16x16x32_bf16 v[98:101], v[154:157], v[192:195], v[98:101]
	v_mfma_f32_16x16x32_bf16 v[126:129], v[150:153], v[166:169], v[126:129]
	v_mfma_f32_16x16x32_bf16 v[122:125], v[158:161], v[166:169], v[122:125]
	v_mfma_f32_16x16x32_bf16 v[118:121], v[150:153], v[176:179], v[118:121]
	v_mfma_f32_16x16x32_bf16 v[114:117], v[158:161], v[176:179], v[114:117]
	v_mfma_f32_16x16x32_bf16 v[110:113], v[150:153], v[188:191], v[110:113]
	v_mfma_f32_16x16x32_bf16 v[106:109], v[158:161], v[188:191], v[106:109]
	v_mfma_f32_16x16x32_bf16 v[102:105], v[150:153], v[196:199], v[102:105]
	v_mfma_f32_16x16x32_bf16 v[98:101], v[158:161], v[196:199], v[98:101]
	s_barrier
	s_add_i32 s54, 0, 0x1c000
	s_add_i32 s43, s43, s48
	v_add_u32_e32 v170, s54, v145
	v_lshl_add_u64 v[224:225], v[220:221], 0, s[26:27]
	s_mov_b32 m0, s43
	ds_read_b128 v[200:203], v170
	ds_read_b128 v[204:207], v170 offset:1024
	ds_read_b128 v[208:211], v170 offset:2048
	ds_read_b128 v[212:215], v170 offset:3072
	global_load_lds_dwordx4 v[224:225], off
	v_lshl_add_u64 v[224:225], v[222:223], 0, s[26:27]
	s_add_i32 m0, s43, 0x2000
	s_nop 0
	global_load_lds_dwordx4 v[224:225], off
	s_barrier
	s_waitcnt lgkmcnt(0)
	s_waitcnt lgkmcnt(0)
	v_mfma_f32_16x16x32_bf16 v[94:97], v[200:203], v[162:165], v[94:97]
	v_mfma_f32_16x16x32_bf16 v[90:93], v[208:211], v[162:165], v[90:93]
	v_mfma_f32_16x16x32_bf16 v[86:89], v[200:203], v[172:175], v[86:89]
	v_mfma_f32_16x16x32_bf16 v[82:85], v[208:211], v[172:175], v[82:85]
	v_mfma_f32_16x16x32_bf16 v[78:81], v[200:203], v[180:183], v[78:81]
	v_mfma_f32_16x16x32_bf16 v[74:77], v[208:211], v[180:183], v[74:77]
	v_mfma_f32_16x16x32_bf16 v[70:73], v[200:203], v[192:195], v[70:73]
	v_mfma_f32_16x16x32_bf16 v[66:69], v[208:211], v[192:195], v[66:69]
	v_mfma_f32_16x16x32_bf16 v[94:97], v[204:207], v[166:169], v[94:97]
	v_mfma_f32_16x16x32_bf16 v[90:93], v[212:215], v[166:169], v[90:93]
	v_mfma_f32_16x16x32_bf16 v[86:89], v[204:207], v[176:179], v[86:89]
	v_mfma_f32_16x16x32_bf16 v[82:85], v[212:215], v[176:179], v[82:85]
	v_mfma_f32_16x16x32_bf16 v[78:81], v[204:207], v[188:191], v[78:81]
	v_mfma_f32_16x16x32_bf16 v[74:77], v[212:215], v[188:191], v[74:77]
	v_mfma_f32_16x16x32_bf16 v[70:73], v[204:207], v[196:199], v[70:73]
	v_mfma_f32_16x16x32_bf16 v[66:69], v[212:215], v[196:199], v[66:69]
	s_mov_b32 m0, s52
	v_lshl_add_u64 v[216:217], v[216:217], 0, s[28:29]
	s_barrier
	ds_read_b128 v[162:165], v144 offset:49152
	ds_read_b128 v[166:169], v144 offset:50176
	ds_read_b128 v[172:175], v144 offset:51200
	ds_read_b128 v[176:179], v144 offset:52224
	ds_read_b128 v[180:183], v144 offset:53248
	ds_read_b128 v[188:191], v144 offset:54272
	ds_read_b128 v[192:195], v144 offset:55296
	ds_read_b128 v[196:199], v144 offset:56320
	global_load_lds_dwordx4 v[216:217], off
	v_lshl_add_u64 v[216:217], v[218:219], 0, s[28:29]
	s_mov_b32 m0, s53
	s_nop 0
	global_load_lds_dwordx4 v[216:217], off
	s_barrier
	s_waitcnt lgkmcnt(0)
	s_waitcnt lgkmcnt(0)
	v_mfma_f32_16x16x32_bf16 v[62:65], v[146:149], v[162:165], v[62:65]
	v_mfma_f32_16x16x32_bf16 v[58:61], v[154:157], v[162:165], v[58:61]
	v_mfma_f32_16x16x32_bf16 v[54:57], v[146:149], v[172:175], v[54:57]
	v_mfma_f32_16x16x32_bf16 v[50:53], v[154:157], v[172:175], v[50:53]
	v_mfma_f32_16x16x32_bf16 v[46:49], v[146:149], v[180:183], v[46:49]
	v_mfma_f32_16x16x32_bf16 v[42:45], v[154:157], v[180:183], v[42:45]
	v_mfma_f32_16x16x32_bf16 v[38:41], v[146:149], v[192:195], v[38:41]
	v_mfma_f32_16x16x32_bf16 v[34:37], v[154:157], v[192:195], v[34:37]
	v_mfma_f32_16x16x32_bf16 v[62:65], v[150:153], v[166:169], v[62:65]
	v_mfma_f32_16x16x32_bf16 v[58:61], v[158:161], v[166:169], v[58:61]
	v_mfma_f32_16x16x32_bf16 v[54:57], v[150:153], v[176:179], v[54:57]
	v_mfma_f32_16x16x32_bf16 v[50:53], v[158:161], v[176:179], v[50:53]
	v_mfma_f32_16x16x32_bf16 v[46:49], v[150:153], v[188:191], v[46:49]
	v_mfma_f32_16x16x32_bf16 v[42:45], v[158:161], v[188:191], v[42:45]
	v_mfma_f32_16x16x32_bf16 v[38:41], v[150:153], v[196:199], v[38:41]
	v_mfma_f32_16x16x32_bf16 v[34:37], v[158:161], v[196:199], v[34:37]
	s_barrier
	s_add_i32 s43, s54, s48
	v_lshl_add_u64 v[146:147], v[220:221], 0, s[30:31]
	s_mov_b32 m0, s43
	s_nop 0
	global_load_lds_dwordx4 v[146:147], off
	v_lshl_add_u64 v[146:147], v[222:223], 0, s[30:31]
	s_add_i32 m0, s43, 0x2000
	s_nop 0
	global_load_lds_dwordx4 v[146:147], off
	s_waitcnt vmcnt(6)
	s_barrier
	v_mfma_f32_16x16x32_bf16 v[30:33], v[200:203], v[162:165], v[30:33]
	v_mfma_f32_16x16x32_bf16 v[26:29], v[208:211], v[162:165], v[26:29]
	v_mfma_f32_16x16x32_bf16 v[22:25], v[200:203], v[172:175], v[22:25]
	v_mfma_f32_16x16x32_bf16 v[18:21], v[208:211], v[172:175], v[18:21]
	v_mfma_f32_16x16x32_bf16 v[14:17], v[200:203], v[180:183], v[14:17]
	v_mfma_f32_16x16x32_bf16 v[10:13], v[208:211], v[180:183], v[10:13]
	v_mfma_f32_16x16x32_bf16 v[6:9], v[200:203], v[192:195], v[6:9]
	v_mfma_f32_16x16x32_bf16 v[2:5], v[208:211], v[192:195], v[2:5]
	v_mfma_f32_16x16x32_bf16 v[30:33], v[204:207], v[166:169], v[30:33]
	v_mfma_f32_16x16x32_bf16 v[26:29], v[212:215], v[166:169], v[26:29]
	v_mfma_f32_16x16x32_bf16 v[22:25], v[204:207], v[176:179], v[22:25]
	v_mfma_f32_16x16x32_bf16 v[18:21], v[212:215], v[176:179], v[18:21]
	v_mfma_f32_16x16x32_bf16 v[14:17], v[204:207], v[188:191], v[14:17]
	v_mfma_f32_16x16x32_bf16 v[10:13], v[212:215], v[188:191], v[10:13]
	v_mfma_f32_16x16x32_bf16 v[6:9], v[204:207], v[196:199], v[6:9]
	v_mfma_f32_16x16x32_bf16 v[2:5], v[212:215], v[196:199], v[2:5]
	s_add_i32 s40, s40, 2
	s_add_u32 s38, s38, 0x100
	s_addc_u32 s39, s39, 0
	s_cmp_gt_u32 s40, 11
	s_barrier
	s_cbranch_scc0 .LBB0_712
	s_add_u32 s36, s36, 0x40780
	v_add_u32_e32 v145, 0, v145
	s_addc_u32 s37, s37, 0
	s_mov_b32 m0, s42
	v_add_u32_e32 v150, 0x10000, v145
	v_lshl_add_u64 v[130:131], s[36:37], 0, v[130:131]
	ds_read_b128 v[134:137], v150
	ds_read_b128 v[138:141], v150 offset:1024
	ds_read_b128 v[146:149], v150 offset:2048
	ds_read_b128 v[150:153], v150 offset:3072
	ds_read_b128 v[154:157], v144
	ds_read_b128 v[158:161], v144 offset:1024
	ds_read_b128 v[162:165], v144 offset:2048
	ds_read_b128 v[166:169], v144 offset:3072
	ds_read_b128 v[172:175], v144 offset:4096
	ds_read_b128 v[176:179], v144 offset:5120
	ds_read_b128 v[180:183], v144 offset:6144
	ds_read_b128 v[188:191], v144 offset:7168
	global_load_lds_dwordx4 v[130:131], off
	v_lshl_add_u64 v[130:131], s[36:37], 0, v[132:133]
	s_mov_b32 m0, s41
	s_nop 0
	global_load_lds_dwordx4 v[130:131], off
	s_barrier
	s_waitcnt lgkmcnt(0)
	s_waitcnt lgkmcnt(0)
	v_mfma_f32_16x16x32_bf16 v[110:113], v[134:137], v[172:175], v[110:113]
	v_mfma_f32_16x16x32_bf16 v[102:105], v[134:137], v[180:183], v[102:105]
	v_mfma_f32_16x16x32_bf16 v[98:101], v[146:149], v[180:183], v[98:101]
	v_mfma_f32_16x16x32_bf16 v[126:129], v[134:137], v[154:157], v[126:129]
	v_mfma_f32_16x16x32_bf16 v[122:125], v[146:149], v[154:157], v[122:125]
	v_mfma_f32_16x16x32_bf16 v[118:121], v[134:137], v[162:165], v[118:121]
	v_mfma_f32_16x16x32_bf16 v[114:117], v[146:149], v[162:165], v[114:117]
	v_mfma_f32_16x16x32_bf16 v[130:133], v[138:141], v[176:179], v[110:113]
	v_mfma_f32_16x16x32_bf16 v[106:109], v[146:149], v[172:175], v[106:109]
	v_mfma_f32_16x16x32_bf16 v[102:105], v[138:141], v[188:191], v[102:105]
	v_mfma_f32_16x16x32_bf16 v[98:101], v[150:153], v[188:191], v[98:101]
	v_mfma_f32_16x16x32_bf16 v[126:129], v[138:141], v[158:161], v[126:129]
	v_mfma_f32_16x16x32_bf16 v[122:125], v[150:153], v[158:161], v[122:125]
	v_mfma_f32_16x16x32_bf16 v[118:121], v[138:141], v[166:169], v[118:121]
	v_mfma_f32_16x16x32_bf16 v[114:117], v[150:153], v[166:169], v[114:117]
	v_mfma_f32_16x16x32_bf16 v[192:195], v[150:153], v[176:179], v[106:109]
	v_add_u32_e32 v170, 0x14000, v145
	s_barrier
	ds_read_b128 v[106:109], v170
	ds_read_b128 v[110:113], v170 offset:1024
	ds_read_b128 v[196:199], v170 offset:2048
	ds_read_b128 v[200:203], v170 offset:3072
	s_barrier
	s_waitcnt lgkmcnt(0)
	s_waitcnt lgkmcnt(0)
	v_mfma_f32_16x16x32_bf16 v[86:89], v[106:109], v[162:165], v[86:89]
	v_mfma_f32_16x16x32_bf16 v[82:85], v[196:199], v[162:165], v[82:85]
	v_mfma_f32_16x16x32_bf16 v[70:73], v[106:109], v[180:183], v[70:73]
	v_mfma_f32_16x16x32_bf16 v[66:69], v[196:199], v[180:183], v[66:69]
	v_mfma_f32_16x16x32_bf16 v[94:97], v[106:109], v[154:157], v[94:97]
	v_mfma_f32_16x16x32_bf16 v[90:93], v[196:199], v[154:157], v[90:93]
	v_mfma_f32_16x16x32_bf16 v[86:89], v[110:113], v[166:169], v[86:89]
	v_mfma_f32_16x16x32_bf16 v[82:85], v[200:203], v[166:169], v[82:85]
	v_mfma_f32_16x16x32_bf16 v[78:81], v[106:109], v[172:175], v[78:81]
	v_mfma_f32_16x16x32_bf16 v[74:77], v[196:199], v[172:175], v[74:77]
	v_mfma_f32_16x16x32_bf16 v[70:73], v[110:113], v[188:191], v[70:73]
	v_mfma_f32_16x16x32_bf16 v[66:69], v[200:203], v[188:191], v[66:69]
	v_mfma_f32_16x16x32_bf16 v[204:207], v[110:113], v[158:161], v[94:97]
	v_mfma_f32_16x16x32_bf16 v[154:157], v[200:203], v[158:161], v[90:93]
	v_mfma_f32_16x16x32_bf16 v[162:165], v[110:113], v[176:179], v[78:81]
	v_mfma_f32_16x16x32_bf16 v[166:169], v[200:203], v[176:179], v[74:77]
	s_barrier
	s_nop 0
	ds_read_b128 v[74:77], v144 offset:16384
	ds_read_b128 v[78:81], v144 offset:17408
	ds_read_b128 v[90:93], v144 offset:18432
	ds_read_b128 v[94:97], v144 offset:19456
	ds_read_b128 v[158:161], v144 offset:20480
	ds_read_b128 v[172:175], v144 offset:21504
	ds_read_b128 v[176:179], v144 offset:22528
	ds_read_b128 v[180:183], v144 offset:23552
	s_waitcnt vmcnt(4)
	s_barrier
	s_waitcnt lgkmcnt(0)
	s_waitcnt lgkmcnt(0)
	v_mfma_f32_16x16x32_bf16 v[62:65], v[134:137], v[74:77], v[62:65]
	v_mfma_f32_16x16x32_bf16 v[58:61], v[146:149], v[74:77], v[58:61]
	v_mfma_f32_16x16x32_bf16 v[54:57], v[134:137], v[90:93], v[54:57]
	v_mfma_f32_16x16x32_bf16 v[50:53], v[146:149], v[90:93], v[50:53]
	v_mfma_f32_16x16x32_bf16 v[38:41], v[134:137], v[176:179], v[38:41]
	v_mfma_f32_16x16x32_bf16 v[34:37], v[146:149], v[176:179], v[34:37]
	v_mfma_f32_16x16x32_bf16 v[62:65], v[138:141], v[78:81], v[62:65]
	v_mfma_f32_16x16x32_bf16 v[58:61], v[150:153], v[78:81], v[58:61]
	v_mfma_f32_16x16x32_bf16 v[54:57], v[138:141], v[94:97], v[54:57]
	v_mfma_f32_16x16x32_bf16 v[50:53], v[150:153], v[94:97], v[50:53]
	v_mfma_f32_16x16x32_bf16 v[46:49], v[134:137], v[158:161], v[46:49]
	v_mfma_f32_16x16x32_bf16 v[42:45], v[146:149], v[158:161], v[42:45]
	v_mfma_f32_16x16x32_bf16 v[38:41], v[138:141], v[180:183], v[38:41]
	v_mfma_f32_16x16x32_bf16 v[34:37], v[150:153], v[180:183], v[34:37]
	v_mfma_f32_16x16x32_bf16 v[188:191], v[138:141], v[172:175], v[46:49]
	v_mfma_f32_16x16x32_bf16 v[208:211], v[150:153], v[172:175], v[42:45]
	v_mfma_f32_16x16x32_bf16 v[22:25], v[106:109], v[90:93], v[22:25]
	v_mfma_f32_16x16x32_bf16 v[18:21], v[196:199], v[90:93], v[18:21]
	v_mfma_f32_16x16x32_bf16 v[6:9], v[106:109], v[176:179], v[6:9]
	v_mfma_f32_16x16x32_bf16 v[2:5], v[196:199], v[176:179], v[2:5]
	v_mfma_f32_16x16x32_bf16 v[30:33], v[106:109], v[74:77], v[30:33]
	v_mfma_f32_16x16x32_bf16 v[26:29], v[196:199], v[74:77], v[26:29]
	v_mfma_f32_16x16x32_bf16 v[22:25], v[110:113], v[94:97], v[22:25]
	v_mfma_f32_16x16x32_bf16 v[18:21], v[200:203], v[94:97], v[18:21]
	v_mfma_f32_16x16x32_bf16 v[14:17], v[106:109], v[158:161], v[14:17]
	v_mfma_f32_16x16x32_bf16 v[10:13], v[196:199], v[158:161], v[10:13]
	v_mfma_f32_16x16x32_bf16 v[6:9], v[110:113], v[180:183], v[6:9]
	v_mfma_f32_16x16x32_bf16 v[2:5], v[200:203], v[180:183], v[2:5]
	v_mfma_f32_16x16x32_bf16 v[146:149], v[110:113], v[78:81], v[30:33]
	v_mfma_f32_16x16x32_bf16 v[150:153], v[200:203], v[78:81], v[26:29]
	v_mfma_f32_16x16x32_bf16 v[212:215], v[110:113], v[172:175], v[14:17]
	v_mfma_f32_16x16x32_bf16 v[172:175], v[200:203], v[172:175], v[10:13]
	v_add_u32_e32 v26, 0x18000, v145
	s_barrier
	ds_read_b128 v[10:13], v26
	ds_read_b128 v[14:17], v26 offset:1024
	ds_read_b128 v[176:179], v26 offset:2048
	ds_read_b128 v[180:183], v26 offset:3072
	ds_read_b128 v[26:29], v144 offset:32768
	ds_read_b128 v[30:33], v144 offset:33792
	ds_read_b128 v[42:45], v144 offset:34816
	ds_read_b128 v[46:49], v144 offset:35840
	ds_read_b128 v[196:199], v144 offset:36864
	ds_read_b128 v[200:203], v144 offset:37888
	ds_read_b128 v[216:219], v144 offset:38912
	ds_read_b128 v[220:223], v144 offset:39936
	s_waitcnt vmcnt(2)
	s_barrier
	s_waitcnt lgkmcnt(0)
	s_waitcnt lgkmcnt(0)
	v_mfma_f32_16x16x32_bf16 v[74:77], v[10:13], v[26:29], v[126:129]
	v_mfma_f32_16x16x32_bf16 v[158:161], v[14:17], v[30:33], v[74:77]
	v_mfma_f32_16x16x32_bf16 v[74:77], v[176:179], v[26:29], v[122:125]
	v_mfma_f32_16x16x32_bf16 v[138:141], v[180:183], v[30:33], v[74:77]
	v_mfma_f32_16x16x32_bf16 v[74:77], v[10:13], v[42:45], v[118:121]
	v_mfma_f32_16x16x32_bf16 v[110:113], v[14:17], v[46:49], v[74:77]
	v_mfma_f32_16x16x32_bf16 v[74:77], v[176:179], v[42:45], v[114:117]
	v_mfma_f32_16x16x32_bf16 v[106:109], v[180:183], v[46:49], v[74:77]
	v_mfma_f32_16x16x32_bf16 v[74:77], v[10:13], v[196:199], v[130:133]
	v_mfma_f32_16x16x32_bf16 v[94:97], v[14:17], v[200:203], v[74:77]
	v_mfma_f32_16x16x32_bf16 v[74:77], v[176:179], v[196:199], v[192:195]
	v_mfma_f32_16x16x32_bf16 v[90:93], v[180:183], v[200:203], v[74:77]
	v_mfma_f32_16x16x32_bf16 v[74:77], v[10:13], v[216:219], v[102:105]
	v_mfma_f32_16x16x32_bf16 v[78:81], v[14:17], v[220:223], v[74:77]
	v_mfma_f32_16x16x32_bf16 v[74:77], v[176:179], v[216:219], v[98:101]
	v_mfma_f32_16x16x32_bf16 v[74:77], v[180:183], v[220:223], v[74:77]
	s_nop 0
	v_add_u32_e32 v98, 0x1c000, v145
	s_barrier
	ds_read_b128 v[114:117], v98
	ds_read_b128 v[118:121], v98 offset:1024
	ds_read_b128 v[122:125], v98 offset:2048
	ds_read_b128 v[126:129], v98 offset:3072
	s_waitcnt vmcnt(0)
	s_barrier
	s_waitcnt lgkmcnt(0)
	s_waitcnt lgkmcnt(0)
	v_mfma_f32_16x16x32_bf16 v[98:101], v[114:117], v[26:29], v[204:207]
	v_mfma_f32_16x16x32_bf16 v[26:29], v[122:125], v[26:29], v[154:157]
	v_mfma_f32_16x16x32_bf16 v[130:133], v[126:129], v[30:33], v[26:29]
	v_mfma_f32_16x16x32_bf16 v[26:29], v[114:117], v[42:45], v[86:89]
	v_mfma_f32_16x16x32_bf16 v[102:105], v[118:121], v[46:49], v[26:29]
	v_mfma_f32_16x16x32_bf16 v[26:29], v[122:125], v[42:45], v[82:85]
	v_mfma_f32_16x16x32_bf16 v[134:137], v[118:121], v[30:33], v[98:101]
	v_mfma_f32_16x16x32_bf16 v[98:101], v[126:129], v[46:49], v[26:29]
	v_mfma_f32_16x16x32_bf16 v[26:29], v[114:117], v[196:199], v[162:165]
	v_mfma_f32_16x16x32_bf16 v[86:89], v[118:121], v[200:203], v[26:29]
	v_mfma_f32_16x16x32_bf16 v[26:29], v[122:125], v[196:199], v[166:169]
	v_mfma_f32_16x16x32_bf16 v[82:85], v[126:129], v[200:203], v[26:29]
	v_mfma_f32_16x16x32_bf16 v[26:29], v[114:117], v[216:219], v[70:73]
	v_mfma_f32_16x16x32_bf16 v[70:73], v[118:121], v[220:223], v[26:29]
	v_mfma_f32_16x16x32_bf16 v[26:29], v[122:125], v[216:219], v[66:69]
	v_mfma_f32_16x16x32_bf16 v[66:69], v[126:129], v[220:223], v[26:29]
	s_barrier
	ds_read_b128 v[154:157], v144 offset:49152
	ds_read_b128 v[162:165], v144 offset:50176
	ds_read_b128 v[166:169], v144 offset:51200
	ds_read_b128 v[192:195], v144 offset:52224
	ds_read_b128 v[196:199], v144 offset:53248
	ds_read_b128 v[200:203], v144 offset:54272
	ds_read_b128 v[204:207], v144 offset:55296
	ds_read_b128 v[216:219], v144 offset:56320
	s_barrier
	s_waitcnt lgkmcnt(0)
	s_waitcnt lgkmcnt(0)
	v_mfma_f32_16x16x32_bf16 v[26:29], v[10:13], v[154:157], v[62:65]
	v_mfma_f32_16x16x32_bf16 v[62:65], v[14:17], v[162:165], v[26:29]
	v_mfma_f32_16x16x32_bf16 v[26:29], v[176:179], v[154:157], v[58:61]
	v_mfma_f32_16x16x32_bf16 v[58:61], v[180:183], v[162:165], v[26:29]
	v_mfma_f32_16x16x32_bf16 v[26:29], v[10:13], v[166:169], v[54:57]
	v_mfma_f32_16x16x32_bf16 v[46:49], v[14:17], v[192:195], v[26:29]
	v_mfma_f32_16x16x32_bf16 v[26:29], v[176:179], v[166:169], v[50:53]
	v_mfma_f32_16x16x32_bf16 v[42:45], v[180:183], v[192:195], v[26:29]
	v_mfma_f32_16x16x32_bf16 v[26:29], v[10:13], v[196:199], v[188:191]
	v_mfma_f32_16x16x32_bf16 v[10:13], v[10:13], v[204:207], v[38:41]
	v_mfma_f32_16x16x32_bf16 v[30:33], v[14:17], v[200:203], v[26:29]
	v_mfma_f32_16x16x32_bf16 v[26:29], v[176:179], v[196:199], v[208:211]
	v_mfma_f32_16x16x32_bf16 v[14:17], v[14:17], v[216:219], v[10:13]
	v_mfma_f32_16x16x32_bf16 v[10:13], v[176:179], v[204:207], v[34:37]
	v_mfma_f32_16x16x32_bf16 v[26:29], v[180:183], v[200:203], v[26:29]
	v_mfma_f32_16x16x32_bf16 v[10:13], v[180:183], v[216:219], v[10:13]
	v_mfma_f32_16x16x32_bf16 v[34:37], v[114:117], v[154:157], v[146:149]
	v_mfma_f32_16x16x32_bf16 v[54:57], v[118:121], v[162:165], v[34:37]
	v_mfma_f32_16x16x32_bf16 v[34:37], v[122:125], v[154:157], v[150:153]
	v_mfma_f32_16x16x32_bf16 v[18:21], v[122:125], v[166:169], v[18:21]
	v_mfma_f32_16x16x32_bf16 v[50:53], v[126:129], v[162:165], v[34:37]
	v_mfma_f32_16x16x32_bf16 v[22:25], v[114:117], v[166:169], v[22:25]
	v_mfma_f32_16x16x32_bf16 v[34:37], v[126:129], v[192:195], v[18:21]
	v_mfma_f32_16x16x32_bf16 v[18:21], v[114:117], v[196:199], v[212:215]
	v_mfma_f32_16x16x32_bf16 v[38:41], v[118:121], v[192:195], v[22:25]
	v_mfma_f32_16x16x32_bf16 v[22:25], v[118:121], v[200:203], v[18:21]
	v_mfma_f32_16x16x32_bf16 v[18:21], v[122:125], v[196:199], v[172:175]
	v_mfma_f32_16x16x32_bf16 v[6:9], v[114:117], v[204:207], v[6:9]
	v_mfma_f32_16x16x32_bf16 v[2:5], v[122:125], v[204:207], v[2:5]
	v_mfma_f32_16x16x32_bf16 v[18:21], v[126:129], v[200:203], v[18:21]
	v_mfma_f32_16x16x32_bf16 v[6:9], v[118:121], v[216:219], v[6:9]
	v_mfma_f32_16x16x32_bf16 v[2:5], v[126:129], v[216:219], v[2:5]
	s_cmpk_lt_u32 s47, 0x100
	s_barrier
	s_cbranch_scc0 .LBB0_715
	s_barrier
.LBB0_715:
	s_setprio 0
	v_or_b32_e32 v114, s34, v143
	v_add_u32_e32 v174, s1, v114
	v_ashrrev_i32_e32 v175, 31, v174
	v_lshlrev_b64 v[182:183], 6, v[174:175]
	v_lshl_add_u64 v[114:115], s[8:9], 0, v[182:183]
	global_load_dwordx4 v[190:193], v[114:115], off
	global_load_dwordx4 v[194:197], v[114:115], off offset:32
	global_load_dwordx4 v[198:201], v[114:115], off offset:16
	global_load_dwordx4 v[202:205], v[114:115], off offset:48
	v_lshlrev_b32_e32 v114, 3, v142
	v_lshl_or_b32 v114, s12, 5, v114
	v_or_b32_e32 v172, s0, v114
	v_ashrrev_i32_e32 v173, 31, v172
	v_lshlrev_b64 v[114:115], 11, v[174:175]
	v_lshl_add_u64 v[116:117], s[2:3], 0, v[114:115]
	v_lshl_add_u64 v[114:115], s[10:11], 0, v[114:115]
	v_lshlrev_b64 v[176:177], 1, v[172:173]
	v_lshl_add_u64 v[116:117], v[116:117], 0, v[176:177]
	v_lshl_add_u64 v[114:115], v[114:115], 0, v[176:177]
	global_load_dwordx4 v[206:209], v[116:117], off
	global_load_dwordx4 v[210:213], v[114:115], off
	v_and_b32_e32 v119, 64, v185
	v_xor_b32_e32 v118, 16, v185
	s_lshr_b32 s0, s0, 6
	v_add_u32_e32 v119, 64, v119
	v_or_b32_e32 v180, 16, v174
	v_xor_b32_e32 v120, 32, v185
	s_and_b32 s34, s0, 12
	v_cmp_lt_i32_e64 s[0:1], v118, v119
	v_ashrrev_i32_e32 v181, 31, v180
	v_lshlrev_b64 v[178:179], 6, v[180:181]
	v_cndmask_b32_e64 v118, v185, v118, s[0:1]
	v_cmp_lt_i32_e64 s[0:1], v120, v119
	v_cmp_eq_u32_e32 vcc, 0, v142
	v_lshlrev_b32_e32 v188, 2, v118
	v_cndmask_b32_e64 v119, v185, v120, s[0:1]
	v_lshl_add_u64 v[120:121], s[8:9], 0, v[178:179]
	global_load_dwordx4 v[166:169], v[116:117], off offset:256
	global_load_dwordx4 v[162:165], v[114:115], off offset:256
	global_load_dwordx4 v[142:145], v[120:121], off offset:48
	global_load_dwordx4 v[150:153], v[120:121], off offset:32
	global_load_dwordx4 v[154:157], v[120:121], off offset:16
	global_load_dwordx4 v[146:149], v[120:121], off
	v_lshlrev_b32_e32 v170, 2, v119
	v_lshlrev_b64 v[118:119], 11, v[180:181]
	v_lshl_add_u64 v[122:123], s[2:3], 0, v[118:119]
	v_lshl_add_u64 v[118:119], s[10:11], 0, v[118:119]
	v_lshl_add_u64 v[114:115], v[122:123], 0, v[176:177]
	v_lshl_add_u64 v[116:117], v[118:119], 0, v[176:177]
	global_load_dwordx4 v[126:129], v[114:115], off
	global_load_dwordx4 v[118:121], v[114:115], off offset:256
	global_load_dwordx4 v[122:125], v[116:117], off
	s_nop 0
	global_load_dwordx4 v[114:117], v[116:117], off offset:256
	s_or_b32 s34, s34, s12
	s_waitcnt vmcnt(0)
	v_mov_b32_e32 v214, v192
	v_mov_b32_e32 v215, v196
	v_mov_b32_e32 v196, v193
	v_mov_b32_e32 v192, v198
	v_mov_b32_e32 v193, v202
	v_mov_b32_e32 v202, v199
	v_mov_b32_e32 v198, v200
	v_mov_b32_e32 v199, v204
	v_mov_b32_e32 v204, v201
	v_mov_b32_e32 v200, v190
	v_mov_b32_e32 v201, v194
	v_mov_b32_e32 v194, v191
	v_pk_add_f32 v[190:191], v[214:215], v[196:197]
	v_pk_add_f32 v[192:193], v[192:193], v[202:203]
	v_pk_add_f32 v[196:197], v[198:199], v[204:205]
	v_pk_add_f32 v[194:195], v[200:201], v[194:195]
	v_pk_add_f32 v[192:193], v[192:193], v[196:197]
	v_pk_add_f32 v[190:191], v[194:195], v[190:191]
	v_lshlrev_b32_e32 v198, 16, v206
	v_pk_add_f32 v[190:191], v[190:191], v[192:193]
	v_and_b32_e32 v199, 0xffff0000, v206
	v_add_f32_e32 v189, v190, v191
	v_fmamk_f32 v189, v189, 0x3a800000, v186
	v_mul_f32_e32 v190, 0x4b800000, v189
	v_cmp_gt_f32_e64 s[0:1], s45, v189
	v_lshlrev_b32_e32 v200, 16, v210
	v_and_b32_e32 v201, 0xffff0000, v210
	v_cndmask_b32_e64 v189, v189, v190, s[0:1]
	v_rsq_f32_e32 v189, v189
	v_lshlrev_b32_e32 v202, 16, v207
	v_and_b32_e32 v203, 0xffff0000, v207
	v_lshlrev_b32_e32 v190, 16, v211
	v_mul_f32_e32 v192, 0x45800000, v189
	v_cndmask_b32_e64 v189, v189, v192, s[0:1]
	v_mul_f32_e32 v158, v158, v189
	v_mul_f32_e32 v159, v159, v189
	v_mul_f32_e32 v158, 0xbfb8aa3b, v158
	v_mul_f32_e32 v159, 0xbfb8aa3b, v159
	v_mul_f32_e32 v136, v136, v189
	v_mul_f32_e32 v137, v137, v189
	v_exp_f32_e32 v158, v158
	v_exp_f32_e32 v159, v159
	v_mul_f32_e32 v136, 0xbfb8aa3b, v136
	v_mul_f32_e32 v137, 0xbfb8aa3b, v137
	v_mul_f32_e32 v130, v130, v189
	v_mul_f32_e32 v131, v131, v189
	v_exp_f32_e32 v136, v136
	v_exp_f32_e32 v137, v137
	v_mul_f32_e32 v130, 0xbfb8aa3b, v130
	v_mul_f32_e32 v131, 0xbfb8aa3b, v131
	v_exp_f32_e32 v130, v130
	v_exp_f32_e32 v131, v131
	v_mul_f32_e32 v160, v160, v189
	v_mul_f32_e32 v161, v161, v189
	v_mul_f32_e32 v138, v138, v189
	v_mul_f32_e32 v160, 0xbfb8aa3b, v160
	v_mul_f32_e32 v161, 0xbfb8aa3b, v161
	v_add_f32_e32 v158, 1.0, v158
	v_add_f32_e32 v159, 1.0, v159
	v_mul_f32_e32 v139, v139, v189
	v_mul_f32_e32 v134, v134, v189
	v_mul_f32_e32 v135, v135, v189
	v_mul_f32_e32 v138, 0xbfb8aa3b, v138
	v_exp_f32_e32 v160, v160
	v_exp_f32_e32 v161, v161
	v_rcp_f32_e32 v158, v158
	v_rcp_f32_e32 v159, v159
	v_mul_f32_e32 v139, 0xbfb8aa3b, v139
	v_mul_f32_e32 v140, v140, v189
	v_mul_f32_e32 v141, v141, v189
	v_mul_f32_e32 v134, 0xbfb8aa3b, v134
	v_mul_f32_e32 v135, 0xbfb8aa3b, v135
	v_add_f32_e32 v136, 1.0, v136
	v_add_f32_e32 v137, 1.0, v137
	v_mul_f32_e32 v132, v132, v189
	v_mul_f32_e32 v133, v133, v189
	v_exp_f32_e32 v138, v138
	v_exp_f32_e32 v139, v139
	v_mul_f32_e32 v140, 0xbfb8aa3b, v140
	v_mul_f32_e32 v141, 0xbfb8aa3b, v141
	v_exp_f32_e32 v134, v134
	v_exp_f32_e32 v135, v135
	v_rcp_f32_e32 v136, v136
	v_rcp_f32_e32 v137, v137
	v_add_f32_e32 v130, 1.0, v130
	v_add_f32_e32 v131, 1.0, v131
	v_mul_f32_e32 v132, 0xbfb8aa3b, v132
	v_mul_f32_e32 v133, 0xbfb8aa3b, v133
	v_exp_f32_e32 v140, v140
	v_exp_f32_e32 v141, v141
	v_rcp_f32_e32 v130, v130
	v_rcp_f32_e32 v131, v131
	v_exp_f32_e32 v132, v132
	v_exp_f32_e32 v133, v133
	v_add_f32_e32 v160, 1.0, v160
	v_add_f32_e32 v161, 1.0, v161
	v_pk_fma_f32 v[158:159], v[158:159], v[200:201], v[198:199]
	v_lshlrev_b32_e32 v198, 16, v166
	v_and_b32_e32 v199, 0xffff0000, v166
	v_lshlrev_b32_e32 v200, 16, v162
	v_and_b32_e32 v201, 0xffff0000, v162
	v_lshlrev_b32_e32 v166, 16, v167
	v_and_b32_e32 v167, 0xffff0000, v167
	v_lshlrev_b32_e32 v162, 16, v163
	v_and_b32_e32 v163, 0xffff0000, v163
	v_rcp_f32_e32 v160, v160
	v_rcp_f32_e32 v161, v161
	v_add_f32_e32 v138, 1.0, v138
	v_add_f32_e32 v139, 1.0, v139
	v_add_f32_e32 v134, 1.0, v134
	v_add_f32_e32 v135, 1.0, v135
	v_pk_fma_f32 v[136:137], v[136:137], v[162:163], v[166:167]
	v_lshlrev_b32_e32 v162, 16, v168
	v_and_b32_e32 v163, 0xffff0000, v168
	v_lshlrev_b32_e32 v166, 16, v164
	v_and_b32_e32 v167, 0xffff0000, v164
	v_rcp_f32_e32 v138, v138
	v_rcp_f32_e32 v139, v139
	v_add_f32_e32 v140, 1.0, v140
	v_add_f32_e32 v141, 1.0, v141
	v_rcp_f32_e32 v134, v134
	v_rcp_f32_e32 v135, v135
	v_pk_fma_f32 v[162:163], v[130:131], v[166:167], v[162:163]
	v_add_f32_e32 v130, 1.0, v132
	v_add_f32_e32 v131, 1.0, v133
	v_rcp_f32_e32 v140, v140
	v_rcp_f32_e32 v141, v141
	v_rcp_f32_e32 v130, v130
	v_rcp_f32_e32 v131, v131
	v_and_b32_e32 v191, 0xffff0000, v211
	v_pk_fma_f32 v[160:161], v[160:161], v[190:191], v[202:203]
	v_lshlrev_b32_e32 v190, 16, v208
	v_and_b32_e32 v191, 0xffff0000, v208
	v_lshlrev_b32_e32 v192, 16, v212
	v_and_b32_e32 v193, 0xffff0000, v212
	v_pk_fma_f32 v[138:139], v[138:139], v[192:193], v[190:191]
	v_lshlrev_b32_e32 v190, 16, v209
	v_and_b32_e32 v191, 0xffff0000, v209
	v_lshlrev_b32_e32 v192, 16, v213
	v_and_b32_e32 v193, 0xffff0000, v213
	v_pk_fma_f32 v[134:135], v[134:135], v[200:201], v[198:199]
	v_lshlrev_b32_e32 v132, 16, v169
	v_and_b32_e32 v133, 0xffff0000, v169
	v_lshlrev_b32_e32 v164, 16, v165
	v_and_b32_e32 v165, 0xffff0000, v165
	v_pk_fma_f32 v[140:141], v[140:141], v[192:193], v[190:191]
	v_pk_fma_f32 v[164:165], v[130:131], v[164:165], v[132:133]
	v_pk_mul_f32 v[130:131], v[134:135], v[134:135]
	v_pk_mul_f32 v[132:133], v[136:137], v[136:137]
	v_pk_mul_f32 v[194:195], v[138:139], v[138:139]
	v_pk_mul_f32 v[196:197], v[140:141], v[140:141]
	v_add_f32_e32 v132, v132, v133
	v_add_f32_e32 v130, v130, v131
	v_pk_mul_f32 v[190:191], v[158:159], v[158:159]
	v_pk_mul_f32 v[192:193], v[160:161], v[160:161]
	v_pk_mul_f32 v[166:167], v[162:163], v[162:163]
	v_pk_mul_f32 v[168:169], v[164:165], v[164:165]
	v_add_f32_e32 v130, v130, v132
	v_add_f32_e32 v131, v196, v197
	v_add_f32_e32 v132, v194, v195
	v_add_f32_e32 v168, v168, v169
	v_add_f32_e32 v166, v166, v167
	v_add_f32_e32 v131, v132, v131
	v_add_f32_e32 v132, v192, v193
	v_add_f32_e32 v133, v190, v191
	v_add_f32_e32 v166, v166, v168
	v_add_f32_e32 v132, v133, v132
	v_add_f32_e32 v130, v130, v166
	v_add_f32_e32 v131, v132, v131
	v_add_f32_e32 v166, v131, v130
	ds_bpermute_b32 v167, v188, v166
	v_lshlrev_b64 v[130:131], 12, v[174:175]
	v_lshl_add_u64 v[130:131], s[74:75], 0, v[130:131]
	v_lshl_add_u64 v[132:133], v[172:173], 2, v[130:131]
	global_store_dwordx4 v[132:133], v[158:161], off
	global_store_dwordx4 v[132:133], v[138:141], off offset:16
	global_store_dwordx4 v[132:133], v[134:137], off offset:512
	global_store_dwordx4 v[132:133], v[162:165], off offset:528
	s_waitcnt lgkmcnt(0)
	v_add_f32_e32 v130, v166, v167
	ds_bpermute_b32 v131, v170, v130
	s_and_saveexec_b64 s[0:1], vcc
	s_cbranch_execz .LBB0_717
	v_lshl_add_u64 v[132:133], s[6:7], 0, v[182:183]
	s_lshl_b32 s12, s34, 2
	v_lshl_add_u64 v[132:133], v[132:133], 0, s[12:13]
	s_waitcnt lgkmcnt(0)
	v_add_f32_e32 v130, v130, v131
	global_store_dword v[132:133], v130, off
